# speedup vs baseline: 1.0169x; 1.0169x over previous
; template <class ARow, class Epi>
; DI void gemm_tile(const ARow& arow, long a_kstride, const u16* __restrict__ Bt, long ldb, int K, int m0, int n0,
;                   const Epi& epi, char* smem) {
;     ...
;   for (int kt = 0; kt < KT; ++kt) {
;     const int cur = kt & 1;
;     if (kt + 1 < KT) GEMM_STAGE(cur ^ 1, kt + 1);
;     const char* sa = smem + cur * 32768 + wm * 64 * 128;
;     const char* sb = smem + cur * 32768 + 16384 + wn * 64 * 128;
; #pragma unroll
;     for (int ks = 0; ks < 2; ++ks) {
;       bf16x8 wf[4], af[4];
; #pragma unroll
;       for (int j = 0; j < 4; ++j) {
;         wf[j] = *(const bf16x8*)(sb + j * 2048 + foff[ks]);
;         af[j] = *(const bf16x8*)(sa + j * 2048 + foff[ks]);
;       }
; #pragma unroll
;       for (int ni = 0; ni < 4; ++ni)
; #pragma unroll
;         for (int mi = 0; mi < 4; ++mi) acc[ni][mi] = __builtin_amdgcn_mfma_f32_16x16x32_bf16(wf[ni], af[mi], acc[ni][mi], 0, 0, 0);
;     }
;     asm volatile("s_waitcnt vmcnt(0)" ::: "memory");
;     __syncthreads();
;   }
.LBB0_217:
	s_and_b32 s6, s1, 0x8000
	s_xor_b32 s7, s6, 0x8000
	v_add_u32_e32 v108, s7, v91
	v_add_u32_e32 v116, s6, v89
	v_or_b32_e32 v117, s6, v90
	v_readfirstlane_b32 s6, v108
	v_add_u32_e32 v109, 0x4000, v108
	v_lshl_add_u64 v[92:93], v[66:67], 0, s[4:5]
	v_add_u32_e32 v110, 0x400, v108
	v_readfirstlane_b32 s7, v109
	s_mov_b32 m0, s6
	v_lshl_add_u64 v[94:95], v[68:69], 0, s[4:5]
	v_add_u32_e32 v111, 0x4400, v108
	v_readfirstlane_b32 s8, v110
	global_load_lds_dwordx4 v[92:93], off
	s_mov_b32 m0, s7
	v_lshl_add_u64 v[96:97], v[70:71], 0, s[4:5]
	v_add_u32_e32 v113, 0x800, v108
	v_readfirstlane_b32 s9, v111
	global_load_lds_dwordx4 v[94:95], off
	s_mov_b32 m0, s8
	v_lshl_add_u64 v[98:99], v[72:73], 0, s[4:5]
	v_add_u32_e32 v114, 0x4800, v108
	v_readfirstlane_b32 s10, v113
	global_load_lds_dwordx4 v[96:97], off
	s_mov_b32 m0, s9
	v_lshl_add_u64 v[100:101], v[74:75], 0, s[4:5]
	v_add_u32_e32 v115, 0xc00, v108
	v_readfirstlane_b32 s11, v114
	global_load_lds_dwordx4 v[98:99], off
	s_mov_b32 m0, s10
	v_lshl_add_u64 v[102:103], v[76:77], 0, s[4:5]
	v_add_u32_e32 v108, 0x4c00, v108
	v_readfirstlane_b32 s12, v115
	global_load_lds_dwordx4 v[100:101], off
	s_mov_b32 m0, s11
	v_lshl_add_u64 v[104:105], v[78:79], 0, s[4:5]
	v_readfirstlane_b32 s13, v108
	global_load_lds_dwordx4 v[102:103], off
	s_mov_b32 m0, s12
	v_lshl_add_u64 v[106:107], v[80:81], 0, s[4:5]
	global_load_lds_dwordx4 v[104:105], off
	s_mov_b32 m0, s13
	v_add_u32_e32 v118, v117, v88
	global_load_lds_dwordx4 v[106:107], off
	v_add_u32_e32 v112, v116, v88
	ds_read_b128 v[92:95], v118 offset:16384
	ds_read_b128 v[96:99], v112
	ds_read_b128 v[100:103], v118 offset:18432
	ds_read_b128 v[104:107], v112 offset:2048
	ds_read_b128 v[108:111], v112 offset:4096
	ds_read_b128 v[112:115], v112 offset:6144
	s_waitcnt lgkmcnt(0)
	v_mfma_f32_16x16x32_bf16 v[60:63], v[92:95], v[96:99], v[60:63]
	v_add_u32_e32 v117, v117, v87
	v_add_u32_e32 v116, v116, v87
	s_add_i32 s1, s1, 0x8000
	v_mfma_f32_16x16x32_bf16 v[56:59], v[92:95], v[104:107], v[56:59]
	s_add_u32 s4, s4, 0x80
	s_addc_u32 s5, s5, 0
	s_cmpk_eq_i32 s4, 0x780
	v_mfma_f32_16x16x32_bf16 v[48:51], v[92:95], v[108:111], v[48:51]
	v_mfma_f32_16x16x32_bf16 v[40:43], v[92:95], v[112:115], v[40:43]
	v_mfma_f32_16x16x32_bf16 v[36:39], v[100:103], v[96:99], v[36:39]
	v_mfma_f32_16x16x32_bf16 v[32:35], v[100:103], v[104:107], v[32:35]
	v_mfma_f32_16x16x32_bf16 v[28:31], v[100:103], v[108:111], v[28:31]
	v_mfma_f32_16x16x32_bf16 v[24:27], v[100:103], v[112:115], v[24:27]
	ds_read_b128 v[92:95], v118 offset:20480
	ds_read_b128 v[100:103], v118 offset:22528
	s_waitcnt lgkmcnt(1)
	v_mfma_f32_16x16x32_bf16 v[20:23], v[92:95], v[96:99], v[20:23]
	v_mfma_f32_16x16x32_bf16 v[16:19], v[92:95], v[104:107], v[16:19]
	v_mfma_f32_16x16x32_bf16 v[12:15], v[92:95], v[108:111], v[12:15]
	v_mfma_f32_16x16x32_bf16 v[8:11], v[92:95], v[112:115], v[8:11]
	ds_read_b128 v[92:95], v117 offset:16384
	s_waitcnt lgkmcnt(1)
	v_mfma_f32_16x16x32_bf16 v[4:7], v[100:103], v[96:99], v[4:7]
	v_mfma_f32_16x16x32_bf16 v[0:3], v[100:103], v[104:107], v[0:3]
	v_mfma_f32_16x16x32_bf16 v[52:55], v[100:103], v[108:111], v[52:55]
	v_mfma_f32_16x16x32_bf16 v[44:47], v[100:103], v[112:115], v[44:47]
	ds_read_b128 v[96:99], v116
	ds_read_b128 v[100:103], v117 offset:18432
	ds_read_b128 v[104:107], v116 offset:2048
	ds_read_b128 v[108:111], v116 offset:4096
	ds_read_b128 v[112:115], v116 offset:6144
	s_waitcnt lgkmcnt(4)
	v_mfma_f32_16x16x32_bf16 v[60:63], v[92:95], v[96:99], v[60:63]
	s_waitcnt lgkmcnt(2)
	v_mfma_f32_16x16x32_bf16 v[56:59], v[92:95], v[104:107], v[56:59]
	s_waitcnt lgkmcnt(1)
	v_mfma_f32_16x16x32_bf16 v[48:51], v[92:95], v[108:111], v[48:51]
	s_waitcnt lgkmcnt(0)
	v_mfma_f32_16x16x32_bf16 v[40:43], v[92:95], v[112:115], v[40:43]
	v_mfma_f32_16x16x32_bf16 v[36:39], v[100:103], v[96:99], v[36:39]
	v_mfma_f32_16x16x32_bf16 v[32:35], v[100:103], v[104:107], v[32:35]
	v_mfma_f32_16x16x32_bf16 v[28:31], v[100:103], v[108:111], v[28:31]
	v_mfma_f32_16x16x32_bf16 v[24:27], v[100:103], v[112:115], v[24:27]
	ds_read_b128 v[92:95], v117 offset:20480
	ds_read_b128 v[100:103], v117 offset:22528
	s_waitcnt lgkmcnt(0)
	s_waitcnt vmcnt(0)
	s_waitcnt vmcnt(0) lgkmcnt(0)
	v_mfma_f32_16x16x32_bf16 v[20:23], v[92:95], v[96:99], v[20:23]
	s_barrier
	v_mfma_f32_16x16x32_bf16 v[16:19], v[92:95], v[104:107], v[16:19]
	v_mfma_f32_16x16x32_bf16 v[12:15], v[92:95], v[108:111], v[12:15]
	v_mfma_f32_16x16x32_bf16 v[8:11], v[92:95], v[112:115], v[8:11]
	v_mfma_f32_16x16x32_bf16 v[4:7], v[100:103], v[96:99], v[4:7]
	v_mfma_f32_16x16x32_bf16 v[0:3], v[100:103], v[104:107], v[0:3]
	v_mfma_f32_16x16x32_bf16 v[52:55], v[100:103], v[108:111], v[52:55]
	v_mfma_f32_16x16x32_bf16 v[44:47], v[100:103], v[112:115], v[44:47]
	s_cbranch_scc0 .LBB0_217
; template <class ARow, class Epi>
; DI void gemm_tile(const ARow& arow, long a_kstride, const u16* __restrict__ Bt, long ldb, int K, int m0, int n0,
;                   const Epi& epi, char* smem) {
;     ...
; #pragma unroll
;     for (int ks = 0; ks < 2; ++ks) {
;       bf16x8 wf[4], af[4];
; #pragma unroll
;       for (int j = 0; j < 4; ++j) {
;         wf[j] = *(const bf16x8*)(sb + j * 2048 + foff[ks]);
;         af[j] = *(const bf16x8*)(sa + j * 2048 + foff[ks]);
;       }
; #pragma unroll
;       for (int ni = 0; ni < 4; ++ni)
; #pragma unroll
;         for (int mi = 0; mi < 4; ++mi) acc[ni][mi] = __builtin_amdgcn_mfma_f32_16x16x32_bf16(wf[ni], af[mi], acc[ni][mi], 0, 0, 0);
;     }
;     asm volatile("s_waitcnt vmcnt(0)" ::: "memory");
;     __syncthreads();
;   }
;     ...
;   const int nh = n0 + wn * 64;
;   if (epi.packed(nh)) {
	v_add_u32_e32 v91, v90, v88
	ds_read_b128 v[66:69], v91 offset:49152
	v_add_u32_e32 v88, v89, v88
	ds_read_b128 v[70:73], v88 offset:32768
	ds_read_b128 v[74:77], v88 offset:34816
	ds_read_b128 v[78:81], v88 offset:36864
	ds_read_b128 v[92:95], v88 offset:38912
	v_add_u32_e32 v116, v90, v87
	s_waitcnt lgkmcnt(3)
	v_mfma_f32_16x16x32_bf16 v[60:63], v[66:69], v[70:73], v[60:63]
	s_waitcnt lgkmcnt(2)
	v_mfma_f32_16x16x32_bf16 v[56:59], v[66:69], v[74:77], v[56:59]
	s_waitcnt lgkmcnt(1)
	v_mfma_f32_16x16x32_bf16 v[48:51], v[66:69], v[78:81], v[48:51]
	s_waitcnt lgkmcnt(0)
	v_mfma_f32_16x16x32_bf16 v[40:43], v[66:69], v[92:95], v[40:43]
	ds_read_b128 v[66:69], v91 offset:51200
	s_waitcnt lgkmcnt(0)
	v_mfma_f32_16x16x32_bf16 v[36:39], v[66:69], v[70:73], v[36:39]
	v_mfma_f32_16x16x32_bf16 v[32:35], v[66:69], v[74:77], v[32:35]
	v_mfma_f32_16x16x32_bf16 v[96:99], v[66:69], v[78:81], v[28:31]
	v_mfma_f32_16x16x32_bf16 v[66:69], v[66:69], v[92:95], v[24:27]
	s_nop 2
	ds_read_b128 v[24:27], v91 offset:53248
	s_waitcnt lgkmcnt(0)
	v_mfma_f32_16x16x32_bf16 v[104:107], v[24:27], v[92:95], v[8:11]
	s_nop 2
	ds_read_b128 v[8:11], v91 offset:55296
	v_mfma_f32_16x16x32_bf16 v[20:23], v[24:27], v[70:73], v[20:23]
	s_waitcnt lgkmcnt(0)
	v_mfma_f32_16x16x32_bf16 v[70:73], v[8:11], v[70:73], v[4:7]
	s_nop 2
	ds_read_b128 v[4:7], v116 offset:49152
	v_mfma_f32_16x16x32_bf16 v[100:103], v[24:27], v[78:81], v[12:15]
	s_nop 2
	v_add_u32_e32 v12, v89, v87
	v_mfma_f32_16x16x32_bf16 v[16:19], v[24:27], v[74:77], v[16:19]
	ds_read_b128 v[88:91], v12 offset:32768
	ds_read_b128 v[108:111], v12 offset:36864
	ds_read_b128 v[112:115], v12 offset:38912
	v_mfma_f32_16x16x32_bf16 v[0:3], v[8:11], v[74:77], v[0:3]
	v_mfma_f32_16x16x32_bf16 v[74:77], v[8:11], v[78:81], v[52:55]
	v_mfma_f32_16x16x32_bf16 v[78:81], v[8:11], v[92:95], v[44:47]
	ds_read_b128 v[92:95], v12 offset:34816
	s_waitcnt lgkmcnt(3)
	v_mfma_f32_16x16x32_bf16 v[60:63], v[4:7], v[88:91], v[60:63]
	s_waitcnt lgkmcnt(0)
	v_mfma_f32_16x16x32_bf16 v[44:47], v[4:7], v[92:95], v[56:59]
	v_mfma_f32_16x16x32_bf16 v[28:31], v[4:7], v[108:111], v[48:51]
	v_mfma_f32_16x16x32_bf16 v[12:15], v[4:7], v[112:115], v[40:43]
	ds_read_b128 v[4:7], v116 offset:51200
	s_waitcnt lgkmcnt(0)
	v_mfma_f32_16x16x32_bf16 v[56:59], v[4:7], v[88:91], v[36:39]
	v_mfma_f32_16x16x32_bf16 v[40:43], v[4:7], v[92:95], v[32:35]
	v_mfma_f32_16x16x32_bf16 v[24:27], v[4:7], v[108:111], v[96:99]
	v_mfma_f32_16x16x32_bf16 v[8:11], v[4:7], v[112:115], v[66:69]
	ds_read_b128 v[4:7], v116 offset:53248
	s_nop 0
	ds_read_b128 v[96:99], v116 offset:55296
	s_waitcnt lgkmcnt(0)
	s_waitcnt vmcnt(0)
	s_waitcnt lgkmcnt(0)
	v_mfma_f32_16x16x32_bf16 v[32:35], v[96:99], v[92:95], v[0:3]
	s_nop 2
	v_or_b32_e32 v0, s0, v64
	v_lshl_or_b32 v66, v85, 6, s42
	v_cmp_lt_i32_e32 vcc, s33, v66
	v_mfma_f32_16x16x32_bf16 v[52:55], v[4:7], v[88:91], v[20:23]
	s_barrier
	v_mfma_f32_16x16x32_bf16 v[36:39], v[4:7], v[92:95], v[16:19]
	v_mfma_f32_16x16x32_bf16 v[20:23], v[4:7], v[108:111], v[100:103]
	v_mfma_f32_16x16x32_bf16 v[4:7], v[4:7], v[112:115], v[104:107]
	v_mfma_f32_16x16x32_bf16 v[48:51], v[96:99], v[88:91], v[70:73]
	v_mfma_f32_16x16x32_bf16 v[16:19], v[96:99], v[108:111], v[74:77]
	s_nop 1
	v_lshlrev_b32_e32 v70, 2, v84
	v_or_b32_e32 v64, v66, v70
	v_lshl_add_u32 v74, v86, 6, v0
	v_mfma_f32_16x16x32_bf16 v[0:3], v[96:99], v[112:115], v[78:81]
	s_nop 7
	v_readfirstlane_b32 s99, v66
	s_cmpk_lt_u32 s99, 0x400
	s_cbranch_scc0 .Lfe_A_not_q
; DI unsigned pack2(float a, float b) { v2f f = {a, b}; return __builtin_bit_cast(unsigned, __builtin_convertvector(f, v2bf)); }
; DI float silu_f(float v) { return v / (1.f + fexp(-v)); }
;   DI u32x2 pack(int, int, float a, float b, float c, float d, float&) const { u32x2 v; v.x = pack2(a, b); v.y = pack2(c, d); return v; }
; template <class ARow, class Epi>
; DI void gemm_tile(const ARow& arow, long a_kstride, const u16* __restrict__ Bt, long ldb, int K, int m0, int n0,
;                   const Epi& epi, char* smem) {
;     ...
;   const int nh = n0 + wn * 64;
;   if (epi.packed(nh)) {
; #pragma unroll
;     for (int mi = 0; mi < 4; ++mi) {
;       const int m = m0 + wm * 64 + mi * 16 + fr;
;       float ss = 0.f;
;       u32x2 pk[4];
; #pragma unroll
;       for (int ni = 0; ni < 4; ++ni) pk[ni] = epi.pack(m, nh + ni * 16 + fq * 4, acc[ni][mi][0], acc[ni][mi][1], acc[ni][mi][2], acc[ni][mi][3], ss);
;       epi.finish16(m, nh, ss);
;       u16* rp = epi.rowp(m) + nh;
; #pragma unroll
;       for (int pp = 0; pp < 2; ++pp) {
;         u32x2 a = pk[2 * pp], b = pk[2 * pp + 1];
;         const u32x2 rx = __builtin_amdgcn_permlane16_swap(a.x, b.x, false, false);
;         const u32x2 ry = __builtin_amdgcn_permlane16_swap(a.y, b.y, false, false);
;         const int nst = (fq & 1) ? ((2 * pp + 1) * 16 + (fq - 1) * 4) : ((2 * pp) * 16 + fq * 4);
;         *(u32x4*)(rp + nst) = (u32x4){rx[0], ry[0], rx[1], ry[1]};
;       }
;   DI u32x2 pack(int m, int n, float a, float b, float c, float d, float& ss) const {
;     if (n < q_end) { a *= qscale; b *= qscale; c *= qscale; d *= qscale; }
;     else if (n >= z_start) { a = silu_f(a); b = silu_f(b); c = silu_f(c); d = silu_f(d); }
;     ss += a * a + b * b + c * c + d * d;
;     u32x2 v; v.x = pack2(a, b); v.y = pack2(c, d);
;     return v;
;   }
	s_load_dwordx2 s[100:101], s[56:57], 0x130
	v_and_b32_e32 v152, 1, v84
	v_mul_u32_u24_e32 v152, 12, v152
	v_lshl_add_u32 v152, v84, 2, v152
	v_add_u32_e32 v152, v152, v66
	v_mul_u32_u24_e32 v153, 0xe00, v74
	v_add_u32_e32 v152, v152, v153
	v_lshlrev_b32_e32 v152, 1, v152
	v_add_u32_e32 v153, 0x1c000, v152
	v_add_u32_e32 v154, 0x38000, v152
	v_add_u32_e32 v155, 0x54000, v152
	s_mov_b32 s98, 0x3e38aa3b
	s_nop 3
	v_pk_mul_f32 v[60:61], v[60:61], s[98:99] op_sel_hi:[1,0]
	v_pk_mul_f32 v[62:63], v[62:63], s[98:99] op_sel_hi:[1,0]
	v_pk_mul_f32 v[56:57], v[56:57], s[98:99] op_sel_hi:[1,0]
	v_pk_mul_f32 v[58:59], v[58:59], s[98:99] op_sel_hi:[1,0]
	v_pk_mul_f32 v[52:53], v[52:53], s[98:99] op_sel_hi:[1,0]
	v_pk_mul_f32 v[54:55], v[54:55], s[98:99] op_sel_hi:[1,0]
	v_pk_mul_f32 v[48:49], v[48:49], s[98:99] op_sel_hi:[1,0]
	v_pk_mul_f32 v[50:51], v[50:51], s[98:99] op_sel_hi:[1,0]
	v_cvt_pk_bf16_f32 v120, v60, v61
	v_cvt_pk_bf16_f32 v121, v62, v63
	v_cvt_pk_bf16_f32 v122, v56, v57
	v_cvt_pk_bf16_f32 v123, v58, v59
	v_cvt_pk_bf16_f32 v124, v52, v53
	v_cvt_pk_bf16_f32 v125, v54, v55
	v_cvt_pk_bf16_f32 v126, v48, v49
	v_cvt_pk_bf16_f32 v127, v50, v51
	s_nop 1
	v_permlane16_swap_b32_e32 v120, v122
	v_permlane16_swap_b32_e32 v121, v123
	v_permlane16_swap_b32_e32 v124, v126
	v_permlane16_swap_b32_e32 v125, v127
	s_waitcnt lgkmcnt(0)
	global_store_dwordx4 v152, v[120:123], s[100:101]
	global_store_dwordx4 v152, v[124:127], s[100:101] offset:64
	v_pk_mul_f32 v[44:45], v[44:45], s[98:99] op_sel_hi:[1,0]
	v_pk_mul_f32 v[46:47], v[46:47], s[98:99] op_sel_hi:[1,0]
	v_pk_mul_f32 v[40:41], v[40:41], s[98:99] op_sel_hi:[1,0]
	v_pk_mul_f32 v[42:43], v[42:43], s[98:99] op_sel_hi:[1,0]
	v_pk_mul_f32 v[36:37], v[36:37], s[98:99] op_sel_hi:[1,0]
	v_pk_mul_f32 v[38:39], v[38:39], s[98:99] op_sel_hi:[1,0]
	v_pk_mul_f32 v[32:33], v[32:33], s[98:99] op_sel_hi:[1,0]
	v_pk_mul_f32 v[34:35], v[34:35], s[98:99] op_sel_hi:[1,0]
	v_cvt_pk_bf16_f32 v128, v44, v45
	v_cvt_pk_bf16_f32 v129, v46, v47
	v_cvt_pk_bf16_f32 v130, v40, v41
	v_cvt_pk_bf16_f32 v131, v42, v43
	v_cvt_pk_bf16_f32 v132, v36, v37
	v_cvt_pk_bf16_f32 v133, v38, v39
	v_cvt_pk_bf16_f32 v134, v32, v33
	v_cvt_pk_bf16_f32 v135, v34, v35
	s_nop 1
	v_permlane16_swap_b32_e32 v128, v130
	v_permlane16_swap_b32_e32 v129, v131
	v_permlane16_swap_b32_e32 v132, v134
	v_permlane16_swap_b32_e32 v133, v135
	global_store_dwordx4 v153, v[128:131], s[100:101]
	global_store_dwordx4 v153, v[132:135], s[100:101] offset:64
	v_pk_mul_f32 v[28:29], v[28:29], s[98:99] op_sel_hi:[1,0]
	v_pk_mul_f32 v[30:31], v[30:31], s[98:99] op_sel_hi:[1,0]
	v_pk_mul_f32 v[24:25], v[24:25], s[98:99] op_sel_hi:[1,0]
	v_pk_mul_f32 v[26:27], v[26:27], s[98:99] op_sel_hi:[1,0]
	v_pk_mul_f32 v[20:21], v[20:21], s[98:99] op_sel_hi:[1,0]
	v_pk_mul_f32 v[22:23], v[22:23], s[98:99] op_sel_hi:[1,0]
	v_pk_mul_f32 v[16:17], v[16:17], s[98:99] op_sel_hi:[1,0]
	v_pk_mul_f32 v[18:19], v[18:19], s[98:99] op_sel_hi:[1,0]
	v_cvt_pk_bf16_f32 v136, v28, v29
	v_cvt_pk_bf16_f32 v137, v30, v31
	v_cvt_pk_bf16_f32 v138, v24, v25
	v_cvt_pk_bf16_f32 v139, v26, v27
	v_cvt_pk_bf16_f32 v140, v20, v21
	v_cvt_pk_bf16_f32 v141, v22, v23
	v_cvt_pk_bf16_f32 v142, v16, v17
	v_cvt_pk_bf16_f32 v143, v18, v19
	s_nop 1
	v_permlane16_swap_b32_e32 v136, v138
	v_permlane16_swap_b32_e32 v137, v139
	v_permlane16_swap_b32_e32 v140, v142
	v_permlane16_swap_b32_e32 v141, v143
	global_store_dwordx4 v154, v[136:139], s[100:101]
	global_store_dwordx4 v154, v[140:143], s[100:101] offset:64
	v_pk_mul_f32 v[12:13], v[12:13], s[98:99] op_sel_hi:[1,0]
	v_pk_mul_f32 v[14:15], v[14:15], s[98:99] op_sel_hi:[1,0]
	v_pk_mul_f32 v[8:9], v[8:9], s[98:99] op_sel_hi:[1,0]
	v_pk_mul_f32 v[10:11], v[10:11], s[98:99] op_sel_hi:[1,0]
	v_pk_mul_f32 v[4:5], v[4:5], s[98:99] op_sel_hi:[1,0]
	v_pk_mul_f32 v[6:7], v[6:7], s[98:99] op_sel_hi:[1,0]
	v_pk_mul_f32 v[0:1], v[0:1], s[98:99] op_sel_hi:[1,0]
	v_pk_mul_f32 v[2:3], v[2:3], s[98:99] op_sel_hi:[1,0]
	v_cvt_pk_bf16_f32 v144, v12, v13
	v_cvt_pk_bf16_f32 v145, v14, v15
	v_cvt_pk_bf16_f32 v146, v8, v9
	v_cvt_pk_bf16_f32 v147, v10, v11
	v_cvt_pk_bf16_f32 v148, v4, v5
	v_cvt_pk_bf16_f32 v149, v6, v7
	v_cvt_pk_bf16_f32 v150, v0, v1
	v_cvt_pk_bf16_f32 v151, v2, v3
	s_nop 1
	v_permlane16_swap_b32_e32 v144, v146
	v_permlane16_swap_b32_e32 v145, v147
	v_permlane16_swap_b32_e32 v148, v150
	v_permlane16_swap_b32_e32 v149, v151
	global_store_dwordx4 v155, v[144:147], s[100:101]
	global_store_dwordx4 v155, v[148:151], s[100:101] offset:64
	s_branch .Lfe_join_A

; template <class ARow, class Epi>
; DI void gemm_tile(const ARow& arow, long a_kstride, const u16* __restrict__ Bt, long ldb, int K, int m0, int n0,
;                   const Epi& epi, char* smem) {
;     ...
;   for (int kt = 0; kt < KT; ++kt) {
;     const int cur = kt & 1;
;     if (kt + 1 < KT) GEMM_STAGE(cur ^ 1, kt + 1);
;     const char* sa = smem + cur * 32768 + wm * 64 * 128;
;     const char* sb = smem + cur * 32768 + 16384 + wn * 64 * 128;
; #pragma unroll
;     for (int ks = 0; ks < 2; ++ks) {
;       bf16x8 wf[4], af[4];
; #pragma unroll
;       for (int j = 0; j < 4; ++j) {
;         wf[j] = *(const bf16x8*)(sb + j * 2048 + foff[ks]);
;         af[j] = *(const bf16x8*)(sa + j * 2048 + foff[ks]);
;       }
; #pragma unroll
;       for (int ni = 0; ni < 4; ++ni)
; #pragma unroll
;         for (int mi = 0; mi < 4; ++mi) acc[ni][mi] = __builtin_amdgcn_mfma_f32_16x16x32_bf16(wf[ni], af[mi], acc[ni][mi], 0, 0, 0);
;     }
;     asm volatile("s_waitcnt vmcnt(0)" ::: "memory");
;     __syncthreads();
;   }
.LBB0_678:
	s_and_b32 s1, s0, 0x8000
	s_xor_b32 s36, s1, 0x8000
	v_add_u32_e32 v54, s36, v33
	v_add_u32_e32 v39, s1, v38
	v_or_b32_e32 v114, s1, v37
	v_readfirstlane_b32 s1, v54
	v_add_u32_e32 v55, 0x4000, v54
	v_lshl_add_u64 v[34:35], v[30:31], 0, s[18:19]
	v_add_u32_e32 v72, 0x400, v54
	v_readfirstlane_b32 s36, v55
	s_mov_b32 m0, s1
	v_lshl_add_u64 v[40:41], v[16:17], 0, s[20:21]
	v_add_u32_e32 v73, 0x4400, v54
	v_readfirstlane_b32 s37, v72
	global_load_lds_dwordx4 v[34:35], off
	s_mov_b32 m0, s36
	v_lshl_add_u64 v[42:43], v[28:29], 0, s[18:19]
	v_add_u32_e32 v74, 0x800, v54
	v_readfirstlane_b32 s38, v73
	global_load_lds_dwordx4 v[40:41], off
	s_mov_b32 m0, s37
	v_lshl_add_u64 v[44:45], v[18:19], 0, s[20:21]
	v_add_u32_e32 v75, 0x4800, v54
	v_readfirstlane_b32 s39, v74
	global_load_lds_dwordx4 v[42:43], off
	s_mov_b32 m0, s38
	v_lshl_add_u64 v[46:47], v[26:27], 0, s[18:19]
	v_add_u32_e32 v76, 0xc00, v54
	v_readfirstlane_b32 s40, v75
	global_load_lds_dwordx4 v[44:45], off
	s_mov_b32 m0, s39
	v_lshl_add_u64 v[48:49], v[20:21], 0, s[20:21]
	v_add_u32_e32 v54, 0x4c00, v54
	v_readfirstlane_b32 s41, v76
	global_load_lds_dwordx4 v[46:47], off
	s_mov_b32 m0, s40
	v_lshl_add_u64 v[50:51], v[24:25], 0, s[18:19]
	v_readfirstlane_b32 s42, v54
	global_load_lds_dwordx4 v[48:49], off
	s_mov_b32 m0, s41
	v_lshl_add_u64 v[52:53], v[22:23], 0, s[20:21]
	global_load_lds_dwordx4 v[50:51], off
	s_mov_b32 m0, s42
	v_add_u32_e32 v100, v114, v36
	global_load_lds_dwordx4 v[52:53], off
	v_add_u32_e32 v96, v39, v36
	ds_read_b128 v[40:43], v100 offset:16384
	ds_read_b128 v[44:47], v96
	ds_read_b128 v[48:51], v100 offset:18432
	ds_read_b128 v[52:55], v96 offset:2048
	s_waitcnt lgkmcnt(0)
	v_mfma_f32_16x16x32_bf16 v[76:79], v[40:43], v[52:55], v[92:95]
	s_nop 2
	ds_read_b128 v[92:95], v96 offset:4096
	ds_read_b128 v[96:99], v96 offset:6144
	v_add_u32_e32 v34, v114, v32
	v_add_u32_e32 v35, v39, v32
	v_mfma_f32_16x16x32_bf16 v[72:75], v[40:43], v[44:47], v[144:147]
	s_add_i32 s0, s0, 0x8000
	s_add_u32 s20, s20, 0x80
	s_addc_u32 s21, s21, 0
	s_waitcnt lgkmcnt(1)
	v_mfma_f32_16x16x32_bf16 v[68:71], v[40:43], v[92:95], v[68:71]
	v_lshl_add_u64 v[24:25], v[24:25], 0, s[14:15]
	v_lshl_add_u64 v[26:27], v[26:27], 0, s[14:15]
	v_lshl_add_u64 v[28:29], v[28:29], 0, s[14:15]
	s_waitcnt lgkmcnt(0)
	v_mfma_f32_16x16x32_bf16 v[12:15], v[40:43], v[96:99], v[12:15]
	v_lshl_add_u64 v[30:31], v[30:31], 0, s[14:15]
	s_cmpk_lg_i32 s20, 0xf80
	v_mfma_f32_16x16x32_bf16 v[40:43], v[48:51], v[44:47], v[140:143]
	v_mfma_f32_16x16x32_bf16 v[84:87], v[48:51], v[52:55], v[84:87]
	v_mfma_f32_16x16x32_bf16 v[60:63], v[48:51], v[92:95], v[60:63]
	v_mfma_f32_16x16x32_bf16 v[4:7], v[48:51], v[96:99], v[4:7]
	ds_read_b128 v[48:51], v100 offset:20480
	ds_read_b128 v[100:103], v100 offset:22528
	s_waitcnt lgkmcnt(1)
	v_mfma_f32_16x16x32_bf16 v[108:111], v[48:51], v[44:47], v[128:131]
	v_mfma_f32_16x16x32_bf16 v[80:83], v[48:51], v[52:55], v[80:83]
	v_mfma_f32_16x16x32_bf16 v[56:59], v[48:51], v[92:95], v[56:59]
	v_mfma_f32_16x16x32_bf16 v[0:3], v[48:51], v[96:99], v[0:3]
	s_waitcnt lgkmcnt(0)
	v_mfma_f32_16x16x32_bf16 v[48:51], v[100:103], v[52:55], v[88:91]
	v_mfma_f32_16x16x32_bf16 v[52:55], v[100:103], v[92:95], v[64:67]
	s_nop 2
	ds_read_b128 v[64:67], v34 offset:16384
	v_mfma_f32_16x16x32_bf16 v[44:47], v[100:103], v[44:47], v[104:107]
	v_mfma_f32_16x16x32_bf16 v[8:11], v[100:103], v[96:99], v[8:11]
	ds_read_b128 v[88:91], v35
	ds_read_b128 v[96:99], v34 offset:18432
	ds_read_b128 v[100:103], v35 offset:2048
	s_waitcnt lgkmcnt(2)
	v_mfma_f32_16x16x32_bf16 v[144:147], v[64:67], v[88:91], v[72:75]
	s_waitcnt lgkmcnt(0)
	v_mfma_f32_16x16x32_bf16 v[92:95], v[64:67], v[100:103], v[76:79]
	s_nop 1
	ds_read_b128 v[72:75], v35 offset:4096
	ds_read_b128 v[76:79], v35 offset:6144
	v_mfma_f32_16x16x32_bf16 v[140:143], v[96:99], v[88:91], v[40:43]
	v_mfma_f32_16x16x32_bf16 v[84:87], v[96:99], v[100:103], v[84:87]
	s_waitcnt lgkmcnt(1)
	v_mfma_f32_16x16x32_bf16 v[60:63], v[96:99], v[72:75], v[60:63]
	s_waitcnt lgkmcnt(0)
	v_mfma_f32_16x16x32_bf16 v[4:7], v[96:99], v[76:79], v[4:7]
	ds_read_b128 v[40:43], v34 offset:20480
	ds_read_b128 v[96:99], v34 offset:22528
	s_waitcnt lgkmcnt(0)
	s_waitcnt vmcnt(0)
	s_waitcnt vmcnt(0) lgkmcnt(0)
	v_mfma_f32_16x16x32_bf16 v[68:71], v[64:67], v[72:75], v[68:71]
	s_barrier
	v_mfma_f32_16x16x32_bf16 v[12:15], v[64:67], v[76:79], v[12:15]
	v_mfma_f32_16x16x32_bf16 v[128:131], v[40:43], v[88:91], v[108:111]
	v_mfma_f32_16x16x32_bf16 v[80:83], v[40:43], v[100:103], v[80:83]
	v_mfma_f32_16x16x32_bf16 v[56:59], v[40:43], v[72:75], v[56:59]
	v_mfma_f32_16x16x32_bf16 v[0:3], v[40:43], v[76:79], v[0:3]
	v_mfma_f32_16x16x32_bf16 v[104:107], v[96:99], v[88:91], v[44:47]
	v_mfma_f32_16x16x32_bf16 v[88:91], v[96:99], v[100:103], v[48:51]
	v_mfma_f32_16x16x32_bf16 v[64:67], v[96:99], v[72:75], v[52:55]
	v_mfma_f32_16x16x32_bf16 v[8:11], v[96:99], v[76:79], v[8:11]
	s_cbranch_scc1 .LBB0_678
	s_lshl_b64 s[0:1], s[16:17], 21
	s_lshl_b32 s16, s16, 12
	s_ashr_i32 s17, s16, 31
	s_add_u32 s0, s8, s0
	s_addc_u32 s1, s9, s1
	s_lshl_b64 s[16:17], s[16:17], 2
	v_lshl_or_b32 v112, v112, 6, s35
	v_lshlrev_b32_e32 v226, 2, v113
	s_add_u32 s16, s6, s16
	v_or_b32_e32 v113, v112, v226
	v_lshlrev_b32_e32 v212, 1, v112
	s_addc_u32 s17, s7, s17
	v_lshl_add_u64 v[214:215], s[0:1], 0, v[212:213]
	v_lshlrev_b32_e32 v212, 2, v113
	v_lshl_add_u64 v[156:157], s[16:17], 0, v[212:213]
	v_add_u32_e32 v28, v38, v32
	v_add_u32_e32 v32, v37, v32
	v_add_u32_e32 v48, v38, v36
	v_add_u32_e32 v52, v37, v36
	v_add_co_u32_e32 v216, vcc, s31, v156
	ds_read_b128 v[16:19], v28 offset:38912
	ds_read_b128 v[72:75], v28 offset:36864
	ds_read_b128 v[20:23], v32 offset:55296
	ds_read_b128 v[24:27], v32 offset:53248
	ds_read_b128 v[96:99], v28 offset:34816
	ds_read_b128 v[108:111], v28 offset:32768
	ds_read_b128 v[28:31], v32 offset:51200
	ds_read_b128 v[32:35], v32 offset:49152
	ds_read_b128 v[36:39], v48 offset:38912
	ds_read_b128 v[76:79], v48 offset:36864
	ds_read_b128 v[40:43], v52 offset:55296
	ds_read_b128 v[44:47], v52 offset:53248
	ds_read_b128 v[100:103], v48 offset:34816
	ds_read_b128 v[148:151], v48 offset:32768
	ds_read_b128 v[48:51], v52 offset:51200
	ds_read_b128 v[52:55], v52 offset:49152
	v_addc_co_u32_e32 v217, vcc, 0, v157, vcc
	s_waitcnt vmcnt(0)
	s_waitcnt lgkmcnt(0)
	s_barrier
; DI unsigned pack2(float a, float b) { v2f f = {a, b}; return __builtin_bit_cast(unsigned, __builtin_convertvector(f, v2bf)); }
;   DI u32x2 pack(int, int, float a, float b, float c, float d, float&) const { u32x2 v; v.x = pack2(a, b); v.y = pack2(c, d); return v; }
; template <class ARow, class Epi>
; DI void gemm_tile(const ARow& arow, long a_kstride, const u16* __restrict__ Bt, long ldb, int K, int m0, int n0,
;                   const Epi& epi, char* smem) {
;     ...
;   if (epi.packed(nh)) {
; #pragma unroll
;     for (int mi = 0; mi < 4; ++mi) {
;       const int m = m0 + wm * 64 + mi * 16 + fr;
;       float ss = 0.f;
;       u32x2 pk[4];
; #pragma unroll
;       for (int ni = 0; ni < 4; ++ni) pk[ni] = epi.pack(m, nh + ni * 16 + fq * 4, acc[ni][mi][0], acc[ni][mi][1], acc[ni][mi][2], acc[ni][mi][3], ss);
;       epi.finish16(m, nh, ss);
;       u16* rp = epi.rowp(m) + nh;
; #pragma unroll
;       for (int pp = 0; pp < 2; ++pp) {
;         u32x2 a = pk[2 * pp], b = pk[2 * pp + 1];
;         const u32x2 rx = __builtin_amdgcn_permlane16_swap(a.x, b.x, false, false);
;         const u32x2 ry = __builtin_amdgcn_permlane16_swap(a.y, b.y, false, false);
;         const int nst = (fq & 1) ? ((2 * pp + 1) * 16 + (fq - 1) * 4) : ((2 * pp) * 16 + fq * 4);
;         *(u32x4*)(rp + nst) = (u32x4){rx[0], ry[0], rx[1], ry[1]};
;       }
;   DI u32x2 pack(int m, int n, float a, float b, float c, float d, float& ss) const {
;     f32x4 bs = {0.f, 0.f, 0.f, 0.f};
; #pragma unroll
;     for (int kc = 0; kc < 16; ++kc) bs += *(const f32x4*)(bias_part + kc * 256 + n);
;     u32x2 v; v.x = pack2(gelu_tanh(a + bs[0]), gelu_tanh(b + bs[1])); v.y = pack2(gelu_tanh(c + bs[2]), gelu_tanh(d + bs[3]));
;     return v;
;   }
	global_load_dwordx4 v[112:115], v212, s[16:17]
	global_load_dwordx4 v[116:119], v212, s[16:17] offset:1024
	global_load_dwordx4 v[120:123], v212, s[16:17] offset:2048
	global_load_dwordx4 v[124:127], v212, s[16:17] offset:3072
	v_add_co_u32_e32 v220, vcc, s30, v156
	global_load_dwordx4 v[132:135], v[216:217], off offset:-4096
	s_nop 0
	v_addc_co_u32_e32 v221, vcc, 0, v157, vcc
	global_load_dwordx4 v[136:139], v[220:221], off offset:1024
	v_mfma_f32_16x16x32_bf16 v[172:175], v[52:55], v[148:151], v[144:147]
	s_nop 2
	global_load_dwordx4 v[144:147], v[220:221], off offset:2048
	global_load_dwordx4 v[152:155], v[220:221], off offset:3072
	global_load_dwordx4 v[164:167], v[216:217], off
	global_load_dwordx4 v[168:171], v[216:217], off offset:1024
	v_add_co_u32_e32 v218, vcc, s33, v156
	v_mfma_f32_16x16x32_bf16 v[184:187], v[44:47], v[148:151], v[128:131]
	global_load_dwordx4 v[176:179], v[216:217], off offset:2048
	s_nop 1
	global_load_dwordx4 v[128:131], v[216:217], off offset:3072
	v_addc_co_u32_e32 v219, vcc, 0, v157, vcc
	v_mfma_f32_16x16x32_bf16 v[188:191], v[48:51], v[148:151], v[140:143]
	v_and_b32_e32 v223, 16, v223
	s_add_i32 s23, s23, s22
	s_add_i32 s24, s24, s25
	global_load_dwordx4 v[140:143], v[218:219], off
	global_load_dwordx4 v[156:159], v[218:219], off offset:1024
	global_load_dwordx4 v[160:163], v[218:219], off offset:2048
	v_mfma_f32_16x16x32_bf16 v[180:183], v[40:43], v[148:151], v[104:107]
	s_add_i32 s26, s26, s27
	s_cmpk_lt_i32 s23, 0x80
	s_waitcnt vmcnt(14)
	v_pk_add_f32 v[112:113], v[112:113], 0 op_sel_hi:[1,0]
	v_mfma_f32_16x16x32_bf16 v[148:151], v[32:35], v[108:111], v[172:175]
	s_waitcnt vmcnt(13)
	v_pk_add_f32 v[112:113], v[112:113], v[116:117]
	v_pk_add_f32 v[114:115], v[114:115], 0 op_sel_hi:[1,0]
	s_waitcnt vmcnt(12)
	v_pk_add_f32 v[112:113], v[112:113], v[120:121]
	global_load_dwordx4 v[172:175], v[218:219], off offset:3072
	s_waitcnt vmcnt(12)
	v_pk_add_f32 v[112:113], v[112:113], v[124:125]
	v_pk_add_f32 v[114:115], v[114:115], v[118:119]
	s_waitcnt vmcnt(11)
	v_pk_add_f32 v[112:113], v[112:113], v[132:133]
	v_pk_add_f32 v[114:115], v[114:115], v[122:123]
	s_waitcnt vmcnt(10)
	v_pk_add_f32 v[112:113], v[112:113], v[136:137]
	v_pk_add_f32 v[114:115], v[114:115], v[126:127]
	s_waitcnt vmcnt(9)
	v_pk_add_f32 v[112:113], v[112:113], v[144:145]
	v_pk_add_f32 v[114:115], v[114:115], v[134:135]
	s_waitcnt vmcnt(8)
	v_pk_add_f32 v[112:113], v[112:113], v[152:153]
	v_pk_add_f32 v[114:115], v[114:115], v[138:139]
	s_waitcnt vmcnt(7)
	v_pk_add_f32 v[112:113], v[112:113], v[164:165]
	v_pk_add_f32 v[114:115], v[114:115], v[146:147]
	s_waitcnt vmcnt(6)
	v_pk_add_f32 v[112:113], v[112:113], v[168:169]
	v_pk_add_f32 v[114:115], v[114:115], v[154:155]
	s_waitcnt vmcnt(5)
	v_pk_add_f32 v[112:113], v[112:113], v[176:177]
	v_pk_add_f32 v[114:115], v[114:115], v[166:167]
	s_waitcnt vmcnt(4)
	v_pk_add_f32 v[112:113], v[112:113], v[128:129]
	v_pk_add_f32 v[114:115], v[114:115], v[170:171]
	s_waitcnt vmcnt(3)
	v_pk_add_f32 v[112:113], v[112:113], v[140:141]
	v_pk_add_f32 v[178:179], v[114:115], v[178:179]
	s_waitcnt vmcnt(2)
	v_pk_add_f32 v[112:113], v[112:113], v[156:157]
	v_pk_add_f32 v[130:131], v[178:179], v[130:131]
	s_waitcnt vmcnt(1)
	v_pk_add_f32 v[128:129], v[112:113], v[160:161]
	v_pk_add_f32 v[130:131], v[130:131], v[142:143]
	v_mfma_f32_16x16x32_bf16 v[104:107], v[28:31], v[108:111], v[188:191]
	v_add_f32_e64 v130, v130, v158
	v_add_f32_e64 v131, v131, v159
	s_nop 0
	global_load_dwordx4 v[188:191], v212, s[16:17] offset:192
	global_load_dwordx4 v[192:195], v212, s[16:17] offset:1216
	global_load_dwordx4 v[196:199], v212, s[16:17] offset:2240
	s_waitcnt vmcnt(3)
	v_pk_add_f32 v[128:129], v[128:129], v[172:173]
	s_nop 0
	v_pk_add_f32 v[228:229], v[148:149], v[128:129]
	v_mfma_f32_16x16x32_bf16 v[208:211], v[24:27], v[108:111], v[184:187]
	v_mul_f32_e32 v128, 0x3d372713, v228
	v_mul_f32_e32 v129, 0x3d372713, v229
	v_mul_f32_e32 v128, v228, v128
	v_mul_f32_e32 v129, v229, v129
	v_fma_f32 v128, v228, v128, v228
	v_fma_f32 v129, v229, v129, v229
	v_mul_f32_e32 v128, 0x3f4c422a, v128
	v_mul_f32_e32 v129, 0x3f4c422a, v129
	v_add_f32_e32 v128, v128, v128
	v_add_f32_e32 v129, v129, v129
	v_mul_f32_e32 v128, 0x3fb8aa3b, v128
	v_mul_f32_e32 v129, 0x3fb8aa3b, v129
	v_exp_f32_e32 v128, v128
	v_exp_f32_e32 v129, v129
	global_load_dwordx4 v[184:187], v212, s[16:17] offset:3264
	global_load_dwordx4 v[200:203], v[220:221], off offset:192
	global_load_dwordx4 v[204:207], v[218:219], off offset:3264
	global_load_dwordx4 v[112:115], v[218:219], off offset:2240
	v_mfma_f32_16x16x32_bf16 v[108:111], v[20:23], v[108:111], v[180:183]
	v_add_f32_e64 v230, v128, 1.0
	v_add_f32_e64 v231, v129, 1.0
	v_pk_add_f32 v[128:129], v[130:131], v[162:163]
	v_div_scale_f32 v160, s[0:1], v231, v231, 2.0
	v_rcp_f32_e32 v176, v160
	v_pk_add_f32 v[128:129], v[128:129], v[174:175]
	v_div_scale_f32 v161, vcc, 2.0, v231, 2.0
	v_fma_f32 v140, -v160, v176, 1.0
	v_pk_add_f32 v[244:245], v[150:151], v[128:129]
	global_load_dwordx4 v[128:131], v212, s[16:17] offset:64
	v_fmac_f32_e32 v176, v140, v176
	global_load_dwordx4 v[140:143], v212, s[16:17] offset:1088
	v_mul_f32_e32 v177, v161, v176
	v_div_scale_f32 v224, s[0:1], v230, v230, 2.0
	global_load_dwordx4 v[148:151], v212, s[16:17] offset:2112
	v_fma_f32 v156, -v160, v177, v161
	v_rcp_f32_e32 v225, v224
	v_fmac_f32_e32 v177, v156, v176
	global_load_dwordx4 v[156:159], v212, s[16:17] offset:3136
	v_fma_f32 v178, -v160, v177, v161
	global_load_dwordx4 v[160:163], v[220:221], off offset:64
	global_load_dwordx4 v[172:175], v[220:221], off offset:1088
	v_div_fmas_f32 v180, v178, v176, v177
; DI unsigned pack2(float a, float b) { v2f f = {a, b}; return __builtin_bit_cast(unsigned, __builtin_convertvector(f, v2bf)); }
;   DI u32x2 pack(int, int, float a, float b, float c, float d, float&) const { u32x2 v; v.x = pack2(a, b); v.y = pack2(c, d); return v; }
;   DI u32x2 pack(int m, int n, float a, float b, float c, float d, float& ss) const {
;     f32x4 bs = {0.f, 0.f, 0.f, 0.f};
; #pragma unroll
;     for (int kc = 0; kc < 16; ++kc) bs += *(const f32x4*)(bias_part + kc * 256 + n);
;     u32x2 v; v.x = pack2(gelu_tanh(a + bs[0]), gelu_tanh(b + bs[1])); v.y = pack2(gelu_tanh(c + bs[2]), gelu_tanh(d + bs[3]));
;     return v;
;   }
	global_load_dwordx4 v[176:179], v[220:221], off offset:2112
	v_div_fixup_f32 v231, v180, v231, 2.0
	v_fma_f32 v180, -v224, v225, 1.0
	global_load_dwordx4 v[132:135], v[220:221], off offset:2240
	v_fmac_f32_e32 v225, v180, v225
	global_load_dwordx4 v[180:183], v[220:221], off offset:3136
	v_div_scale_f32 v232, vcc, 2.0, v230, 2.0
	v_mul_f32_e32 v234, v232, v225
	v_fma_f32 v233, -v224, v234, v232
	v_fmac_f32_e32 v234, v233, v225
	v_fma_f32 v224, -v224, v234, v232
	v_mul_f32_e32 v232, 0x3d372713, v244
	v_mul_f32_e32 v233, 0x3d372713, v245
	v_mul_f32_e32 v232, v244, v232
	v_mul_f32_e32 v233, v245, v233
	v_fma_f32 v232, v244, v232, v244
	v_fma_f32 v233, v245, v233, v245
	v_mul_f32_e32 v232, 0x3f4c422a, v232
	v_mul_f32_e32 v233, 0x3f4c422a, v233
	v_add_f32_e32 v232, v232, v232
	v_add_f32_e32 v233, v233, v233
	v_mul_f32_e32 v232, 0x3fb8aa3b, v232
	v_mul_f32_e32 v233, 0x3fb8aa3b, v233
	v_exp_f32_e32 v232, v232
	v_exp_f32_e32 v233, v233
	v_div_fmas_f32 v224, v224, v225, v234
	v_div_fixup_f32 v230, v224, v230, 2.0
	v_pk_add_f32 v[230:231], v[230:231], 1.0 op_sel_hi:[1,0] neg_lo:[1,0] neg_hi:[1,0]
	v_pk_add_f32 v[232:233], v[232:233], 1.0 op_sel_hi:[1,0]
	v_pk_mul_f32 v[228:229], v[228:229], 0.5 op_sel_hi:[1,0]
	v_div_scale_f32 v224, s[0:1], v233, v233, 2.0
	v_rcp_f32_e32 v225, v224
	v_pk_add_f32 v[230:231], v[230:231], 1.0 op_sel_hi:[1,0]
	global_load_dwordx4 v[144:147], v[216:217], off offset:64
	global_load_dwordx4 v[152:155], v[216:217], off offset:1088
	v_pk_mul_f32 v[248:249], v[228:229], v[230:231]
	v_fma_f32 v228, -v224, v225, 1.0
	v_fmac_f32_e32 v225, v228, v225
	v_div_scale_f32 v228, vcc, 2.0, v233, 2.0
	v_mul_f32_e32 v229, v228, v225
	v_fma_f32 v230, -v224, v229, v228
	v_fmac_f32_e32 v229, v230, v225
	v_fma_f32 v224, -v224, v229, v228
	v_div_scale_f32 v228, s[0:1], v232, v232, 2.0
	v_rcp_f32_e32 v230, v228
	v_div_fmas_f32 v224, v224, v225, v229
	v_div_fixup_f32 v247, v224, v233, 2.0
	global_load_dwordx4 v[164:167], v[216:217], off offset:2112
	global_load_dwordx4 v[168:171], v[216:217], off offset:3136
	v_fma_f32 v224, -v228, v230, 1.0
	v_fmac_f32_e32 v230, v224, v230
	v_div_scale_f32 v224, vcc, 2.0, v232, 2.0
	v_mul_f32_e32 v225, v224, v230
	v_fma_f32 v229, -v228, v225, v224
	v_fmac_f32_e32 v225, v229, v230
	v_fma_f32 v224, -v228, v225, v224
	v_div_fmas_f32 v224, v224, v230, v225
	v_div_fixup_f32 v246, v224, v232, 2.0
	global_load_dwordx4 v[228:231], v212, s[16:17] offset:128
	global_load_dwordx4 v[124:127], v[220:221], off offset:1216
	s_waitcnt vmcnt(14)
	v_pk_add_f32 v[232:233], v[130:131], 0 op_sel_hi:[1,0]
	v_pk_add_f32 v[234:235], v[128:129], 0 op_sel_hi:[1,0]
	global_load_dwordx4 v[128:131], v212, s[16:17] offset:1152
	s_waitcnt vmcnt(14)
	v_pk_add_f32 v[232:233], v[232:233], v[142:143]
	v_pk_add_f32 v[234:235], v[234:235], v[140:141]
	global_load_dwordx4 v[140:143], v212, s[16:17] offset:2176
	s_waitcnt vmcnt(14)
	v_pk_add_f32 v[232:233], v[232:233], v[150:151]
	v_pk_add_f32 v[234:235], v[234:235], v[148:149]
	global_load_dwordx4 v[148:151], v212, s[16:17] offset:3200
	global_load_dwordx4 v[136:139], v[220:221], off offset:3264
	s_waitcnt vmcnt(15)
	v_pk_add_f32 v[232:233], v[232:233], v[158:159]
	v_pk_add_f32 v[234:235], v[234:235], v[156:157]
	s_waitcnt vmcnt(14)
	v_pk_add_f32 v[232:233], v[232:233], v[162:163]
	global_load_dwordx4 v[156:159], v[220:221], off offset:128
	v_pk_add_f32 v[234:235], v[234:235], v[160:161]
	s_waitcnt vmcnt(14)
	v_pk_add_f32 v[232:233], v[232:233], v[174:175]
	v_pk_add_f32 v[234:235], v[234:235], v[172:173]
	global_load_dwordx4 v[172:175], v[220:221], off offset:2176
	s_waitcnt vmcnt(14)
	v_pk_add_f32 v[240:241], v[232:233], v[178:179]
	global_load_dwordx4 v[116:119], v[218:219], off offset:192
	global_load_dwordx4 v[120:123], v[218:219], off offset:1216
	global_load_dwordx4 v[160:163], v[220:221], off offset:1152
	v_pk_add_f32 v[250:251], v[234:235], v[176:177]
	global_load_dwordx4 v[176:179], v[218:219], off offset:64
	global_load_dwordx4 v[232:235], v[218:219], off offset:1088
	global_load_dwordx4 v[236:239], v[220:221], off offset:3200
	s_waitcnt vmcnt(18)
	v_pk_add_f32 v[252:253], v[240:241], v[182:183]
	global_load_dwordx4 v[240:243], v[218:219], off offset:2112
	v_pk_add_f32 v[250:251], v[250:251], v[180:181]
	global_load_dwordx4 v[180:183], v[218:219], off offset:3136
	v_pk_add_f32 v[246:247], v[246:247], 1.0 op_sel_hi:[1,0] neg_lo:[1,0] neg_hi:[1,0]
	v_pk_mul_f32 v[244:245], v[244:245], 0.5 op_sel_hi:[1,0]
	v_pk_add_f32 v[246:247], v[246:247], 1.0 op_sel_hi:[1,0]
	v_mfma_f32_16x16x32_bf16 v[92:95], v[52:55], v[100:103], v[92:95]
	v_mul_f32_e64 v224, v244, v246
	v_mul_f32_e64 v225, v245, v247
	global_load_dwordx4 v[244:247], v[218:219], off offset:3200
	s_waitcnt vmcnt(20)
	v_pk_add_f32 v[144:145], v[250:251], v[144:145]
	s_waitcnt vmcnt(19)
	v_pk_add_f32 v[144:145], v[144:145], v[152:153]
	v_pk_add_f32 v[146:147], v[252:253], v[146:147]
	v_mfma_f32_16x16x32_bf16 v[84:87], v[48:51], v[100:103], v[84:87]
	v_add_f32_e64 v146, v146, v154
	v_add_f32_e64 v147, v147, v155
	s_waitcnt vmcnt(18)
	v_pk_add_f32 v[144:145], v[144:145], v[164:165]
	s_waitcnt vmcnt(17)
	v_pk_add_f32 v[152:153], v[144:145], v[168:169]
	v_pk_add_f32 v[146:147], v[146:147], v[166:167]
	global_load_dwordx4 v[166:169], v[218:219], off offset:2176
	v_pk_add_f32 v[170:171], v[146:147], v[170:171]
	global_load_dwordx4 v[144:147], v[218:219], off offset:128
	v_mfma_f32_16x16x32_bf16 v[80:83], v[44:47], v[100:103], v[80:83]
	s_waitcnt vmcnt(7)
	v_pk_add_f32 v[164:165], v[152:153], v[176:177]
	s_waitcnt vmcnt(6)
	v_pk_add_f32 v[164:165], v[164:165], v[232:233]
	v_pk_add_f32 v[170:171], v[170:171], v[178:179]
	global_load_dwordx4 v[152:155], v[218:219], off offset:1152
	s_waitcnt vmcnt(5)
; DI unsigned pack2(float a, float b) { v2f f = {a, b}; return __builtin_bit_cast(unsigned, __builtin_convertvector(f, v2bf)); }
;   DI u32x2 pack(int, int, float a, float b, float c, float d, float&) const { u32x2 v; v.x = pack2(a, b); v.y = pack2(c, d); return v; }
;   DI u32x2 pack(int m, int n, float a, float b, float c, float d, float& ss) const {
;     f32x4 bs = {0.f, 0.f, 0.f, 0.f};
; #pragma unroll
;     for (int kc = 0; kc < 16; ++kc) bs += *(const f32x4*)(bias_part + kc * 256 + n);
;     u32x2 v; v.x = pack2(gelu_tanh(a + bs[0]), gelu_tanh(b + bs[1])); v.y = pack2(gelu_tanh(c + bs[2]), gelu_tanh(d + bs[3]));
;     return v;
;   }
	v_pk_add_f32 v[164:165], v[164:165], v[240:241]
	v_pk_add_f32 v[170:171], v[170:171], v[234:235]
	s_waitcnt vmcnt(4)
	v_pk_add_f32 v[164:165], v[164:165], v[180:181]
	v_pk_add_f32 v[170:171], v[170:171], v[242:243]
	v_pk_add_f32 v[250:251], v[104:105], v[164:165]
	v_pk_add_f32 v[170:171], v[170:171], v[182:183]
	v_mul_f32_e32 v104, 0x3d372713, v250
	v_mul_f32_e32 v105, 0x3d372713, v251
	v_mul_f32_e32 v104, v250, v104
	v_mul_f32_e32 v105, v251, v105
	v_fma_f32 v104, v250, v104, v250
	v_fma_f32 v105, v251, v105, v251
	v_mul_f32_e32 v104, 0x3f4c422a, v104
	v_mul_f32_e32 v105, 0x3f4c422a, v105
	v_add_f32_e32 v104, v104, v104
	v_add_f32_e32 v105, v105, v105
	v_mul_f32_e32 v104, 0x3fb8aa3b, v104
	v_mul_f32_e32 v105, 0x3fb8aa3b, v105
	v_exp_f32_e32 v104, v104
	v_exp_f32_e32 v105, v105
	v_pk_add_f32 v[170:171], v[106:107], v[170:171]
	v_or_b32_e32 v164, s34, v227
	global_load_dwordx4 v[180:183], v[216:217], off offset:1152
	v_pk_add_f32 v[104:105], v[104:105], 1.0 op_sel_hi:[1,0]
	global_load_dwordx4 v[232:235], v[216:217], off offset:2176
	v_div_scale_f32 v165, s[0:1], v105, v105, 2.0
	v_rcp_f32_e32 v176, v165
	global_load_dwordx4 v[240:243], v[216:217], off offset:3200
	v_lshl_add_u32 v164, v254, 6, v164
	v_mfma_f32_16x16x32_bf16 v[92:95], v[32:35], v[96:99], v[92:95]
	v_fma_f32 v106, -v165, v176, 1.0
	v_fmac_f32_e32 v176, v106, v176
	v_div_scale_f32 v106, vcc, 2.0, v105, 2.0
	v_mul_f32_e32 v107, v106, v176
	v_fma_f32 v177, -v165, v107, v106
	v_fmac_f32_e32 v107, v177, v176
	v_fma_f32 v106, -v165, v107, v106
	v_div_scale_f32 v165, s[0:1], v104, v104, 2.0
	v_rcp_f32_e32 v227, v165
	v_div_fmas_f32 v106, v106, v176, v107
	v_div_fixup_f32 v107, v106, v105, 2.0
	v_mfma_f32_16x16x32_bf16 v[68:71], v[52:55], v[76:79], v[68:71]
	v_fma_f32 v105, -v165, v227, 1.0
	v_fmac_f32_e32 v227, v105, v227
	v_div_scale_f32 v105, vcc, 2.0, v104, 2.0
	v_mul_f32_e32 v106, v105, v227
	v_fma_f32 v176, -v165, v106, v105
	v_fmac_f32_e32 v106, v176, v227
	global_load_dwordx4 v[176:179], v[216:217], off offset:128
	v_fma_f32 v105, -v165, v106, v105
	v_div_fmas_f32 v105, v105, v227, v106
	v_div_fixup_f32 v106, v105, v104, 2.0
	v_mul_f32_e32 v104, 0x3d372713, v170
	v_mul_f32_e32 v104, v170, v104
	v_fma_f32 v104, v170, v104, v170
	v_mul_f32_e32 v104, 0x3f4c422a, v104
	v_add_f32_e32 v104, v104, v104
	v_mul_f32_e32 v104, 0x3fb8aa3b, v104
	v_exp_f32_e32 v252, v104
	v_mul_f32_e32 v104, 0x3d372713, v171
	v_mul_f32_e32 v104, v171, v104
	v_fma_f32 v104, v171, v104, v171
	v_mul_f32_e32 v104, 0x3f4c422a, v104
	v_add_f32_e32 v104, v104, v104
	v_mul_f32_e32 v104, 0x3fb8aa3b, v104
	v_exp_f32_e32 v253, v104
	v_cvt_pk_bf16_f32 v104, v248, v249
	v_pk_add_f32 v[106:107], v[106:107], 1.0 op_sel_hi:[1,0] neg_lo:[1,0] neg_hi:[1,0]
	v_cvt_pk_bf16_f32 v105, v224, v225
	v_pk_add_f32 v[248:249], v[252:253], 1.0 op_sel_hi:[1,0]
	v_pk_mul_f32 v[224:225], v[250:251], 0.5 op_sel_hi:[1,0]
	v_div_scale_f32 v165, s[0:1], v249, v249, 2.0
	v_rcp_f32_e32 v227, v165
	v_pk_add_f32 v[106:107], v[106:107], 1.0 op_sel_hi:[1,0]
	v_div_scale_f32 v250, s[0:1], v248, v248, 2.0
	v_pk_mul_f32 v[106:107], v[224:225], v[106:107]
	v_rcp_f32_e32 v251, v250
	v_cvt_pk_bf16_f32 v106, v106, v107
	v_fma_f32 v107, -v165, v227, 1.0
	v_fmac_f32_e32 v227, v107, v227
	v_div_scale_f32 v107, vcc, 2.0, v249, 2.0
	v_mul_f32_e32 v224, v107, v227
	v_fma_f32 v225, -v165, v224, v107
	v_fmac_f32_e32 v224, v225, v227
	v_fma_f32 v107, -v165, v224, v107
	v_fma_f32 v165, -v250, v251, 1.0
	v_div_fmas_f32 v107, v107, v227, v224
	v_fmac_f32_e32 v251, v165, v251
	v_div_scale_f32 v165, vcc, 2.0, v248, 2.0
	v_mul_f32_e32 v224, v165, v251
	v_fma_f32 v225, -v250, v224, v165
	v_fmac_f32_e32 v224, v225, v251
	v_div_fixup_f32 v225, v107, v249, 2.0
	v_fma_f32 v107, -v250, v224, v165
	v_div_fmas_f32 v107, v107, v251, v224
	v_div_fixup_f32 v224, v107, v248, 2.0
	v_pk_add_f32 v[224:225], v[224:225], 1.0 op_sel_hi:[1,0] neg_lo:[1,0] neg_hi:[1,0]
	v_pk_mul_f32 v[170:171], v[170:171], 0.5 op_sel_hi:[1,0]
	v_pk_add_f32 v[224:225], v[224:225], 1.0 op_sel_hi:[1,0]
	v_ashrrev_i32_e32 v165, 31, v164
	v_pk_mul_f32 v[170:171], v[170:171], v[224:225]
	v_pk_add_f32 v[224:225], v[228:229], 0 op_sel_hi:[1,0]
	v_cvt_pk_bf16_f32 v107, v170, v171
	v_pk_add_f32 v[170:171], v[230:231], 0 op_sel_hi:[1,0]
	v_pk_add_f32 v[128:129], v[224:225], v[128:129]
	v_pk_add_f32 v[130:131], v[170:171], v[130:131]
	v_pk_add_f32 v[128:129], v[128:129], v[140:141]
	v_pk_add_f32 v[130:131], v[130:131], v[142:143]
	v_pk_add_f32 v[128:129], v[128:129], v[148:149]
	v_pk_add_f32 v[130:131], v[130:131], v[150:151]
	v_pk_add_f32 v[128:129], v[128:129], v[156:157]
	v_pk_add_f32 v[130:131], v[130:131], v[158:159]
	v_pk_add_f32 v[128:129], v[128:129], v[160:161]
	v_pk_add_f32 v[130:131], v[130:131], v[162:163]
	v_pk_add_f32 v[128:129], v[128:129], v[172:173]
	v_pk_add_f32 v[130:131], v[130:131], v[174:175]
	v_pk_add_f32 v[142:143], v[128:129], v[236:237]
	v_pk_add_f32 v[140:141], v[130:131], v[238:239]
	global_load_dwordx4 v[128:131], v[216:217], off offset:192
	v_permlane16_swap_b32_e32 v104, v106
	v_permlane16_swap_b32_e32 v105, v107
	v_mfma_f32_16x16x32_bf16 v[170:173], v[40:43], v[100:103], v[88:91]
	s_waitcnt vmcnt(1)
; DI unsigned pack2(float a, float b) { v2f f = {a, b}; return __builtin_bit_cast(unsigned, __builtin_convertvector(f, v2bf)); }
;   DI u32x2 pack(int, int, float a, float b, float c, float d, float&) const { u32x2 v; v.x = pack2(a, b); v.y = pack2(c, d); return v; }
;   DI u32x2 pack(int m, int n, float a, float b, float c, float d, float& ss) const {
;     f32x4 bs = {0.f, 0.f, 0.f, 0.f};
; #pragma unroll
;     for (int kc = 0; kc < 16; ++kc) bs += *(const f32x4*)(bias_part + kc * 256 + n);
;     u32x2 v; v.x = pack2(gelu_tanh(a + bs[0]), gelu_tanh(b + bs[1])); v.y = pack2(gelu_tanh(c + bs[2]), gelu_tanh(d + bs[3]));
;     return v;
;   }
	v_pk_add_f32 v[150:151], v[142:143], v[176:177]
	v_pk_add_f32 v[148:149], v[140:141], v[178:179]
	global_load_dwordx4 v[140:143], v[216:217], off offset:1216
	v_pk_add_f32 v[158:159], v[150:151], v[180:181]
	v_pk_add_f32 v[156:157], v[148:149], v[182:183]
	global_load_dwordx4 v[148:151], v[216:217], off offset:2240
	v_pk_add_f32 v[162:163], v[158:159], v[232:233]
	v_pk_add_f32 v[160:161], v[156:157], v[234:235]
	global_load_dwordx4 v[156:159], v[216:217], off offset:3264
	v_pk_add_f32 v[162:163], v[162:163], v[240:241]
	v_pk_add_f32 v[160:161], v[160:161], v[242:243]
	v_pk_add_f32 v[144:145], v[162:163], v[144:145]
	v_pk_add_f32 v[146:147], v[160:161], v[146:147]
	v_pk_add_f32 v[144:145], v[144:145], v[152:153]
	v_pk_add_f32 v[146:147], v[146:147], v[154:155]
	v_pk_add_f32 v[144:145], v[144:145], v[166:167]
	v_pk_add_f32 v[146:147], v[146:147], v[168:169]
	v_pk_add_f32 v[144:145], v[144:145], v[244:245]
	v_pk_add_f32 v[146:147], v[146:147], v[246:247]
	v_pk_add_f32 v[144:145], v[208:209], v[144:145]
	v_pk_add_f32 v[146:147], v[210:211], v[146:147]
	v_mul_f32_e32 v152, 0x3d372713, v144
	v_mul_f32_e32 v153, 0x3d372713, v145
	v_mul_f32_e32 v152, v144, v152
	v_mul_f32_e32 v153, v145, v153
	v_fma_f32 v152, v144, v152, v144
	v_fma_f32 v153, v145, v153, v145
	v_mul_f32_e32 v152, 0x3f4c422a, v152
	v_mul_f32_e32 v153, 0x3f4c422a, v153
	v_add_f32_e32 v152, v152, v152
	v_add_f32_e32 v153, v153, v153
	v_mul_f32_e32 v152, 0x3fb8aa3b, v152
	v_mul_f32_e32 v153, 0x3fb8aa3b, v153
	v_exp_f32_e32 v152, v152
	v_exp_f32_e32 v153, v153
	v_pk_mul_f32 v[144:145], v[144:145], 0.5 op_sel_hi:[1,0]
	v_mov_b32_e32 v167, v213
	v_mov_b32_e32 v169, v213
	v_pk_add_f32 v[152:153], v[152:153], 1.0 op_sel_hi:[1,0]
	v_mfma_f32_16x16x32_bf16 v[88:91], v[28:31], v[96:99], v[84:87]
	v_div_scale_f32 v154, s[0:1], v153, v153, 2.0
	v_rcp_f32_e32 v155, v154
	v_mfma_f32_16x16x32_bf16 v[84:87], v[24:27], v[96:99], v[80:83]
	v_fma_f32 v160, -v154, v155, 1.0
	v_fmac_f32_e32 v155, v160, v155
	v_div_scale_f32 v160, vcc, 2.0, v153, 2.0
	v_mul_f32_e32 v161, v160, v155
	v_fma_f32 v162, -v154, v161, v160
	v_fmac_f32_e32 v161, v162, v155
	v_fma_f32 v154, -v154, v161, v160
	v_div_scale_f32 v160, s[0:1], v152, v152, 2.0
	v_rcp_f32_e32 v162, v160
	v_div_fmas_f32 v154, v154, v155, v161
	v_div_fixup_f32 v153, v154, v153, 2.0
	v_mfma_f32_16x16x32_bf16 v[80:83], v[20:23], v[96:99], v[170:173]
	v_fma_f32 v154, -v160, v162, 1.0
	v_fmac_f32_e32 v162, v154, v162
	v_div_scale_f32 v154, vcc, 2.0, v152, 2.0
	v_mul_f32_e32 v155, v154, v162
	v_fma_f32 v161, -v160, v155, v154
	v_fmac_f32_e32 v155, v161, v162
	v_fma_f32 v154, -v160, v155, v154
	v_div_fmas_f32 v160, v154, v162, v155
	v_mul_f32_e32 v154, 0x3d372713, v146
	v_mul_f32_e32 v155, 0x3d372713, v147
	v_mul_f32_e32 v154, v146, v154
	v_mul_f32_e32 v155, v147, v155
	v_fma_f32 v154, v146, v154, v146
	v_fma_f32 v155, v147, v155, v147
	v_mul_f32_e32 v154, 0x3f4c422a, v154
	v_mul_f32_e32 v155, 0x3f4c422a, v155
	v_add_f32_e32 v154, v154, v154
	v_add_f32_e32 v155, v155, v155
	v_mul_f32_e32 v154, 0x3fb8aa3b, v154
	v_mul_f32_e32 v155, 0x3fb8aa3b, v155
	v_exp_f32_e32 v154, v154
	v_exp_f32_e32 v155, v155
	v_div_fixup_f32 v152, v160, v152, 2.0
	v_pk_add_f32 v[152:153], v[152:153], 1.0 op_sel_hi:[1,0] neg_lo:[1,0] neg_hi:[1,0]
	v_pk_mul_f32 v[146:147], v[146:147], 0.5 op_sel_hi:[1,0]
	v_pk_add_f32 v[154:155], v[154:155], 1.0 op_sel_hi:[1,0]
	v_pk_add_f32 v[152:153], v[152:153], 1.0 op_sel_hi:[1,0]
	v_div_scale_f32 v160, s[0:1], v155, v155, 2.0
	v_rcp_f32_e32 v161, v160
	v_pk_mul_f32 v[144:145], v[144:145], v[152:153]
	v_mfma_f32_16x16x32_bf16 v[60:63], v[48:51], v[76:79], v[60:63]
	v_cvt_pk_bf16_f32 v144, v144, v145
	v_fma_f32 v145, -v160, v161, 1.0
	v_fmac_f32_e32 v161, v145, v161
	v_div_scale_f32 v145, vcc, 2.0, v155, 2.0
	v_mul_f32_e32 v152, v145, v161
	v_fma_f32 v153, -v160, v152, v145
	v_fmac_f32_e32 v152, v153, v161
	v_fma_f32 v145, -v160, v152, v145
	v_div_scale_f32 v160, s[0:1], v154, v154, 2.0
	v_rcp_f32_e32 v162, v160
	v_div_fmas_f32 v145, v145, v161, v152
	v_div_fixup_f32 v153, v145, v155, 2.0
	v_mfma_f32_16x16x32_bf16 v[56:59], v[44:47], v[76:79], v[56:59]
	v_fma_f32 v145, -v160, v162, 1.0
	v_fmac_f32_e32 v162, v145, v162
	v_div_scale_f32 v145, vcc, 2.0, v154, 2.0
	v_mul_f32_e32 v152, v145, v162
	v_fma_f32 v155, -v160, v152, v145
	v_fmac_f32_e32 v152, v155, v162
	v_fma_f32 v145, -v160, v152, v145
	v_div_fmas_f32 v145, v145, v162, v152
	v_div_fixup_f32 v152, v145, v154, 2.0
	v_pk_add_f32 v[152:153], v[152:153], 1.0 op_sel_hi:[1,0] neg_lo:[1,0] neg_hi:[1,0]
	v_mfma_f32_16x16x32_bf16 v[68:71], v[32:35], v[72:75], v[68:71]
	v_add_f32_e64 v152, v152, 1.0
	v_add_f32_e64 v153, v153, 1.0
	v_pk_mul_f32 v[146:147], v[146:147], v[152:153]
	v_pk_add_f32 v[152:153], v[188:189], 0 op_sel_hi:[1,0]
	v_cvt_pk_bf16_f32 v145, v146, v147
	v_pk_add_f32 v[152:153], v[152:153], v[192:193]
	v_pk_add_f32 v[146:147], v[190:191], 0 op_sel_hi:[1,0]
	v_pk_add_f32 v[152:153], v[152:153], v[196:197]
	v_pk_add_f32 v[146:147], v[146:147], v[194:195]
	v_pk_add_f32 v[152:153], v[152:153], v[184:185]
	v_pk_add_f32 v[146:147], v[146:147], v[198:199]
	v_pk_add_f32 v[152:153], v[152:153], v[200:201]
	v_pk_add_f32 v[146:147], v[146:147], v[186:187]
	v_pk_add_f32 v[124:125], v[152:153], v[124:125]
	v_pk_add_f32 v[146:147], v[146:147], v[202:203]
	v_pk_add_f32 v[124:125], v[124:125], v[132:133]
	v_pk_add_f32 v[126:127], v[146:147], v[126:127]
	v_pk_add_f32 v[124:125], v[124:125], v[136:137]
	v_pk_add_f32 v[126:127], v[126:127], v[134:135]
	s_waitcnt vmcnt(3)
	v_pk_add_f32 v[124:125], v[124:125], v[128:129]
	v_pk_add_f32 v[126:127], v[126:127], v[138:139]
	s_waitcnt vmcnt(2)
; DI unsigned pack2(float a, float b) { v2f f = {a, b}; return __builtin_bit_cast(unsigned, __builtin_convertvector(f, v2bf)); }
;   DI u32x2 pack(int, int, float a, float b, float c, float d, float&) const { u32x2 v; v.x = pack2(a, b); v.y = pack2(c, d); return v; }
; template <class ARow, class Epi>
; DI void gemm_tile(const ARow& arow, long a_kstride, const u16* __restrict__ Bt, long ldb, int K, int m0, int n0,
;                   const Epi& epi, char* smem) {
;     ...
;       for (int ni = 0; ni < 4; ++ni) pk[ni] = epi.pack(m, nh + ni * 16 + fq * 4, acc[ni][mi][0], acc[ni][mi][1], acc[ni][mi][2], acc[ni][mi][3], ss);
;       epi.finish16(m, nh, ss);
;       u16* rp = epi.rowp(m) + nh;
; #pragma unroll
;       for (int pp = 0; pp < 2; ++pp) {
;         u32x2 a = pk[2 * pp], b = pk[2 * pp + 1];
;         const u32x2 rx = __builtin_amdgcn_permlane16_swap(a.x, b.x, false, false);
;         const u32x2 ry = __builtin_amdgcn_permlane16_swap(a.y, b.y, false, false);
;         const int nst = (fq & 1) ? ((2 * pp + 1) * 16 + (fq - 1) * 4) : ((2 * pp) * 16 + fq * 4);
;         *(u32x4*)(rp + nst) = (u32x4){rx[0], ry[0], rx[1], ry[1]};
;   DI u32x2 pack(int m, int n, float a, float b, float c, float d, float& ss) const {
;     f32x4 bs = {0.f, 0.f, 0.f, 0.f};
; #pragma unroll
;     for (int kc = 0; kc < 16; ++kc) bs += *(const f32x4*)(bias_part + kc * 256 + n);
;     u32x2 v; v.x = pack2(gelu_tanh(a + bs[0]), gelu_tanh(b + bs[1])); v.y = pack2(gelu_tanh(c + bs[2]), gelu_tanh(d + bs[3]));
;     return v;
;   }
	v_pk_add_f32 v[124:125], v[124:125], v[140:141]
	v_pk_add_f32 v[126:127], v[126:127], v[130:131]
	s_waitcnt vmcnt(1)
	v_pk_add_f32 v[124:125], v[124:125], v[148:149]
	v_pk_add_f32 v[126:127], v[126:127], v[142:143]
	s_waitcnt vmcnt(0)
	v_pk_add_f32 v[124:125], v[124:125], v[156:157]
	v_pk_add_f32 v[126:127], v[126:127], v[150:151]
	v_pk_add_f32 v[116:117], v[124:125], v[116:117]
	v_mfma_f32_16x16x32_bf16 v[12:15], v[52:55], v[36:39], v[12:15]
	v_add_f32_e64 v116, v116, v120
	v_add_f32_e64 v117, v117, v121
	v_pk_add_f32 v[112:113], v[116:117], v[112:113]
	v_pk_add_f32 v[116:117], v[126:127], v[158:159]
	v_pk_add_f32 v[112:113], v[112:113], v[204:205]
	v_pk_add_f32 v[116:117], v[116:117], v[118:119]
	v_pk_add_f32 v[108:109], v[108:109], v[112:113]
	v_pk_add_f32 v[116:117], v[116:117], v[122:123]
	v_mul_f32_e32 v112, 0x3d372713, v108
	v_mul_f32_e32 v113, 0x3d372713, v109
	v_mul_f32_e32 v112, v108, v112
	v_mul_f32_e32 v113, v109, v113
	v_fma_f32 v112, v108, v112, v108
	v_fma_f32 v113, v109, v113, v109
	v_mul_f32_e32 v112, 0x3f4c422a, v112
	v_mul_f32_e32 v113, 0x3f4c422a, v113
	v_add_f32_e32 v112, v112, v112
	v_add_f32_e32 v113, v113, v113
	v_mul_f32_e32 v112, 0x3fb8aa3b, v112
	v_mul_f32_e32 v113, 0x3fb8aa3b, v113
	v_exp_f32_e32 v112, v112
	v_exp_f32_e32 v113, v113
	v_pk_add_f32 v[114:115], v[116:117], v[114:115]
	v_pk_mul_f32 v[108:109], v[108:109], 0.5 op_sel_hi:[1,0]
	v_pk_add_f32 v[114:115], v[114:115], v[206:207]
	v_pk_add_f32 v[112:113], v[112:113], 1.0 op_sel_hi:[1,0]
	v_pk_add_f32 v[110:111], v[110:111], v[114:115]
	v_div_scale_f32 v118, s[0:1], v113, v113, 2.0
	v_rcp_f32_e32 v119, v118
	v_mfma_f32_16x16x32_bf16 v[4:7], v[48:51], v[36:39], v[4:7]
	v_fma_f32 v114, -v118, v119, 1.0
	v_fmac_f32_e32 v119, v114, v119
	v_div_scale_f32 v114, vcc, 2.0, v113, 2.0
	v_mul_f32_e32 v115, v114, v119
	v_fma_f32 v116, -v118, v115, v114
	v_fmac_f32_e32 v115, v116, v119
	v_div_scale_f32 v116, s[0:1], v112, v112, 2.0
	v_rcp_f32_e32 v117, v116
	v_fma_f32 v114, -v118, v115, v114
	v_div_fmas_f32 v114, v114, v119, v115
	v_div_fixup_f32 v113, v114, v113, 2.0
	v_fma_f32 v114, -v116, v117, 1.0
	v_fmac_f32_e32 v117, v114, v117
	v_div_scale_f32 v114, vcc, 2.0, v112, 2.0
	v_mul_f32_e32 v115, v114, v117
	v_fma_f32 v118, -v116, v115, v114
	v_fmac_f32_e32 v115, v118, v117
	v_fma_f32 v114, -v116, v115, v114
	v_div_fmas_f32 v116, v114, v117, v115
	v_mul_f32_e32 v114, 0x3d372713, v110
	v_mul_f32_e32 v115, 0x3d372713, v111
	v_mul_f32_e32 v114, v110, v114
	v_mul_f32_e32 v115, v111, v115
	v_fma_f32 v114, v110, v114, v110
	v_fma_f32 v115, v111, v115, v111
	v_mul_f32_e32 v114, 0x3f4c422a, v114
	v_mul_f32_e32 v115, 0x3f4c422a, v115
	v_add_f32_e32 v114, v114, v114
	v_add_f32_e32 v115, v115, v115
	v_mul_f32_e32 v114, 0x3fb8aa3b, v114
	v_mul_f32_e32 v115, 0x3fb8aa3b, v115
	v_exp_f32_e32 v114, v114
	v_exp_f32_e32 v115, v115
	v_div_fixup_f32 v112, v116, v112, 2.0
	v_pk_add_f32 v[112:113], v[112:113], 1.0 op_sel_hi:[1,0] neg_lo:[1,0] neg_hi:[1,0]
	v_pk_mul_f32 v[110:111], v[110:111], 0.5 op_sel_hi:[1,0]
	v_pk_add_f32 v[114:115], v[114:115], 1.0 op_sel_hi:[1,0]
	v_pk_add_f32 v[112:113], v[112:113], 1.0 op_sel_hi:[1,0]
	v_div_scale_f32 v116, s[0:1], v115, v115, 2.0
	v_rcp_f32_e32 v117, v116
	v_pk_mul_f32 v[108:109], v[108:109], v[112:113]
	v_mfma_f32_16x16x32_bf16 v[0:3], v[44:47], v[36:39], v[0:3]
	v_cvt_pk_bf16_f32 v146, v108, v109
	v_fma_f32 v108, -v116, v117, 1.0
	v_fmac_f32_e32 v117, v108, v117
	v_div_scale_f32 v108, vcc, 2.0, v115, 2.0
	v_mul_f32_e32 v109, v108, v117
	v_fma_f32 v112, -v116, v109, v108
	v_fmac_f32_e32 v109, v112, v117
	v_div_scale_f32 v112, s[0:1], v114, v114, 2.0
	v_rcp_f32_e32 v113, v112
	v_fma_f32 v108, -v116, v109, v108
	v_div_fmas_f32 v108, v108, v117, v109
	v_div_fixup_f32 v109, v108, v115, 2.0
	v_fma_f32 v108, -v112, v113, 1.0
	v_fmac_f32_e32 v113, v108, v113
	v_div_scale_f32 v108, vcc, 2.0, v114, 2.0
	v_mul_f32_e32 v115, v108, v113
	v_fma_f32 v116, -v112, v115, v108
	v_fmac_f32_e32 v115, v116, v113
	v_fma_f32 v108, -v112, v115, v108
	v_div_fmas_f32 v108, v108, v113, v115
	v_div_fixup_f32 v108, v108, v114, 2.0
	v_pk_add_f32 v[108:109], v[108:109], 1.0 op_sel_hi:[1,0] neg_lo:[1,0] neg_hi:[1,0]
	v_cmp_eq_u32_e32 vcc, 0, v223
	v_pk_add_f32 v[108:109], v[108:109], 1.0 op_sel_hi:[1,0]
	v_permlane16_swap_b32_e32 v144, v146
	v_pk_mul_f32 v[108:109], v[110:111], v[108:109]
	v_add_u32_e32 v110, 12, v226
	v_cvt_pk_bf16_f32 v147, v108, v109
	v_lshlrev_b64 v[108:109], 9, v[164:165]
	v_cndmask_b32_e32 v110, v110, v226, vcc
	v_lshl_add_u64 v[108:109], v[214:215], 0, v[108:109]
	v_lshlrev_b32_e32 v166, 1, v110
	v_lshl_add_u64 v[110:111], v[108:109], 0, v[166:167]
	global_store_dwordx4 v[110:111], v[104:107], off
	v_permlane16_swap_b32_e32 v145, v147
	s_nop 0
	v_add_u32_e32 v104, 44, v226
	v_or_b32_e32 v105, 32, v226
	v_cndmask_b32_e32 v104, v104, v105, vcc
	v_lshlrev_b32_e32 v168, 1, v104
	v_lshl_add_u64 v[104:105], v[108:109], 0, v[168:169]
	global_store_dwordx4 v[104:105], v[144:147], off
	global_load_dwordx4 v[144:147], v212, s[16:17]
	s_nop 0
	global_load_dwordx4 v[148:151], v212, s[16:17] offset:1024
	global_load_dwordx4 v[152:155], v212, s[16:17] offset:2048
	global_load_dwordx4 v[156:159], v212, s[16:17] offset:3072
	global_load_dwordx4 v[160:163], v[216:217], off offset:-4096
	global_load_dwordx4 v[136:139], v[220:221], off offset:1024
	global_load_dwordx4 v[128:131], v[220:221], off offset:2048
	global_load_dwordx4 v[124:127], v[220:221], off offset:3072
	global_load_dwordx4 v[116:119], v[218:219], off offset:-4096
	global_load_dwordx4 v[132:135], v[216:217], off offset:1024
	global_load_dwordx4 v[140:143], v[216:217], off offset:2048
	global_load_dwordx4 v[100:103], v[216:217], off offset:3072
	global_load_dwordx4 v[104:107], v[218:219], off
	global_load_dwordx4 v[108:111], v[218:219], off offset:1024
	global_load_dwordx4 v[112:115], v[218:219], off offset:2048
	global_load_dwordx4 v[120:123], v[218:219], off offset:3072
	global_load_dwordx4 v[182:185], v[218:219], off offset:3136
	global_load_dwordx4 v[96:99], v212, s[16:17] offset:64
	global_load_dwordx4 v[174:177], v[218:219], off offset:1088
	global_load_dwordx4 v[178:181], v[218:219], off offset:2112
	v_mfma_f32_16x16x32_bf16 v[12:15], v[32:35], v[16:19], v[12:15]
	s_waitcnt vmcnt(19)
; DI unsigned pack2(float a, float b) { v2f f = {a, b}; return __builtin_bit_cast(unsigned, __builtin_convertvector(f, v2bf)); }
;   DI u32x2 pack(int, int, float a, float b, float c, float d, float&) const { u32x2 v; v.x = pack2(a, b); v.y = pack2(c, d); return v; }
;   DI u32x2 pack(int m, int n, float a, float b, float c, float d, float& ss) const {
;     f32x4 bs = {0.f, 0.f, 0.f, 0.f};
; #pragma unroll
;     for (int kc = 0; kc < 16; ++kc) bs += *(const f32x4*)(bias_part + kc * 256 + n);
;     u32x2 v; v.x = pack2(gelu_tanh(a + bs[0]), gelu_tanh(b + bs[1])); v.y = pack2(gelu_tanh(c + bs[2]), gelu_tanh(d + bs[3]));
;     return v;
;   }
	v_pk_add_f32 v[170:171], v[146:147], 0 op_sel_hi:[1,0]
	v_pk_add_f32 v[172:173], v[144:145], 0 op_sel_hi:[1,0]
	s_waitcnt vmcnt(18)
	v_pk_add_f32 v[170:171], v[170:171], v[150:151]
	v_pk_add_f32 v[172:173], v[172:173], v[148:149]
	s_waitcnt vmcnt(17)
	v_pk_add_f32 v[170:171], v[170:171], v[154:155]
	v_pk_add_f32 v[172:173], v[172:173], v[152:153]
	s_waitcnt vmcnt(16)
	v_pk_add_f32 v[170:171], v[170:171], v[158:159]
	v_pk_add_f32 v[172:173], v[172:173], v[156:157]
	s_waitcnt vmcnt(15)
	v_pk_add_f32 v[170:171], v[170:171], v[162:163]
	v_pk_add_f32 v[172:173], v[172:173], v[160:161]
	s_waitcnt vmcnt(14)
	v_pk_add_f32 v[170:171], v[170:171], v[138:139]
	v_pk_add_f32 v[172:173], v[172:173], v[136:137]
	s_waitcnt vmcnt(13)
	v_pk_add_f32 v[170:171], v[170:171], v[130:131]
	v_pk_add_f32 v[172:173], v[172:173], v[128:129]
	s_waitcnt vmcnt(12)
	v_pk_add_f32 v[170:171], v[170:171], v[126:127]
	v_pk_add_f32 v[172:173], v[172:173], v[124:125]
	s_waitcnt vmcnt(11)
	v_pk_add_f32 v[170:171], v[170:171], v[118:119]
	v_pk_add_f32 v[172:173], v[172:173], v[116:117]
	s_waitcnt vmcnt(10)
	v_pk_add_f32 v[170:171], v[170:171], v[134:135]
	v_pk_add_f32 v[172:173], v[172:173], v[132:133]
	s_waitcnt vmcnt(9)
	v_pk_add_f32 v[186:187], v[170:171], v[142:143]
	v_pk_add_f32 v[170:171], v[172:173], v[140:141]
	s_waitcnt vmcnt(8)
	v_pk_add_f32 v[102:103], v[186:187], v[102:103]
	v_pk_add_f32 v[100:101], v[170:171], v[100:101]
	s_waitcnt vmcnt(7)
	v_pk_add_f32 v[102:103], v[102:103], v[106:107]
	v_pk_add_f32 v[100:101], v[100:101], v[104:105]
	s_waitcnt vmcnt(6)
	v_pk_add_f32 v[102:103], v[102:103], v[110:111]
	v_pk_add_f32 v[100:101], v[100:101], v[108:109]
	global_load_dwordx4 v[144:147], v212, s[16:17] offset:1088
	s_waitcnt vmcnt(6)
	v_pk_add_f32 v[100:101], v[100:101], v[112:113]
	global_load_dwordx4 v[148:151], v212, s[16:17] offset:2112
	global_load_dwordx4 v[152:155], v212, s[16:17] offset:3136
	s_waitcnt vmcnt(7)
	v_pk_add_f32 v[100:101], v[100:101], v[120:121]
	global_load_dwordx4 v[136:139], v[220:221], off offset:1216
	v_pk_add_f32 v[92:93], v[92:93], v[100:101]
	global_load_dwordx4 v[156:159], v[216:217], off offset:64
	global_load_dwordx4 v[116:119], v[216:217], off offset:1088
	v_mul_f32_e32 v100, 0x3d372713, v92
	v_mul_f32_e32 v101, 0x3d372713, v93
	v_mul_f32_e32 v100, v92, v100
	v_mul_f32_e32 v101, v93, v101
	v_fma_f32 v100, v92, v100, v92
	v_fma_f32 v101, v93, v101, v93
	v_mul_f32_e32 v100, 0x3f4c422a, v100
	v_mul_f32_e32 v101, 0x3f4c422a, v101
	v_add_f32_e32 v100, v100, v100
	v_add_f32_e32 v101, v101, v101
	v_mul_f32_e32 v100, 0x3fb8aa3b, v100
	v_mul_f32_e32 v101, 0x3fb8aa3b, v101
	v_exp_f32_e32 v100, v100
	v_exp_f32_e32 v101, v101
	global_load_dwordx4 v[132:135], v[216:217], off offset:2112
	global_load_dwordx4 v[140:143], v[216:217], off offset:3136
	global_load_dwordx4 v[170:173], v[218:219], off offset:64
	v_pk_add_f32 v[120:121], v[100:101], 1.0 op_sel_hi:[1,0]
	v_pk_add_f32 v[100:101], v[102:103], v[114:115]
	v_div_scale_f32 v104, s[0:1], v121, v121, 2.0
	v_rcp_f32_e32 v105, v104
	v_pk_add_f32 v[100:101], v[100:101], v[122:123]
	v_div_scale_f32 v122, s[0:1], v120, v120, 2.0
	v_pk_add_f32 v[94:95], v[94:95], v[100:101]
	v_fma_f32 v100, -v104, v105, 1.0
	v_fmac_f32_e32 v105, v100, v105
	v_div_scale_f32 v100, vcc, 2.0, v121, 2.0
	v_mul_f32_e32 v106, v100, v105
	v_fma_f32 v101, -v104, v106, v100
	v_rcp_f32_e32 v123, v122
	v_fmac_f32_e32 v106, v101, v105
	v_fma_f32 v104, -v104, v106, v100
	global_load_dwordx4 v[100:103], v[220:221], off offset:64
	v_div_fmas_f32 v108, v104, v105, v106
	global_load_dwordx4 v[104:107], v[220:221], off offset:1088
	v_div_fixup_f32 v121, v108, v121, 2.0
	v_fma_f32 v112, -v122, v123, 1.0
	global_load_dwordx4 v[108:111], v[220:221], off offset:2112
	v_fmac_f32_e32 v123, v112, v123
	global_load_dwordx4 v[112:115], v[220:221], off offset:3136
	v_div_scale_f32 v165, vcc, 2.0, v120, 2.0
	v_mul_f32_e32 v186, v165, v123
	v_fma_f32 v187, -v122, v186, v165
	v_fmac_f32_e32 v186, v187, v123
	v_fma_f32 v122, -v122, v186, v165
	v_div_fmas_f32 v165, v122, v123, v186
	v_mul_f32_e32 v122, 0x3d372713, v94
	v_mul_f32_e32 v123, 0x3d372713, v95
	v_mul_f32_e32 v122, v94, v122
	v_mul_f32_e32 v123, v95, v123
	v_fma_f32 v122, v94, v122, v94
	v_fma_f32 v123, v95, v123, v95
	v_mul_f32_e32 v122, 0x3f4c422a, v122
	v_mul_f32_e32 v123, 0x3f4c422a, v123
	v_add_f32_e32 v122, v122, v122
	v_add_f32_e32 v123, v123, v123
	v_mul_f32_e32 v122, 0x3fb8aa3b, v122
	v_mul_f32_e32 v123, 0x3fb8aa3b, v123
	v_exp_f32_e32 v122, v122
	v_exp_f32_e32 v123, v123
	v_div_fixup_f32 v120, v165, v120, 2.0
	v_pk_add_f32 v[120:121], v[120:121], 1.0 op_sel_hi:[1,0] neg_lo:[1,0] neg_hi:[1,0]
	v_pk_mul_f32 v[92:93], v[92:93], 0.5 op_sel_hi:[1,0]
	v_pk_add_f32 v[122:123], v[122:123], 1.0 op_sel_hi:[1,0]
	v_pk_add_f32 v[120:121], v[120:121], 1.0 op_sel_hi:[1,0]
	v_div_scale_f32 v165, s[0:1], v123, v123, 2.0
	v_rcp_f32_e32 v186, v165
	v_pk_mul_f32 v[92:93], v[92:93], v[120:121]
	v_pk_mul_f32 v[94:95], v[94:95], 0.5 op_sel_hi:[1,0]
	v_cvt_pk_bf16_f32 v92, v92, v93
	v_fma_f32 v93, -v165, v186, 1.0
	v_fmac_f32_e32 v186, v93, v186
	v_div_scale_f32 v93, vcc, 2.0, v123, 2.0
	v_mul_f32_e32 v120, v93, v186
	v_fma_f32 v121, -v165, v120, v93
	v_fmac_f32_e32 v120, v121, v186
	v_fma_f32 v93, -v165, v120, v93
	v_div_scale_f32 v165, s[0:1], v122, v122, 2.0
	v_rcp_f32_e32 v187, v165
	v_div_fmas_f32 v93, v93, v186, v120
	v_div_fixup_f32 v121, v93, v123, 2.0
	s_waitcnt vmcnt(15)
; DI unsigned pack2(float a, float b) { v2f f = {a, b}; return __builtin_bit_cast(unsigned, __builtin_convertvector(f, v2bf)); }
;   DI u32x2 pack(int, int, float a, float b, float c, float d, float&) const { u32x2 v; v.x = pack2(a, b); v.y = pack2(c, d); return v; }
;   DI u32x2 pack(int m, int n, float a, float b, float c, float d, float& ss) const {
;     f32x4 bs = {0.f, 0.f, 0.f, 0.f};
; #pragma unroll
;     for (int kc = 0; kc < 16; ++kc) bs += *(const f32x4*)(bias_part + kc * 256 + n);
;     u32x2 v; v.x = pack2(gelu_tanh(a + bs[0]), gelu_tanh(b + bs[1])); v.y = pack2(gelu_tanh(c + bs[2]), gelu_tanh(d + bs[3]));
;     return v;
;   }
	v_pk_add_f32 v[96:97], v[96:97], 0 op_sel_hi:[1,0]
	v_fma_f32 v93, -v165, v187, 1.0
	v_fmac_f32_e32 v187, v93, v187
	v_div_scale_f32 v93, vcc, 2.0, v122, 2.0
	v_mul_f32_e32 v120, v93, v187
	v_fma_f32 v123, -v165, v120, v93
	v_fmac_f32_e32 v120, v123, v187
	v_fma_f32 v93, -v165, v120, v93
	v_div_fmas_f32 v93, v93, v187, v120
	v_div_fixup_f32 v120, v93, v122, 2.0
	v_pk_add_f32 v[120:121], v[120:121], 1.0 op_sel_hi:[1,0] neg_lo:[1,0] neg_hi:[1,0]
	s_waitcnt vmcnt(12)
	v_pk_add_f32 v[96:97], v[96:97], v[144:145]
	v_pk_add_f32 v[120:121], v[120:121], 1.0 op_sel_hi:[1,0]
	s_waitcnt vmcnt(11)
	v_pk_add_f32 v[96:97], v[96:97], v[148:149]
	v_pk_mul_f32 v[94:95], v[94:95], v[120:121]
	s_waitcnt vmcnt(10)
	v_pk_add_f32 v[120:121], v[96:97], v[152:153]
	v_cvt_pk_bf16_f32 v93, v94, v95
	v_pk_add_f32 v[94:95], v[98:99], 0 op_sel_hi:[1,0]
	global_load_dwordx4 v[96:99], v[220:221], off offset:128
	v_pk_add_f32 v[94:95], v[94:95], v[146:147]
	global_load_dwordx4 v[128:131], v[220:221], off offset:2240
	v_pk_add_f32 v[94:95], v[94:95], v[150:151]
	global_load_dwordx4 v[160:163], v[220:221], off offset:192
	v_pk_add_f32 v[94:95], v[94:95], v[154:155]
	global_load_dwordx4 v[124:127], v[220:221], off offset:3264
	s_waitcnt vmcnt(7)
	v_pk_add_f32 v[120:121], v[120:121], v[100:101]
	v_pk_add_f32 v[94:95], v[94:95], v[102:103]
	global_load_dwordx4 v[100:103], v[220:221], off offset:1152
	s_waitcnt vmcnt(7)
	v_pk_add_f32 v[120:121], v[120:121], v[104:105]
	v_pk_add_f32 v[94:95], v[94:95], v[106:107]
	s_waitcnt vmcnt(6)
	v_pk_add_f32 v[120:121], v[120:121], v[108:109]
	v_pk_add_f32 v[94:95], v[94:95], v[110:111]
	global_load_dwordx4 v[108:111], v[220:221], off offset:3200
	s_waitcnt vmcnt(6)
	v_pk_add_f32 v[112:113], v[120:121], v[112:113]
	v_pk_add_f32 v[94:95], v[94:95], v[114:115]
	v_pk_add_f32 v[112:113], v[112:113], v[156:157]
	v_pk_add_f32 v[94:95], v[94:95], v[158:159]
	v_pk_add_f32 v[112:113], v[112:113], v[116:117]
	v_pk_add_f32 v[94:95], v[94:95], v[118:119]
	v_pk_add_f32 v[112:113], v[112:113], v[132:133]
	v_pk_add_f32 v[94:95], v[94:95], v[134:135]
	v_pk_add_f32 v[112:113], v[112:113], v[140:141]
	v_pk_add_f32 v[94:95], v[94:95], v[142:143]
	v_pk_add_f32 v[112:113], v[112:113], v[170:171]
	v_pk_add_f32 v[94:95], v[94:95], v[172:173]
	v_pk_add_f32 v[112:113], v[112:113], v[174:175]
	global_load_dwordx4 v[170:173], v[218:219], off offset:2176
	v_pk_add_f32 v[112:113], v[112:113], v[178:179]
	v_pk_add_f32 v[94:95], v[94:95], v[176:177]
	v_pk_add_f32 v[112:113], v[112:113], v[182:183]
	global_load_dwordx4 v[116:119], v212, s[16:17] offset:2176
	v_pk_add_f32 v[178:179], v[88:89], v[112:113]
	global_load_dwordx4 v[120:123], v212, s[16:17] offset:3200
	v_mul_f32_e32 v88, 0x3d372713, v178
	v_mul_f32_e32 v89, 0x3d372713, v179
	v_mul_f32_e32 v88, v178, v88
	v_mul_f32_e32 v89, v179, v89
	v_fma_f32 v88, v178, v88, v178
	v_fma_f32 v89, v179, v89, v179
	v_mul_f32_e32 v88, 0x3f4c422a, v88
	v_mul_f32_e32 v89, 0x3f4c422a, v89
	v_add_f32_e32 v88, v88, v88
	v_add_f32_e32 v89, v89, v89
	v_mul_f32_e32 v88, 0x3fb8aa3b, v88
	v_mul_f32_e32 v89, 0x3fb8aa3b, v89
	v_exp_f32_e32 v88, v88
	v_exp_f32_e32 v89, v89
	global_load_dwordx4 v[104:107], v[220:221], off offset:2176
	global_load_dwordx4 v[174:177], v[218:219], off offset:3200
	v_pk_mul_f32 v[178:179], v[178:179], 0.5 op_sel_hi:[1,0]
	v_pk_add_f32 v[182:183], v[88:89], 1.0 op_sel_hi:[1,0]
	v_pk_add_f32 v[88:89], v[94:95], v[180:181]
	v_div_scale_f32 v112, s[0:1], v183, v183, 2.0
	v_rcp_f32_e32 v113, v112
	v_pk_add_f32 v[88:89], v[88:89], v[184:185]
	v_div_scale_f32 v132, s[0:1], v182, v182, 2.0
	v_pk_add_f32 v[180:181], v[90:91], v[88:89]
	v_fma_f32 v88, -v112, v113, 1.0
	v_fmac_f32_e32 v113, v88, v113
	v_div_scale_f32 v88, vcc, 2.0, v183, 2.0
	v_mul_f32_e32 v94, v88, v113
	v_fma_f32 v89, -v112, v94, v88
	v_rcp_f32_e32 v133, v132
	v_fmac_f32_e32 v94, v89, v113
	v_fma_f32 v95, -v112, v94, v88
	v_div_fmas_f32 v94, v95, v113, v94
	v_div_fixup_f32 v95, v94, v183, 2.0
	v_fma_f32 v94, -v132, v133, 1.0
	global_load_dwordx4 v[88:91], v212, s[16:17] offset:128
	v_fmac_f32_e32 v133, v94, v133
	v_div_scale_f32 v94, vcc, 2.0, v182, 2.0
	global_load_dwordx4 v[112:115], v212, s[16:17] offset:1152
	v_mul_f32_e32 v134, v94, v133
	v_fma_f32 v135, -v132, v134, v94
	v_fmac_f32_e32 v134, v135, v133
	v_fma_f32 v94, -v132, v134, v94
	v_mul_f32_e32 v132, 0x3d372713, v180
	v_mul_f32_e32 v132, v180, v132
	v_fma_f32 v140, v180, v132, v180
	v_mul_f32_e32 v140, 0x3f4c422a, v140
	v_div_fmas_f32 v94, v94, v133, v134
	global_load_dwordx4 v[132:135], v[216:217], off offset:128
	v_add_f32_e32 v144, v140, v140
	global_load_dwordx4 v[140:143], v[216:217], off offset:1152
	v_mul_f32_e32 v144, 0x3fb8aa3b, v144
	v_exp_f32_e32 v184, v144
	global_load_dwordx4 v[144:147], v[216:217], off offset:2176
	v_mul_f32_e32 v148, 0x3d372713, v181
	v_mul_f32_e32 v152, v181, v148
	global_load_dwordx4 v[148:151], v[216:217], off offset:3200
	v_fma_f32 v156, v181, v152, v181
	global_load_dwordx4 v[152:155], v[218:219], off offset:128
	v_mul_f32_e32 v165, 0x3f4c422a, v156
	global_load_dwordx4 v[156:159], v[218:219], off offset:1152
	v_add_f32_e32 v165, v165, v165
	v_mul_f32_e32 v165, 0x3fb8aa3b, v165
	v_exp_f32_e32 v185, v165
	v_div_fixup_f32 v94, v94, v182, 2.0
	v_pk_add_f32 v[94:95], v[94:95], 1.0 op_sel_hi:[1,0] neg_lo:[1,0] neg_hi:[1,0]
	v_pk_mul_f32 v[180:181], v[180:181], 0.5 op_sel_hi:[1,0]
	v_pk_add_f32 v[182:183], v[184:185], 1.0 op_sel_hi:[1,0]
	v_pk_add_f32 v[94:95], v[94:95], 1.0 op_sel_hi:[1,0]
	v_div_scale_f32 v165, s[0:1], v183, v183, 2.0
	v_rcp_f32_e32 v184, v165
	v_pk_mul_f32 v[94:95], v[178:179], v[94:95]
	s_nop 0
	v_cvt_pk_bf16_f32 v94, v94, v95
	v_fma_f32 v95, -v165, v184, 1.0
	v_fmac_f32_e32 v184, v95, v184
	v_div_scale_f32 v95, vcc, 2.0, v183, 2.0
	v_mul_f32_e32 v178, v95, v184
	v_fma_f32 v179, -v165, v178, v95
	v_fmac_f32_e32 v178, v179, v184
	v_fma_f32 v95, -v165, v178, v95
	v_div_scale_f32 v165, s[0:1], v182, v182, 2.0
	v_rcp_f32_e32 v185, v165
	v_div_fmas_f32 v95, v95, v184, v178
	v_div_fixup_f32 v179, v95, v183, 2.0
	v_permlane16_swap_b32_e32 v92, v94
	v_fma_f32 v95, -v165, v185, 1.0
	v_fmac_f32_e32 v185, v95, v185
	v_div_scale_f32 v95, vcc, 2.0, v182, 2.0
	v_mul_f32_e32 v178, v95, v185
	v_fma_f32 v183, -v165, v178, v95
	v_fmac_f32_e32 v178, v183, v185
	v_fma_f32 v95, -v165, v178, v95
	v_div_fmas_f32 v95, v95, v185, v178
	v_div_fixup_f32 v178, v95, v182, 2.0
	v_pk_add_f32 v[178:179], v[178:179], 1.0 op_sel_hi:[1,0] neg_lo:[1,0] neg_hi:[1,0]
	s_nop 0
	v_pk_add_f32 v[178:179], v[178:179], 1.0 op_sel_hi:[1,0]
	s_nop 0
	v_pk_mul_f32 v[178:179], v[180:181], v[178:179]
	s_nop 0
	v_cvt_pk_bf16_f32 v95, v178, v179
	global_load_dwordx4 v[178:181], v212, s[16:17] offset:192
	s_nop 0
	v_permlane16_swap_b32_e32 v93, v95
	s_waitcnt vmcnt(8)
; DI unsigned pack2(float a, float b) { v2f f = {a, b}; return __builtin_bit_cast(unsigned, __builtin_convertvector(f, v2bf)); }
;   DI u32x2 pack(int, int, float a, float b, float c, float d, float&) const { u32x2 v; v.x = pack2(a, b); v.y = pack2(c, d); return v; }
;   DI u32x2 pack(int m, int n, float a, float b, float c, float d, float& ss) const {
;     f32x4 bs = {0.f, 0.f, 0.f, 0.f};
; #pragma unroll
;     for (int kc = 0; kc < 16; ++kc) bs += *(const f32x4*)(bias_part + kc * 256 + n);
;     u32x2 v; v.x = pack2(gelu_tanh(a + bs[0]), gelu_tanh(b + bs[1])); v.y = pack2(gelu_tanh(c + bs[2]), gelu_tanh(d + bs[3]));
;     return v;
;   }
	v_pk_add_f32 v[184:185], v[88:89], 0 op_sel_hi:[1,0]
	v_pk_add_f32 v[182:183], v[90:91], 0 op_sel_hi:[1,0]
	global_load_dwordx4 v[88:91], v212, s[16:17] offset:1216
	s_waitcnt vmcnt(8)
	v_pk_add_f32 v[184:185], v[184:185], v[112:113]
	v_pk_add_f32 v[182:183], v[182:183], v[114:115]
	global_load_dwordx4 v[112:115], v212, s[16:17] offset:2240
	v_pk_add_f32 v[184:185], v[184:185], v[116:117]
	v_pk_add_f32 v[182:183], v[182:183], v[118:119]
	global_load_dwordx4 v[116:119], v212, s[16:17] offset:3264
	v_pk_add_f32 v[120:121], v[184:185], v[120:121]
	v_pk_add_f32 v[122:123], v[182:183], v[122:123]
	v_pk_add_f32 v[96:97], v[120:121], v[96:97]
	v_pk_add_f32 v[98:99], v[122:123], v[98:99]
	v_pk_add_f32 v[96:97], v[96:97], v[100:101]
	v_pk_add_f32 v[98:99], v[98:99], v[102:103]
	v_pk_add_f32 v[96:97], v[96:97], v[104:105]
	v_pk_add_f32 v[98:99], v[98:99], v[106:107]
	v_pk_add_f32 v[102:103], v[96:97], v[108:109]
	v_pk_add_f32 v[100:101], v[98:99], v[110:111]
	global_load_dwordx4 v[96:99], v[216:217], off offset:192
	s_waitcnt vmcnt(10)
	v_pk_add_f32 v[106:107], v[102:103], v[132:133]
	v_pk_add_f32 v[104:105], v[100:101], v[134:135]
	global_load_dwordx4 v[100:103], v[216:217], off offset:1216
	s_waitcnt vmcnt(10)
	v_pk_add_f32 v[110:111], v[106:107], v[140:141]
	v_pk_add_f32 v[108:109], v[104:105], v[142:143]
	global_load_dwordx4 v[104:107], v[216:217], off offset:2240
	s_waitcnt vmcnt(10)
	v_pk_add_f32 v[120:121], v[110:111], v[144:145]
	v_pk_add_f32 v[182:183], v[108:109], v[146:147]
	global_load_dwordx4 v[108:111], v[216:217], off offset:3264
	s_waitcnt vmcnt(10)
	v_pk_add_f32 v[132:133], v[120:121], v[148:149]
	global_load_dwordx4 v[120:123], v[218:219], off offset:192
	s_waitcnt vmcnt(10)
	v_pk_add_f32 v[140:141], v[132:133], v[152:153]
	global_load_dwordx4 v[132:135], v[218:219], off offset:1216
	s_waitcnt vmcnt(10)
	v_pk_add_f32 v[144:145], v[140:141], v[156:157]
	global_load_dwordx4 v[140:143], v[218:219], off offset:2240
	v_pk_add_f32 v[148:149], v[144:145], v[170:171]
	global_load_dwordx4 v[144:147], v[218:219], off offset:3264
	v_pk_add_f32 v[148:149], v[148:149], v[174:175]
	v_pk_add_f32 v[150:151], v[182:183], v[150:151]
	v_pk_add_f32 v[84:85], v[84:85], v[148:149]
	v_pk_add_f32 v[150:151], v[150:151], v[154:155]
	v_mul_f32_e32 v148, 0x3d372713, v84
	v_mul_f32_e32 v149, 0x3d372713, v85
	v_mul_f32_e32 v148, v84, v148
	v_mul_f32_e32 v149, v85, v149
	v_fma_f32 v148, v84, v148, v84
	v_fma_f32 v149, v85, v149, v85
	v_mul_f32_e32 v148, 0x3f4c422a, v148
	v_mul_f32_e32 v149, 0x3f4c422a, v149
	v_add_f32_e32 v148, v148, v148
	v_add_f32_e32 v149, v149, v149
	v_mul_f32_e32 v148, 0x3fb8aa3b, v148
	v_mul_f32_e32 v149, 0x3fb8aa3b, v149
	v_exp_f32_e32 v148, v148
	v_exp_f32_e32 v149, v149
	v_pk_add_f32 v[150:151], v[150:151], v[158:159]
	v_pk_mul_f32 v[84:85], v[84:85], 0.5 op_sel_hi:[1,0]
	v_pk_add_f32 v[150:151], v[150:151], v[172:173]
	v_pk_add_f32 v[148:149], v[148:149], 1.0 op_sel_hi:[1,0]
	v_pk_add_f32 v[150:151], v[150:151], v[176:177]
	v_div_scale_f32 v152, s[0:1], v149, v149, 2.0
	v_rcp_f32_e32 v153, v152
	v_pk_add_f32 v[86:87], v[86:87], v[150:151]
	v_fma_f32 v150, -v152, v153, 1.0
	v_fmac_f32_e32 v153, v150, v153
	v_div_scale_f32 v150, vcc, 2.0, v149, 2.0
	v_mul_f32_e32 v151, v150, v153
	v_fma_f32 v154, -v152, v151, v150
	v_fmac_f32_e32 v151, v154, v153
	v_fma_f32 v150, -v152, v151, v150
	v_div_scale_f32 v152, s[0:1], v148, v148, 2.0
	v_rcp_f32_e32 v154, v152
	v_div_fmas_f32 v150, v150, v153, v151
	v_div_fixup_f32 v149, v150, v149, 2.0
	v_fma_f32 v150, -v152, v154, 1.0
	v_fmac_f32_e32 v154, v150, v154
	v_div_scale_f32 v150, vcc, 2.0, v148, 2.0
	v_mul_f32_e32 v151, v150, v154
	v_fma_f32 v153, -v152, v151, v150
	v_fmac_f32_e32 v151, v153, v154
	v_fma_f32 v150, -v152, v151, v150
	v_div_fmas_f32 v152, v150, v154, v151
	v_mul_f32_e32 v150, 0x3d372713, v86
	v_mul_f32_e32 v151, 0x3d372713, v87
	v_mul_f32_e32 v150, v86, v150
	v_mul_f32_e32 v151, v87, v151
	v_fma_f32 v150, v86, v150, v86
	v_fma_f32 v151, v87, v151, v87
	v_mul_f32_e32 v150, 0x3f4c422a, v150
	v_mul_f32_e32 v151, 0x3f4c422a, v151
	v_add_f32_e32 v150, v150, v150
	v_add_f32_e32 v151, v151, v151
	v_mul_f32_e32 v150, 0x3fb8aa3b, v150
	v_mul_f32_e32 v151, 0x3fb8aa3b, v151
	v_exp_f32_e32 v150, v150
	v_exp_f32_e32 v151, v151
	v_div_fixup_f32 v148, v152, v148, 2.0
	v_pk_add_f32 v[148:149], v[148:149], 1.0 op_sel_hi:[1,0] neg_lo:[1,0] neg_hi:[1,0]
	v_pk_mul_f32 v[86:87], v[86:87], 0.5 op_sel_hi:[1,0]
	v_pk_add_f32 v[150:151], v[150:151], 1.0 op_sel_hi:[1,0]
	v_pk_add_f32 v[148:149], v[148:149], 1.0 op_sel_hi:[1,0]
	v_div_scale_f32 v152, s[0:1], v151, v151, 2.0
	v_rcp_f32_e32 v153, v152
	v_pk_mul_f32 v[84:85], v[84:85], v[148:149]
	s_nop 0
	v_cvt_pk_bf16_f32 v84, v84, v85
	v_fma_f32 v85, -v152, v153, 1.0
	v_fmac_f32_e32 v153, v85, v153
	v_div_scale_f32 v85, vcc, 2.0, v151, 2.0
	v_mul_f32_e32 v148, v85, v153
	v_fma_f32 v149, -v152, v148, v85
	v_fmac_f32_e32 v148, v149, v153
	v_fma_f32 v85, -v152, v148, v85
	v_div_scale_f32 v152, s[0:1], v150, v150, 2.0
	v_rcp_f32_e32 v154, v152
	v_div_fmas_f32 v85, v85, v153, v148
	v_div_fixup_f32 v149, v85, v151, 2.0
	v_fma_f32 v85, -v152, v154, 1.0
	v_fmac_f32_e32 v154, v85, v154
	v_div_scale_f32 v85, vcc, 2.0, v150, 2.0
	v_mul_f32_e32 v148, v85, v154
	v_fma_f32 v151, -v152, v148, v85
	v_fmac_f32_e32 v148, v151, v154
	v_fma_f32 v85, -v152, v148, v85
	v_div_fmas_f32 v85, v85, v154, v148
	v_div_fixup_f32 v148, v85, v150, 2.0
	v_pk_add_f32 v[148:149], v[148:149], 1.0 op_sel_hi:[1,0] neg_lo:[1,0] neg_hi:[1,0]
	s_nop 0
	v_pk_add_f32 v[148:149], v[148:149], 1.0 op_sel_hi:[1,0]
	s_nop 0
	v_pk_mul_f32 v[86:87], v[86:87], v[148:149]
	s_waitcnt vmcnt(11)
; DI unsigned pack2(float a, float b) { v2f f = {a, b}; return __builtin_bit_cast(unsigned, __builtin_convertvector(f, v2bf)); }
;   DI u32x2 pack(int, int, float a, float b, float c, float d, float&) const { u32x2 v; v.x = pack2(a, b); v.y = pack2(c, d); return v; }
; template <class ARow, class Epi>
; DI void gemm_tile(const ARow& arow, long a_kstride, const u16* __restrict__ Bt, long ldb, int K, int m0, int n0,
;                   const Epi& epi, char* smem) {
;     ...
;     for (int mi = 0; mi < 4; ++mi) {
;       const int m = m0 + wm * 64 + mi * 16 + fr;
;       float ss = 0.f;
;       u32x2 pk[4];
; #pragma unroll
;       for (int ni = 0; ni < 4; ++ni) pk[ni] = epi.pack(m, nh + ni * 16 + fq * 4, acc[ni][mi][0], acc[ni][mi][1], acc[ni][mi][2], acc[ni][mi][3], ss);
;       epi.finish16(m, nh, ss);
;       u16* rp = epi.rowp(m) + nh;
; #pragma unroll
;       for (int pp = 0; pp < 2; ++pp) {
;         u32x2 a = pk[2 * pp], b = pk[2 * pp + 1];
;         const u32x2 rx = __builtin_amdgcn_permlane16_swap(a.x, b.x, false, false);
;         const u32x2 ry = __builtin_amdgcn_permlane16_swap(a.y, b.y, false, false);
;         const int nst = (fq & 1) ? ((2 * pp + 1) * 16 + (fq - 1) * 4) : ((2 * pp) * 16 + fq * 4);
;         *(u32x4*)(rp + nst) = (u32x4){rx[0], ry[0], rx[1], ry[1]};
;       }
;   DI u32x2 pack(int m, int n, float a, float b, float c, float d, float& ss) const {
;     f32x4 bs = {0.f, 0.f, 0.f, 0.f};
; #pragma unroll
;     for (int kc = 0; kc < 16; ++kc) bs += *(const f32x4*)(bias_part + kc * 256 + n);
;     u32x2 v; v.x = pack2(gelu_tanh(a + bs[0]), gelu_tanh(b + bs[1])); v.y = pack2(gelu_tanh(c + bs[2]), gelu_tanh(d + bs[3]));
;     return v;
;   }
	v_pk_add_f32 v[148:149], v[178:179], 0 op_sel_hi:[1,0]
	v_cvt_pk_bf16_f32 v85, v86, v87
	s_waitcnt vmcnt(10)
	v_pk_add_f32 v[88:89], v[148:149], v[88:89]
	v_pk_add_f32 v[86:87], v[180:181], 0 op_sel_hi:[1,0]
	s_waitcnt vmcnt(9)
	v_pk_add_f32 v[88:89], v[88:89], v[112:113]
	v_pk_add_f32 v[86:87], v[86:87], v[90:91]
	s_waitcnt vmcnt(8)
	v_pk_add_f32 v[88:89], v[88:89], v[116:117]
	v_pk_add_f32 v[86:87], v[86:87], v[114:115]
	v_pk_add_f32 v[88:89], v[88:89], v[160:161]
	v_pk_add_f32 v[86:87], v[86:87], v[118:119]
	v_pk_add_f32 v[88:89], v[88:89], v[136:137]
	v_pk_add_f32 v[86:87], v[86:87], v[162:163]
	v_pk_add_f32 v[88:89], v[88:89], v[128:129]
	v_pk_add_f32 v[86:87], v[86:87], v[138:139]
	v_pk_add_f32 v[88:89], v[88:89], v[124:125]
	v_pk_add_f32 v[86:87], v[86:87], v[130:131]
	s_waitcnt vmcnt(7)
	v_pk_add_f32 v[88:89], v[88:89], v[96:97]
	v_pk_add_f32 v[86:87], v[86:87], v[126:127]
	s_waitcnt vmcnt(6)
	v_pk_add_f32 v[88:89], v[88:89], v[100:101]
	v_pk_add_f32 v[86:87], v[86:87], v[98:99]
	s_waitcnt vmcnt(5)
	v_pk_add_f32 v[88:89], v[88:89], v[104:105]
	v_pk_add_f32 v[86:87], v[86:87], v[102:103]
	s_waitcnt vmcnt(4)
	v_pk_add_f32 v[88:89], v[88:89], v[108:109]
	v_pk_add_f32 v[86:87], v[86:87], v[106:107]
	s_waitcnt vmcnt(3)
	v_pk_add_f32 v[88:89], v[88:89], v[120:121]
	v_pk_add_f32 v[86:87], v[86:87], v[110:111]
	s_waitcnt vmcnt(2)
	v_pk_add_f32 v[88:89], v[88:89], v[132:133]
	v_pk_add_f32 v[86:87], v[86:87], v[122:123]
	s_waitcnt vmcnt(1)
	v_pk_add_f32 v[88:89], v[88:89], v[140:141]
	v_pk_add_f32 v[86:87], v[86:87], v[134:135]
	s_waitcnt vmcnt(0)
	v_pk_add_f32 v[88:89], v[88:89], v[144:145]
	v_pk_add_f32 v[86:87], v[86:87], v[142:143]
	v_pk_add_f32 v[80:81], v[80:81], v[88:89]
	v_pk_add_f32 v[86:87], v[86:87], v[146:147]
	v_mul_f32_e32 v88, 0x3d372713, v80
	v_mul_f32_e32 v89, 0x3d372713, v81
	v_mul_f32_e32 v88, v80, v88
	v_mul_f32_e32 v89, v81, v89
	v_fma_f32 v88, v80, v88, v80
	v_fma_f32 v89, v81, v89, v81
	v_mul_f32_e32 v88, 0x3f4c422a, v88
	v_mul_f32_e32 v89, 0x3f4c422a, v89
	v_add_f32_e32 v88, v88, v88
	v_add_f32_e32 v89, v89, v89
	v_mul_f32_e32 v88, 0x3fb8aa3b, v88
	v_mul_f32_e32 v89, 0x3fb8aa3b, v89
	v_exp_f32_e32 v88, v88
	v_exp_f32_e32 v89, v89
	v_pk_add_f32 v[82:83], v[82:83], v[86:87]
	v_pk_mul_f32 v[80:81], v[80:81], 0.5 op_sel_hi:[1,0]
	v_mfma_f32_16x16x32_bf16 v[140:143], v[40:43], v[76:79], v[64:67]
	v_add_f32_e64 v88, v88, 1.0
	v_add_f32_e64 v89, v89, 1.0
	v_div_scale_f32 v90, s[0:1], v89, v89, 2.0
	v_rcp_f32_e32 v91, v90
	v_mfma_f32_16x16x32_bf16 v[64:67], v[28:31], v[72:75], v[60:63]
	v_fma_f32 v86, -v90, v91, 1.0
	v_fmac_f32_e32 v91, v86, v91
	v_div_scale_f32 v86, vcc, 2.0, v89, 2.0
	v_mul_f32_e32 v87, v86, v91
	v_fma_f32 v96, -v90, v87, v86
	v_fmac_f32_e32 v87, v96, v91
	v_fma_f32 v86, -v90, v87, v86
	v_div_scale_f32 v90, s[0:1], v88, v88, 2.0
	v_rcp_f32_e32 v96, v90
	v_div_fmas_f32 v86, v86, v91, v87
	v_div_fixup_f32 v87, v86, v89, 2.0
	v_mfma_f32_16x16x32_bf16 v[60:63], v[24:27], v[72:75], v[56:59]
	v_fma_f32 v86, -v90, v96, 1.0
	v_fmac_f32_e32 v96, v86, v96
	v_div_scale_f32 v86, vcc, 2.0, v88, 2.0
	v_mul_f32_e32 v89, v86, v96
	v_fma_f32 v91, -v90, v89, v86
	v_fmac_f32_e32 v89, v91, v96
	v_fma_f32 v86, -v90, v89, v86
	v_div_fmas_f32 v86, v86, v96, v89
	v_mul_f32_e32 v89, 0x3d372713, v82
	v_mul_f32_e32 v89, v82, v89
	v_fma_f32 v89, v82, v89, v82
	v_mul_f32_e32 v89, 0x3f4c422a, v89
	v_add_f32_e32 v89, v89, v89
	v_mul_f32_e32 v89, 0x3fb8aa3b, v89
	v_exp_f32_e32 v90, v89
	v_mul_f32_e32 v89, 0x3d372713, v83
	v_mul_f32_e32 v89, v83, v89
	v_fma_f32 v89, v83, v89, v83
	v_mul_f32_e32 v89, 0x3f4c422a, v89
	v_add_f32_e32 v89, v89, v89
	v_mul_f32_e32 v89, 0x3fb8aa3b, v89
	v_exp_f32_e32 v91, v89
	v_div_fixup_f32 v86, v86, v88, 2.0
	v_pk_add_f32 v[86:87], v[86:87], 1.0 op_sel_hi:[1,0] neg_lo:[1,0] neg_hi:[1,0]
	v_pk_mul_f32 v[82:83], v[82:83], 0.5 op_sel_hi:[1,0]
	v_pk_add_f32 v[88:89], v[90:91], 1.0 op_sel_hi:[1,0]
	v_pk_add_f32 v[86:87], v[86:87], 1.0 op_sel_hi:[1,0]
	v_div_scale_f32 v90, s[0:1], v89, v89, 2.0
	v_rcp_f32_e32 v91, v90
	v_pk_mul_f32 v[80:81], v[80:81], v[86:87]
	v_mfma_f32_16x16x32_bf16 v[56:59], v[20:23], v[72:75], v[140:143]
	v_cvt_pk_bf16_f32 v86, v80, v81
	v_fma_f32 v80, -v90, v91, 1.0
	v_fmac_f32_e32 v91, v80, v91
	v_div_scale_f32 v80, vcc, 2.0, v89, 2.0
	v_mul_f32_e32 v81, v80, v91
	v_fma_f32 v87, -v90, v81, v80
	v_fmac_f32_e32 v81, v87, v91
	v_div_scale_f32 v87, s[0:1], v88, v88, 2.0
	v_fma_f32 v80, -v90, v81, v80
	v_rcp_f32_e32 v90, v87
	v_div_fmas_f32 v80, v80, v91, v81
	v_div_fixup_f32 v81, v80, v89, 2.0
	v_permlane16_swap_b32_e32 v84, v86
	v_fma_f32 v80, -v87, v90, 1.0
	v_fmac_f32_e32 v90, v80, v90
	v_div_scale_f32 v80, vcc, 2.0, v88, 2.0
	v_mul_f32_e32 v89, v80, v90
	v_fma_f32 v91, -v87, v89, v80
	v_fmac_f32_e32 v89, v91, v90
	v_fma_f32 v80, -v87, v89, v80
	v_div_fmas_f32 v80, v80, v90, v89
	v_div_fixup_f32 v80, v80, v88, 2.0
	v_pk_add_f32 v[80:81], v[80:81], 1.0 op_sel_hi:[1,0] neg_lo:[1,0] neg_hi:[1,0]
	s_nop 0
	v_pk_add_f32 v[80:81], v[80:81], 1.0 op_sel_hi:[1,0]
	s_nop 0
	v_pk_mul_f32 v[80:81], v[82:83], v[80:81]
	s_nop 0
	v_cvt_pk_bf16_f32 v87, v80, v81
	v_or_b32_e32 v80, 16, v164
	v_ashrrev_i32_e32 v81, 31, v80
	v_lshlrev_b64 v[80:81], 9, v[80:81]
	v_lshl_add_u64 v[80:81], v[214:215], 0, v[80:81]
	v_lshl_add_u64 v[82:83], v[80:81], 0, v[166:167]
	v_permlane16_swap_b32_e32 v85, v87
	v_lshl_add_u64 v[80:81], v[80:81], 0, v[168:169]
	global_store_dwordx4 v[82:83], v[92:95], off
	global_store_dwordx4 v[80:81], v[84:87], off
	global_load_dwordx4 v[120:123], v212, s[16:17]
	global_load_dwordx4 v[124:127], v212, s[16:17] offset:1024
	global_load_dwordx4 v[128:131], v212, s[16:17] offset:2048
	global_load_dwordx4 v[132:135], v212, s[16:17] offset:3072
	global_load_dwordx4 v[136:139], v[216:217], off offset:-4096
	global_load_dwordx4 v[112:115], v[220:221], off offset:1024
	global_load_dwordx4 v[104:107], v[220:221], off offset:2048
	global_load_dwordx4 v[100:103], v[220:221], off offset:3072
	global_load_dwordx4 v[92:95], v[218:219], off offset:-4096
	global_load_dwordx4 v[108:111], v[216:217], off offset:1024
	global_load_dwordx4 v[116:119], v[216:217], off offset:2048
	global_load_dwordx4 v[76:79], v[216:217], off offset:3072
	global_load_dwordx4 v[80:83], v[218:219], off
	global_load_dwordx4 v[84:87], v[218:219], off offset:1024
	global_load_dwordx4 v[88:91], v[218:219], off offset:2048
	global_load_dwordx4 v[96:99], v[218:219], off offset:3072
	global_load_dwordx4 v[148:151], v[218:219], off offset:2112
	global_load_dwordx4 v[72:75], v212, s[16:17] offset:64
	global_load_dwordx4 v[152:155], v[218:219], off offset:3136
	global_load_dwordx4 v[144:147], v[218:219], off offset:1088
	s_waitcnt vmcnt(19)
; DI unsigned pack2(float a, float b) { v2f f = {a, b}; return __builtin_bit_cast(unsigned, __builtin_convertvector(f, v2bf)); }
;   DI u32x2 pack(int, int, float a, float b, float c, float d, float&) const { u32x2 v; v.x = pack2(a, b); v.y = pack2(c, d); return v; }
; template <class ARow, class Epi>
; DI void gemm_tile(const ARow& arow, long a_kstride, const u16* __restrict__ Bt, long ldb, int K, int m0, int n0,
;                   const Epi& epi, char* smem) {
;     ...
;     for (int mi = 0; mi < 4; ++mi) {
;       const int m = m0 + wm * 64 + mi * 16 + fr;
;       float ss = 0.f;
;       u32x2 pk[4];
; #pragma unroll
;       for (int ni = 0; ni < 4; ++ni) pk[ni] = epi.pack(m, nh + ni * 16 + fq * 4, acc[ni][mi][0], acc[ni][mi][1], acc[ni][mi][2], acc[ni][mi][3], ss);
;       epi.finish16(m, nh, ss);
;       u16* rp = epi.rowp(m) + nh;
; #pragma unroll
;       for (int pp = 0; pp < 2; ++pp) {
;         u32x2 a = pk[2 * pp], b = pk[2 * pp + 1];
;         const u32x2 rx = __builtin_amdgcn_permlane16_swap(a.x, b.x, false, false);
;         const u32x2 ry = __builtin_amdgcn_permlane16_swap(a.y, b.y, false, false);
;         const int nst = (fq & 1) ? ((2 * pp + 1) * 16 + (fq - 1) * 4) : ((2 * pp) * 16 + fq * 4);
;         *(u32x4*)(rp + nst) = (u32x4){rx[0], ry[0], rx[1], ry[1]};
;       }
;   DI u32x2 pack(int m, int n, float a, float b, float c, float d, float& ss) const {
;     f32x4 bs = {0.f, 0.f, 0.f, 0.f};
; #pragma unroll
;     for (int kc = 0; kc < 16; ++kc) bs += *(const f32x4*)(bias_part + kc * 256 + n);
;     u32x2 v; v.x = pack2(gelu_tanh(a + bs[0]), gelu_tanh(b + bs[1])); v.y = pack2(gelu_tanh(c + bs[2]), gelu_tanh(d + bs[3]));
;     return v;
;   }
	v_pk_add_f32 v[140:141], v[122:123], 0 op_sel_hi:[1,0]
	v_pk_add_f32 v[142:143], v[120:121], 0 op_sel_hi:[1,0]
	s_waitcnt vmcnt(18)
	v_pk_add_f32 v[140:141], v[140:141], v[126:127]
	v_pk_add_f32 v[142:143], v[142:143], v[124:125]
	s_waitcnt vmcnt(17)
	v_pk_add_f32 v[140:141], v[140:141], v[130:131]
	v_pk_add_f32 v[142:143], v[142:143], v[128:129]
	s_waitcnt vmcnt(16)
	v_pk_add_f32 v[140:141], v[140:141], v[134:135]
	v_pk_add_f32 v[142:143], v[142:143], v[132:133]
	s_waitcnt vmcnt(15)
	v_pk_add_f32 v[140:141], v[140:141], v[138:139]
	v_pk_add_f32 v[142:143], v[142:143], v[136:137]
	s_waitcnt vmcnt(14)
	v_pk_add_f32 v[140:141], v[140:141], v[114:115]
	v_pk_add_f32 v[142:143], v[142:143], v[112:113]
	s_waitcnt vmcnt(13)
	v_pk_add_f32 v[140:141], v[140:141], v[106:107]
	v_pk_add_f32 v[142:143], v[142:143], v[104:105]
	s_waitcnt vmcnt(12)
	v_pk_add_f32 v[140:141], v[140:141], v[102:103]
	v_pk_add_f32 v[142:143], v[142:143], v[100:101]
	s_waitcnt vmcnt(11)
	v_pk_add_f32 v[140:141], v[140:141], v[94:95]
	v_pk_add_f32 v[142:143], v[142:143], v[92:93]
	s_waitcnt vmcnt(10)
	v_pk_add_f32 v[140:141], v[140:141], v[110:111]
	v_pk_add_f32 v[142:143], v[142:143], v[108:109]
	s_waitcnt vmcnt(9)
	v_pk_add_f32 v[156:157], v[140:141], v[118:119]
	v_pk_add_f32 v[140:141], v[142:143], v[116:117]
	s_waitcnt vmcnt(8)
	v_pk_add_f32 v[78:79], v[156:157], v[78:79]
	v_pk_add_f32 v[76:77], v[140:141], v[76:77]
	s_waitcnt vmcnt(7)
	v_pk_add_f32 v[78:79], v[78:79], v[82:83]
	v_pk_add_f32 v[76:77], v[76:77], v[80:81]
	s_waitcnt vmcnt(6)
	v_pk_add_f32 v[78:79], v[78:79], v[86:87]
	v_pk_add_f32 v[76:77], v[76:77], v[84:85]
	global_load_dwordx4 v[120:123], v212, s[16:17] offset:1088
	s_waitcnt vmcnt(6)
	v_pk_add_f32 v[76:77], v[76:77], v[88:89]
	global_load_dwordx4 v[124:127], v212, s[16:17] offset:2112
	global_load_dwordx4 v[128:131], v212, s[16:17] offset:3136
	s_waitcnt vmcnt(7)
	v_pk_add_f32 v[76:77], v[76:77], v[96:97]
	global_load_dwordx4 v[112:115], v[220:221], off offset:1216
	v_pk_add_f32 v[68:69], v[68:69], v[76:77]
	global_load_dwordx4 v[132:135], v[216:217], off offset:64
	global_load_dwordx4 v[92:95], v[216:217], off offset:1088
	v_mul_f32_e32 v76, 0x3d372713, v68
	v_mul_f32_e32 v77, 0x3d372713, v69
	v_mul_f32_e32 v76, v68, v76
	v_mul_f32_e32 v77, v69, v77
	v_fma_f32 v76, v68, v76, v68
	v_fma_f32 v77, v69, v77, v69
	v_mul_f32_e32 v76, 0x3f4c422a, v76
	v_mul_f32_e32 v77, 0x3f4c422a, v77
	v_add_f32_e32 v76, v76, v76
	v_add_f32_e32 v77, v77, v77
	v_mul_f32_e32 v76, 0x3fb8aa3b, v76
	v_mul_f32_e32 v77, 0x3fb8aa3b, v77
	v_exp_f32_e32 v76, v76
	v_exp_f32_e32 v77, v77
	global_load_dwordx4 v[108:111], v[216:217], off offset:2112
	global_load_dwordx4 v[116:119], v[216:217], off offset:3136
	global_load_dwordx4 v[140:143], v[218:219], off offset:64
	v_pk_add_f32 v[96:97], v[76:77], 1.0 op_sel_hi:[1,0]
	v_pk_add_f32 v[76:77], v[78:79], v[90:91]
	v_div_scale_f32 v80, s[0:1], v97, v97, 2.0
	v_rcp_f32_e32 v81, v80
	v_pk_add_f32 v[76:77], v[76:77], v[98:99]
	v_div_scale_f32 v98, s[0:1], v96, v96, 2.0
	v_pk_add_f32 v[70:71], v[70:71], v[76:77]
	v_fma_f32 v76, -v80, v81, 1.0
	v_fmac_f32_e32 v81, v76, v81
	v_div_scale_f32 v76, vcc, 2.0, v97, 2.0
	v_mul_f32_e32 v82, v76, v81
	v_fma_f32 v77, -v80, v82, v76
	v_rcp_f32_e32 v99, v98
	v_fmac_f32_e32 v82, v77, v81
	v_fma_f32 v80, -v80, v82, v76
	global_load_dwordx4 v[76:79], v[220:221], off offset:64
	v_div_fmas_f32 v84, v80, v81, v82
	global_load_dwordx4 v[80:83], v[220:221], off offset:1088
	v_div_fixup_f32 v97, v84, v97, 2.0
	v_fma_f32 v88, -v98, v99, 1.0
	global_load_dwordx4 v[84:87], v[220:221], off offset:2112
	v_fmac_f32_e32 v99, v88, v99
	global_load_dwordx4 v[88:91], v[220:221], off offset:3136
	v_div_scale_f32 v156, vcc, 2.0, v96, 2.0
	v_mul_f32_e32 v157, v156, v99
	v_fma_f32 v158, -v98, v157, v156
	v_fmac_f32_e32 v157, v158, v99
	v_fma_f32 v98, -v98, v157, v156
	v_div_fmas_f32 v156, v98, v99, v157
	v_mul_f32_e32 v98, 0x3d372713, v70
	v_mul_f32_e32 v99, 0x3d372713, v71
	v_mul_f32_e32 v98, v70, v98
	v_mul_f32_e32 v99, v71, v99
	v_fma_f32 v98, v70, v98, v70
	v_fma_f32 v99, v71, v99, v71
	v_mul_f32_e32 v98, 0x3f4c422a, v98
	v_mul_f32_e32 v99, 0x3f4c422a, v99
	v_add_f32_e32 v98, v98, v98
	v_add_f32_e32 v99, v99, v99
	v_mul_f32_e32 v98, 0x3fb8aa3b, v98
	v_mul_f32_e32 v99, 0x3fb8aa3b, v99
	v_exp_f32_e32 v98, v98
	v_exp_f32_e32 v99, v99
	v_div_fixup_f32 v96, v156, v96, 2.0
	v_pk_add_f32 v[96:97], v[96:97], 1.0 op_sel_hi:[1,0] neg_lo:[1,0] neg_hi:[1,0]
	v_pk_mul_f32 v[68:69], v[68:69], 0.5 op_sel_hi:[1,0]
	v_pk_add_f32 v[98:99], v[98:99], 1.0 op_sel_hi:[1,0]
	v_pk_add_f32 v[96:97], v[96:97], 1.0 op_sel_hi:[1,0]
	v_div_scale_f32 v156, s[0:1], v99, v99, 2.0
	v_rcp_f32_e32 v157, v156
	v_pk_mul_f32 v[68:69], v[68:69], v[96:97]
	v_pk_mul_f32 v[70:71], v[70:71], 0.5 op_sel_hi:[1,0]
	v_cvt_pk_bf16_f32 v68, v68, v69
	v_fma_f32 v69, -v156, v157, 1.0
	v_fmac_f32_e32 v157, v69, v157
	v_div_scale_f32 v69, vcc, 2.0, v99, 2.0
	v_mul_f32_e32 v96, v69, v157
	v_fma_f32 v97, -v156, v96, v69
	v_fmac_f32_e32 v96, v97, v157
	v_fma_f32 v69, -v156, v96, v69
	v_div_scale_f32 v156, s[0:1], v98, v98, 2.0
	v_rcp_f32_e32 v158, v156
	v_div_fmas_f32 v69, v69, v157, v96
	v_div_fixup_f32 v97, v69, v99, 2.0
	s_waitcnt vmcnt(15)
	v_pk_add_f32 v[72:73], v[72:73], 0 op_sel_hi:[1,0]
	v_fma_f32 v69, -v156, v158, 1.0
	v_fmac_f32_e32 v158, v69, v158
	v_div_scale_f32 v69, vcc, 2.0, v98, 2.0
	v_mul_f32_e32 v96, v69, v158
	v_fma_f32 v99, -v156, v96, v69
	v_fmac_f32_e32 v96, v99, v158
	v_fma_f32 v69, -v156, v96, v69
	v_div_fmas_f32 v69, v69, v158, v96
	v_div_fixup_f32 v96, v69, v98, 2.0
	v_pk_add_f32 v[96:97], v[96:97], 1.0 op_sel_hi:[1,0] neg_lo:[1,0] neg_hi:[1,0]
	s_waitcnt vmcnt(12)
; DI unsigned pack2(float a, float b) { v2f f = {a, b}; return __builtin_bit_cast(unsigned, __builtin_convertvector(f, v2bf)); }
;   DI u32x2 pack(int, int, float a, float b, float c, float d, float&) const { u32x2 v; v.x = pack2(a, b); v.y = pack2(c, d); return v; }
; template <class ARow, class Epi>
; DI void gemm_tile(const ARow& arow, long a_kstride, const u16* __restrict__ Bt, long ldb, int K, int m0, int n0,
;                   const Epi& epi, char* smem) {
;     ...
;     for (int mi = 0; mi < 4; ++mi) {
;       const int m = m0 + wm * 64 + mi * 16 + fr;
;       float ss = 0.f;
;       u32x2 pk[4];
; #pragma unroll
;       for (int ni = 0; ni < 4; ++ni) pk[ni] = epi.pack(m, nh + ni * 16 + fq * 4, acc[ni][mi][0], acc[ni][mi][1], acc[ni][mi][2], acc[ni][mi][3], ss);
;       epi.finish16(m, nh, ss);
;       u16* rp = epi.rowp(m) + nh;
; #pragma unroll
;       for (int pp = 0; pp < 2; ++pp) {
;         u32x2 a = pk[2 * pp], b = pk[2 * pp + 1];
;         const u32x2 rx = __builtin_amdgcn_permlane16_swap(a.x, b.x, false, false);
;         const u32x2 ry = __builtin_amdgcn_permlane16_swap(a.y, b.y, false, false);
;         const int nst = (fq & 1) ? ((2 * pp + 1) * 16 + (fq - 1) * 4) : ((2 * pp) * 16 + fq * 4);
;         *(u32x4*)(rp + nst) = (u32x4){rx[0], ry[0], rx[1], ry[1]};
;       }
;   DI u32x2 pack(int m, int n, float a, float b, float c, float d, float& ss) const {
;     f32x4 bs = {0.f, 0.f, 0.f, 0.f};
; #pragma unroll
;     for (int kc = 0; kc < 16; ++kc) bs += *(const f32x4*)(bias_part + kc * 256 + n);
;     u32x2 v; v.x = pack2(gelu_tanh(a + bs[0]), gelu_tanh(b + bs[1])); v.y = pack2(gelu_tanh(c + bs[2]), gelu_tanh(d + bs[3]));
;     return v;
;   }
	v_pk_add_f32 v[72:73], v[72:73], v[120:121]
	v_pk_add_f32 v[96:97], v[96:97], 1.0 op_sel_hi:[1,0]
	s_waitcnt vmcnt(11)
	v_pk_add_f32 v[72:73], v[72:73], v[124:125]
	v_pk_mul_f32 v[70:71], v[70:71], v[96:97]
	s_waitcnt vmcnt(10)
	v_pk_add_f32 v[96:97], v[72:73], v[128:129]
	v_cvt_pk_bf16_f32 v69, v70, v71
	v_pk_add_f32 v[70:71], v[74:75], 0 op_sel_hi:[1,0]
	global_load_dwordx4 v[136:139], v[220:221], off offset:192
	global_load_dwordx4 v[72:75], v[220:221], off offset:128
	v_pk_add_f32 v[70:71], v[70:71], v[122:123]
	global_load_dwordx4 v[104:107], v[220:221], off offset:2240
	v_pk_add_f32 v[70:71], v[70:71], v[126:127]
	global_load_dwordx4 v[100:103], v[220:221], off offset:3264
	v_pk_add_f32 v[70:71], v[70:71], v[130:131]
	s_waitcnt vmcnt(7)
	v_pk_add_f32 v[96:97], v[96:97], v[76:77]
	v_pk_add_f32 v[70:71], v[70:71], v[78:79]
	global_load_dwordx4 v[76:79], v[220:221], off offset:1152
	s_waitcnt vmcnt(7)
	v_pk_add_f32 v[96:97], v[96:97], v[80:81]
	v_pk_add_f32 v[70:71], v[70:71], v[82:83]
	s_waitcnt vmcnt(6)
	v_pk_add_f32 v[96:97], v[96:97], v[84:85]
	v_pk_add_f32 v[70:71], v[70:71], v[86:87]
	global_load_dwordx4 v[84:87], v[220:221], off offset:3200
	s_waitcnt vmcnt(6)
	v_pk_add_f32 v[88:89], v[96:97], v[88:89]
	v_pk_add_f32 v[70:71], v[70:71], v[90:91]
	v_pk_add_f32 v[88:89], v[88:89], v[132:133]
	v_pk_add_f32 v[70:71], v[70:71], v[134:135]
	v_pk_add_f32 v[88:89], v[88:89], v[92:93]
	v_pk_add_f32 v[70:71], v[70:71], v[94:95]
	v_pk_add_f32 v[88:89], v[88:89], v[108:109]
	v_pk_add_f32 v[70:71], v[70:71], v[110:111]
	v_pk_add_f32 v[88:89], v[88:89], v[116:117]
	v_pk_add_f32 v[70:71], v[70:71], v[118:119]
	v_pk_add_f32 v[88:89], v[88:89], v[140:141]
	v_pk_add_f32 v[70:71], v[70:71], v[142:143]
	v_pk_add_f32 v[88:89], v[88:89], v[144:145]
	v_pk_add_f32 v[70:71], v[70:71], v[146:147]
	v_pk_add_f32 v[88:89], v[88:89], v[148:149]
	global_load_dwordx4 v[92:95], v212, s[16:17] offset:2176
	v_pk_add_f32 v[88:89], v[88:89], v[152:153]
	global_load_dwordx4 v[96:99], v212, s[16:17] offset:3200
	v_pk_add_f32 v[148:149], v[64:65], v[88:89]
	global_load_dwordx4 v[80:83], v[220:221], off offset:2176
	v_mul_f32_e32 v64, 0x3d372713, v148
	v_mul_f32_e32 v65, 0x3d372713, v149
	v_mul_f32_e32 v64, v148, v64
	v_mul_f32_e32 v65, v149, v65
	v_fma_f32 v64, v148, v64, v148
	v_fma_f32 v65, v149, v65, v149
	v_mul_f32_e32 v64, 0x3f4c422a, v64
	v_mul_f32_e32 v65, 0x3f4c422a, v65
	v_add_f32_e32 v64, v64, v64
	v_add_f32_e32 v65, v65, v65
	v_mul_f32_e32 v64, 0x3fb8aa3b, v64
	v_mul_f32_e32 v65, 0x3fb8aa3b, v65
	v_exp_f32_e32 v64, v64
	v_exp_f32_e32 v65, v65
	v_pk_mul_f32 v[148:149], v[148:149], 0.5 op_sel_hi:[1,0]
	v_pk_add_f32 v[152:153], v[64:65], 1.0 op_sel_hi:[1,0]
	s_nop 0
	v_div_scale_f32 v88, s[0:1], v153, v153, 2.0
	v_rcp_f32_e32 v89, v88
	v_pk_add_f32 v[64:65], v[70:71], v[150:151]
	v_div_scale_f32 v108, s[0:1], v152, v152, 2.0
	v_pk_add_f32 v[64:65], v[64:65], v[154:155]
	v_rcp_f32_e32 v109, v108
	v_pk_add_f32 v[150:151], v[66:67], v[64:65]
	v_fma_f32 v64, -v88, v89, 1.0
	v_fmac_f32_e32 v89, v64, v89
	v_div_scale_f32 v64, vcc, 2.0, v153, 2.0
	v_mul_f32_e32 v70, v64, v89
	v_fma_f32 v65, -v88, v70, v64
	v_fmac_f32_e32 v70, v65, v89
	v_fma_f32 v71, -v88, v70, v64
	v_div_fmas_f32 v70, v71, v89, v70
	v_div_fixup_f32 v71, v70, v153, 2.0
	v_fma_f32 v70, -v108, v109, 1.0
	global_load_dwordx4 v[64:67], v212, s[16:17] offset:128
	v_fmac_f32_e32 v109, v70, v109
	v_div_scale_f32 v70, vcc, 2.0, v152, 2.0
	global_load_dwordx4 v[88:91], v212, s[16:17] offset:1152
	v_mul_f32_e32 v110, v70, v109
	v_fma_f32 v111, -v108, v110, v70
	v_fmac_f32_e32 v110, v111, v109
	v_fma_f32 v70, -v108, v110, v70
	v_mul_f32_e32 v108, 0x3d372713, v150
	v_mul_f32_e32 v108, v150, v108
	v_fma_f32 v116, v150, v108, v150
	v_mul_f32_e32 v116, 0x3f4c422a, v116
	v_div_fmas_f32 v70, v70, v109, v110
	global_load_dwordx4 v[108:111], v[216:217], off offset:128
	v_add_f32_e32 v120, v116, v116
	global_load_dwordx4 v[116:119], v[216:217], off offset:1152
	v_mul_f32_e32 v120, 0x3fb8aa3b, v120
	v_exp_f32_e32 v154, v120
	global_load_dwordx4 v[120:123], v[216:217], off offset:2176
	v_mul_f32_e32 v124, 0x3d372713, v151
	v_mul_f32_e32 v128, v151, v124
	global_load_dwordx4 v[124:127], v[216:217], off offset:3200
	v_fma_f32 v132, v151, v128, v151
	global_load_dwordx4 v[128:131], v[218:219], off offset:128
	v_mul_f32_e32 v140, 0x3f4c422a, v132
	global_load_dwordx4 v[132:135], v[218:219], off offset:1152
	v_add_f32_e32 v144, v140, v140
	global_load_dwordx4 v[140:143], v[218:219], off offset:2176
	v_mul_f32_e32 v153, 0x3fb8aa3b, v144
	global_load_dwordx4 v[144:147], v[218:219], off offset:3200
	v_exp_f32_e32 v155, v153
	v_div_fixup_f32 v70, v70, v152, 2.0
	v_pk_add_f32 v[70:71], v[70:71], 1.0 op_sel_hi:[1,0] neg_lo:[1,0] neg_hi:[1,0]
	v_pk_mul_f32 v[150:151], v[150:151], 0.5 op_sel_hi:[1,0]
	v_pk_add_f32 v[152:153], v[154:155], 1.0 op_sel_hi:[1,0]
	v_pk_add_f32 v[70:71], v[70:71], 1.0 op_sel_hi:[1,0]
	v_div_scale_f32 v154, s[0:1], v153, v153, 2.0
	v_rcp_f32_e32 v155, v154
	v_pk_mul_f32 v[70:71], v[148:149], v[70:71]
	s_nop 0
	v_cvt_pk_bf16_f32 v70, v70, v71
	v_fma_f32 v71, -v154, v155, 1.0
	v_fmac_f32_e32 v155, v71, v155
	v_div_scale_f32 v71, vcc, 2.0, v153, 2.0
	v_mul_f32_e32 v148, v71, v155
	v_fma_f32 v149, -v154, v148, v71
	v_fmac_f32_e32 v148, v149, v155
	v_fma_f32 v71, -v154, v148, v71
	v_div_scale_f32 v154, s[0:1], v152, v152, 2.0
	v_rcp_f32_e32 v156, v154
	v_div_fmas_f32 v71, v71, v155, v148
	v_div_fixup_f32 v149, v71, v153, 2.0
	v_permlane16_swap_b32_e32 v68, v70
	v_fma_f32 v71, -v154, v156, 1.0
	v_fmac_f32_e32 v156, v71, v156
	v_div_scale_f32 v71, vcc, 2.0, v152, 2.0
	v_mul_f32_e32 v148, v71, v156
	v_fma_f32 v153, -v154, v148, v71
	v_fmac_f32_e32 v148, v153, v156
	v_fma_f32 v71, -v154, v148, v71
	v_div_fmas_f32 v71, v71, v156, v148
	v_div_fixup_f32 v148, v71, v152, 2.0
	v_pk_add_f32 v[148:149], v[148:149], 1.0 op_sel_hi:[1,0] neg_lo:[1,0] neg_hi:[1,0]
	s_nop 0
	v_pk_add_f32 v[148:149], v[148:149], 1.0 op_sel_hi:[1,0]
	s_nop 0
	v_pk_mul_f32 v[148:149], v[150:151], v[148:149]
	s_nop 0
	v_cvt_pk_bf16_f32 v71, v148, v149
	global_load_dwordx4 v[148:151], v212, s[16:17] offset:192
	s_nop 0
	v_permlane16_swap_b32_e32 v69, v71
	s_waitcnt vmcnt(10)
; DI unsigned pack2(float a, float b) { v2f f = {a, b}; return __builtin_bit_cast(unsigned, __builtin_convertvector(f, v2bf)); }
;   DI u32x2 pack(int, int, float a, float b, float c, float d, float&) const { u32x2 v; v.x = pack2(a, b); v.y = pack2(c, d); return v; }
; template <class ARow, class Epi>
; DI void gemm_tile(const ARow& arow, long a_kstride, const u16* __restrict__ Bt, long ldb, int K, int m0, int n0,
;                   const Epi& epi, char* smem) {
;     ...
;     for (int mi = 0; mi < 4; ++mi) {
;       const int m = m0 + wm * 64 + mi * 16 + fr;
;       float ss = 0.f;
;       u32x2 pk[4];
; #pragma unroll
;       for (int ni = 0; ni < 4; ++ni) pk[ni] = epi.pack(m, nh + ni * 16 + fq * 4, acc[ni][mi][0], acc[ni][mi][1], acc[ni][mi][2], acc[ni][mi][3], ss);
;       epi.finish16(m, nh, ss);
;       u16* rp = epi.rowp(m) + nh;
; #pragma unroll
;       for (int pp = 0; pp < 2; ++pp) {
;         u32x2 a = pk[2 * pp], b = pk[2 * pp + 1];
;         const u32x2 rx = __builtin_amdgcn_permlane16_swap(a.x, b.x, false, false);
;         const u32x2 ry = __builtin_amdgcn_permlane16_swap(a.y, b.y, false, false);
;         const int nst = (fq & 1) ? ((2 * pp + 1) * 16 + (fq - 1) * 4) : ((2 * pp) * 16 + fq * 4);
;         *(u32x4*)(rp + nst) = (u32x4){rx[0], ry[0], rx[1], ry[1]};
;       }
;   DI u32x2 pack(int m, int n, float a, float b, float c, float d, float& ss) const {
;     f32x4 bs = {0.f, 0.f, 0.f, 0.f};
; #pragma unroll
;     for (int kc = 0; kc < 16; ++kc) bs += *(const f32x4*)(bias_part + kc * 256 + n);
;     u32x2 v; v.x = pack2(gelu_tanh(a + bs[0]), gelu_tanh(b + bs[1])); v.y = pack2(gelu_tanh(c + bs[2]), gelu_tanh(d + bs[3]));
;     return v;
;   }
	v_pk_add_f32 v[154:155], v[64:65], 0 op_sel_hi:[1,0]
	v_pk_add_f32 v[152:153], v[66:67], 0 op_sel_hi:[1,0]
	global_load_dwordx4 v[64:67], v212, s[16:17] offset:1216
	s_waitcnt vmcnt(10)
	v_pk_add_f32 v[154:155], v[154:155], v[88:89]
	v_pk_add_f32 v[152:153], v[152:153], v[90:91]
	global_load_dwordx4 v[88:91], v212, s[16:17] offset:2240
	v_pk_add_f32 v[154:155], v[154:155], v[92:93]
	v_pk_add_f32 v[152:153], v[152:153], v[94:95]
	global_load_dwordx4 v[92:95], v212, s[16:17] offset:3264
	v_pk_add_f32 v[96:97], v[154:155], v[96:97]
	v_pk_add_f32 v[98:99], v[152:153], v[98:99]
	v_pk_add_f32 v[72:73], v[96:97], v[72:73]
	v_pk_add_f32 v[74:75], v[98:99], v[74:75]
	v_pk_add_f32 v[72:73], v[72:73], v[76:77]
	v_pk_add_f32 v[74:75], v[74:75], v[78:79]
	v_pk_add_f32 v[72:73], v[72:73], v[80:81]
	v_pk_add_f32 v[74:75], v[74:75], v[82:83]
	v_pk_add_f32 v[78:79], v[72:73], v[84:85]
	v_pk_add_f32 v[76:77], v[74:75], v[86:87]
	global_load_dwordx4 v[72:75], v[216:217], off offset:192
	s_waitcnt vmcnt(12)
	v_pk_add_f32 v[82:83], v[78:79], v[108:109]
	v_pk_add_f32 v[80:81], v[76:77], v[110:111]
	global_load_dwordx4 v[76:79], v[216:217], off offset:1216
	s_waitcnt vmcnt(12)
	v_pk_add_f32 v[86:87], v[82:83], v[116:117]
	v_pk_add_f32 v[84:85], v[80:81], v[118:119]
	global_load_dwordx4 v[80:83], v[216:217], off offset:2240
	s_waitcnt vmcnt(12)
	v_pk_add_f32 v[96:97], v[86:87], v[120:121]
	v_pk_add_f32 v[152:153], v[84:85], v[122:123]
	global_load_dwordx4 v[84:87], v[216:217], off offset:3264
	s_waitcnt vmcnt(12)
	v_pk_add_f32 v[108:109], v[96:97], v[124:125]
	global_load_dwordx4 v[96:99], v[218:219], off offset:192
	s_waitcnt vmcnt(12)
	v_pk_add_f32 v[116:117], v[108:109], v[128:129]
	global_load_dwordx4 v[108:111], v[218:219], off offset:1216
	s_waitcnt vmcnt(12)
	v_pk_add_f32 v[120:121], v[116:117], v[132:133]
	global_load_dwordx4 v[116:119], v[218:219], off offset:2240
	s_waitcnt vmcnt(12)
	v_pk_add_f32 v[124:125], v[120:121], v[140:141]
	global_load_dwordx4 v[120:123], v[218:219], off offset:3264
	s_waitcnt vmcnt(12)
	v_pk_add_f32 v[124:125], v[124:125], v[144:145]
	v_pk_add_f32 v[126:127], v[152:153], v[126:127]
	v_pk_add_f32 v[60:61], v[60:61], v[124:125]
	v_pk_add_f32 v[126:127], v[126:127], v[130:131]
	v_mul_f32_e32 v124, 0x3d372713, v60
	v_mul_f32_e32 v125, 0x3d372713, v61
	v_mul_f32_e32 v124, v60, v124
	v_mul_f32_e32 v125, v61, v125
	v_fma_f32 v124, v60, v124, v60
	v_fma_f32 v125, v61, v125, v61
	v_mul_f32_e32 v124, 0x3f4c422a, v124
	v_mul_f32_e32 v125, 0x3f4c422a, v125
	v_add_f32_e32 v124, v124, v124
	v_add_f32_e32 v125, v125, v125
	v_mul_f32_e32 v124, 0x3fb8aa3b, v124
	v_mul_f32_e32 v125, 0x3fb8aa3b, v125
	v_exp_f32_e32 v124, v124
	v_exp_f32_e32 v125, v125
	v_pk_add_f32 v[126:127], v[126:127], v[134:135]
	v_pk_mul_f32 v[60:61], v[60:61], 0.5 op_sel_hi:[1,0]
	v_pk_add_f32 v[126:127], v[126:127], v[142:143]
	v_pk_add_f32 v[124:125], v[124:125], 1.0 op_sel_hi:[1,0]
	v_pk_add_f32 v[126:127], v[126:127], v[146:147]
	v_div_scale_f32 v128, s[0:1], v125, v125, 2.0
	v_rcp_f32_e32 v129, v128
	v_pk_add_f32 v[62:63], v[62:63], v[126:127]
	v_fma_f32 v126, -v128, v129, 1.0
	v_fmac_f32_e32 v129, v126, v129
	v_div_scale_f32 v126, vcc, 2.0, v125, 2.0
	v_mul_f32_e32 v127, v126, v129
	v_fma_f32 v130, -v128, v127, v126
	v_fmac_f32_e32 v127, v130, v129
	v_fma_f32 v126, -v128, v127, v126
	v_div_scale_f32 v128, s[0:1], v124, v124, 2.0
	v_rcp_f32_e32 v130, v128
	v_div_fmas_f32 v126, v126, v129, v127
	v_div_fixup_f32 v125, v126, v125, 2.0
	v_fma_f32 v126, -v128, v130, 1.0
	v_fmac_f32_e32 v130, v126, v130
	v_div_scale_f32 v126, vcc, 2.0, v124, 2.0
	v_mul_f32_e32 v127, v126, v130
	v_fma_f32 v129, -v128, v127, v126
	v_fmac_f32_e32 v127, v129, v130
	v_fma_f32 v126, -v128, v127, v126
	v_div_fmas_f32 v128, v126, v130, v127
	v_mul_f32_e32 v126, 0x3d372713, v62
	v_mul_f32_e32 v127, 0x3d372713, v63
	v_mul_f32_e32 v126, v62, v126
	v_mul_f32_e32 v127, v63, v127
	v_fma_f32 v126, v62, v126, v62
	v_fma_f32 v127, v63, v127, v63
	v_mul_f32_e32 v126, 0x3f4c422a, v126
	v_mul_f32_e32 v127, 0x3f4c422a, v127
	v_add_f32_e32 v126, v126, v126
	v_add_f32_e32 v127, v127, v127
	v_mul_f32_e32 v126, 0x3fb8aa3b, v126
	v_mul_f32_e32 v127, 0x3fb8aa3b, v127
	v_exp_f32_e32 v126, v126
	v_exp_f32_e32 v127, v127
	v_div_fixup_f32 v124, v128, v124, 2.0
	v_pk_add_f32 v[124:125], v[124:125], 1.0 op_sel_hi:[1,0] neg_lo:[1,0] neg_hi:[1,0]
	v_pk_mul_f32 v[62:63], v[62:63], 0.5 op_sel_hi:[1,0]
	v_pk_add_f32 v[126:127], v[126:127], 1.0 op_sel_hi:[1,0]
	v_pk_add_f32 v[124:125], v[124:125], 1.0 op_sel_hi:[1,0]
	v_div_scale_f32 v128, s[0:1], v127, v127, 2.0
	v_rcp_f32_e32 v129, v128
	v_pk_mul_f32 v[60:61], v[60:61], v[124:125]
	s_nop 0
	v_cvt_pk_bf16_f32 v60, v60, v61
	v_fma_f32 v61, -v128, v129, 1.0
	v_fmac_f32_e32 v129, v61, v129
	v_div_scale_f32 v61, vcc, 2.0, v127, 2.0
	v_mul_f32_e32 v124, v61, v129
	v_fma_f32 v125, -v128, v124, v61
	v_fmac_f32_e32 v124, v125, v129
	v_fma_f32 v61, -v128, v124, v61
	v_div_scale_f32 v128, s[0:1], v126, v126, 2.0
	v_rcp_f32_e32 v130, v128
	v_div_fmas_f32 v61, v61, v129, v124
	v_div_fixup_f32 v125, v61, v127, 2.0
	v_fma_f32 v61, -v128, v130, 1.0
	v_fmac_f32_e32 v130, v61, v130
	v_div_scale_f32 v61, vcc, 2.0, v126, 2.0
	v_mul_f32_e32 v124, v61, v130
	v_fma_f32 v127, -v128, v124, v61
	v_fmac_f32_e32 v124, v127, v130
	v_fma_f32 v61, -v128, v124, v61
	v_div_fmas_f32 v61, v61, v130, v124
	v_div_fixup_f32 v124, v61, v126, 2.0
	v_pk_add_f32 v[124:125], v[124:125], 1.0 op_sel_hi:[1,0] neg_lo:[1,0] neg_hi:[1,0]
	s_nop 0
	v_pk_add_f32 v[124:125], v[124:125], 1.0 op_sel_hi:[1,0]
	s_nop 0
	v_pk_mul_f32 v[62:63], v[62:63], v[124:125]
	s_waitcnt vmcnt(11)
; DI unsigned pack2(float a, float b) { v2f f = {a, b}; return __builtin_bit_cast(unsigned, __builtin_convertvector(f, v2bf)); }
;   DI u32x2 pack(int, int, float a, float b, float c, float d, float&) const { u32x2 v; v.x = pack2(a, b); v.y = pack2(c, d); return v; }
; template <class ARow, class Epi>
; DI void gemm_tile(const ARow& arow, long a_kstride, const u16* __restrict__ Bt, long ldb, int K, int m0, int n0,
;                   const Epi& epi, char* smem) {
;     ...
;     for (int mi = 0; mi < 4; ++mi) {
;       const int m = m0 + wm * 64 + mi * 16 + fr;
;       float ss = 0.f;
;       u32x2 pk[4];
; #pragma unroll
;       for (int ni = 0; ni < 4; ++ni) pk[ni] = epi.pack(m, nh + ni * 16 + fq * 4, acc[ni][mi][0], acc[ni][mi][1], acc[ni][mi][2], acc[ni][mi][3], ss);
;       epi.finish16(m, nh, ss);
;       u16* rp = epi.rowp(m) + nh;
; #pragma unroll
;       for (int pp = 0; pp < 2; ++pp) {
;         u32x2 a = pk[2 * pp], b = pk[2 * pp + 1];
;         const u32x2 rx = __builtin_amdgcn_permlane16_swap(a.x, b.x, false, false);
;         const u32x2 ry = __builtin_amdgcn_permlane16_swap(a.y, b.y, false, false);
;         const int nst = (fq & 1) ? ((2 * pp + 1) * 16 + (fq - 1) * 4) : ((2 * pp) * 16 + fq * 4);
;         *(u32x4*)(rp + nst) = (u32x4){rx[0], ry[0], rx[1], ry[1]};
;       }
;   DI u32x2 pack(int m, int n, float a, float b, float c, float d, float& ss) const {
;     f32x4 bs = {0.f, 0.f, 0.f, 0.f};
; #pragma unroll
;     for (int kc = 0; kc < 16; ++kc) bs += *(const f32x4*)(bias_part + kc * 256 + n);
;     u32x2 v; v.x = pack2(gelu_tanh(a + bs[0]), gelu_tanh(b + bs[1])); v.y = pack2(gelu_tanh(c + bs[2]), gelu_tanh(d + bs[3]));
;     return v;
;   }
	v_pk_add_f32 v[124:125], v[148:149], 0 op_sel_hi:[1,0]
	v_cvt_pk_bf16_f32 v61, v62, v63
	s_waitcnt vmcnt(10)
	v_pk_add_f32 v[64:65], v[124:125], v[64:65]
	v_pk_add_f32 v[62:63], v[150:151], 0 op_sel_hi:[1,0]
	s_waitcnt vmcnt(9)
	v_pk_add_f32 v[64:65], v[64:65], v[88:89]
	v_pk_add_f32 v[62:63], v[62:63], v[66:67]
	s_waitcnt vmcnt(8)
	v_pk_add_f32 v[64:65], v[64:65], v[92:93]
	v_pk_add_f32 v[62:63], v[62:63], v[90:91]
	v_pk_add_f32 v[64:65], v[64:65], v[136:137]
	v_pk_add_f32 v[62:63], v[62:63], v[94:95]
	v_pk_add_f32 v[64:65], v[64:65], v[112:113]
	v_pk_add_f32 v[62:63], v[62:63], v[138:139]
	v_pk_add_f32 v[64:65], v[64:65], v[104:105]
	v_pk_add_f32 v[62:63], v[62:63], v[114:115]
	v_pk_add_f32 v[64:65], v[64:65], v[100:101]
	v_pk_add_f32 v[62:63], v[62:63], v[106:107]
	s_waitcnt vmcnt(7)
	v_pk_add_f32 v[64:65], v[64:65], v[72:73]
	v_pk_add_f32 v[62:63], v[62:63], v[102:103]
	s_waitcnt vmcnt(6)
	v_pk_add_f32 v[64:65], v[64:65], v[76:77]
	v_pk_add_f32 v[62:63], v[62:63], v[74:75]
	s_waitcnt vmcnt(5)
	v_pk_add_f32 v[64:65], v[64:65], v[80:81]
	v_pk_add_f32 v[62:63], v[62:63], v[78:79]
	s_waitcnt vmcnt(4)
	v_pk_add_f32 v[64:65], v[64:65], v[84:85]
	v_pk_add_f32 v[62:63], v[62:63], v[82:83]
	s_waitcnt vmcnt(3)
	v_pk_add_f32 v[64:65], v[64:65], v[96:97]
	v_pk_add_f32 v[62:63], v[62:63], v[86:87]
	s_waitcnt vmcnt(2)
	v_pk_add_f32 v[64:65], v[64:65], v[108:109]
	v_pk_add_f32 v[62:63], v[62:63], v[98:99]
	s_waitcnt vmcnt(1)
	v_pk_add_f32 v[64:65], v[64:65], v[116:117]
	v_pk_add_f32 v[62:63], v[62:63], v[110:111]
	s_waitcnt vmcnt(0)
	v_pk_add_f32 v[64:65], v[64:65], v[120:121]
	v_pk_add_f32 v[62:63], v[62:63], v[118:119]
	v_pk_add_f32 v[56:57], v[56:57], v[64:65]
	v_pk_add_f32 v[62:63], v[62:63], v[122:123]
	v_mul_f32_e32 v64, 0x3d372713, v56
	v_mul_f32_e32 v65, 0x3d372713, v57
	v_mul_f32_e32 v64, v56, v64
	v_mul_f32_e32 v65, v57, v65
	v_fma_f32 v64, v56, v64, v56
	v_fma_f32 v65, v57, v65, v57
	v_mul_f32_e32 v64, 0x3f4c422a, v64
	v_mul_f32_e32 v65, 0x3f4c422a, v65
	v_add_f32_e32 v64, v64, v64
	v_add_f32_e32 v65, v65, v65
	v_mul_f32_e32 v64, 0x3fb8aa3b, v64
	v_mul_f32_e32 v65, 0x3fb8aa3b, v65
	v_exp_f32_e32 v64, v64
	v_exp_f32_e32 v65, v65
	v_pk_add_f32 v[58:59], v[58:59], v[62:63]
	v_pk_mul_f32 v[56:57], v[56:57], 0.5 op_sel_hi:[1,0]
	v_mfma_f32_16x16x32_bf16 v[90:93], v[40:43], v[36:39], v[8:11]
	v_add_f32_e64 v64, v64, 1.0
	v_add_f32_e64 v65, v65, 1.0
	v_div_scale_f32 v66, s[0:1], v65, v65, 2.0
	v_rcp_f32_e32 v67, v66
	v_mfma_f32_16x16x32_bf16 v[8:11], v[28:31], v[16:19], v[4:7]
	v_fma_f32 v62, -v66, v67, 1.0
	v_fmac_f32_e32 v67, v62, v67
	v_div_scale_f32 v62, vcc, 2.0, v65, 2.0
	v_mul_f32_e32 v63, v62, v67
	v_fma_f32 v72, -v66, v63, v62
	v_fmac_f32_e32 v63, v72, v67
	v_fma_f32 v62, -v66, v63, v62
	v_div_scale_f32 v66, s[0:1], v64, v64, 2.0
	v_rcp_f32_e32 v72, v66
	v_div_fmas_f32 v62, v62, v67, v63
	v_div_fixup_f32 v63, v62, v65, 2.0
	v_mfma_f32_16x16x32_bf16 v[4:7], v[24:27], v[16:19], v[0:3]
	v_fma_f32 v62, -v66, v72, 1.0
	v_fmac_f32_e32 v72, v62, v72
	v_div_scale_f32 v62, vcc, 2.0, v64, 2.0
	v_mul_f32_e32 v65, v62, v72
	v_fma_f32 v67, -v66, v65, v62
	v_fmac_f32_e32 v65, v67, v72
	v_fma_f32 v62, -v66, v65, v62
	v_div_fmas_f32 v62, v62, v72, v65
	v_mul_f32_e32 v65, 0x3d372713, v58
	v_mul_f32_e32 v65, v58, v65
	v_fma_f32 v65, v58, v65, v58
	v_mul_f32_e32 v65, 0x3f4c422a, v65
	v_add_f32_e32 v65, v65, v65
	v_mul_f32_e32 v65, 0x3fb8aa3b, v65
	v_exp_f32_e32 v66, v65
	v_mul_f32_e32 v65, 0x3d372713, v59
	v_mul_f32_e32 v65, v59, v65
	v_fma_f32 v65, v59, v65, v59
	v_mul_f32_e32 v65, 0x3f4c422a, v65
	v_add_f32_e32 v65, v65, v65
	v_mul_f32_e32 v65, 0x3fb8aa3b, v65
	v_exp_f32_e32 v67, v65
	v_div_fixup_f32 v62, v62, v64, 2.0
	v_pk_add_f32 v[62:63], v[62:63], 1.0 op_sel_hi:[1,0] neg_lo:[1,0] neg_hi:[1,0]
	v_pk_mul_f32 v[58:59], v[58:59], 0.5 op_sel_hi:[1,0]
	v_pk_add_f32 v[64:65], v[66:67], 1.0 op_sel_hi:[1,0]
	v_pk_add_f32 v[62:63], v[62:63], 1.0 op_sel_hi:[1,0]
	v_div_scale_f32 v66, s[0:1], v65, v65, 2.0
	v_rcp_f32_e32 v67, v66
	v_pk_mul_f32 v[56:57], v[56:57], v[62:63]
	v_mfma_f32_16x16x32_bf16 v[0:3], v[20:23], v[16:19], v[90:93]
	v_cvt_pk_bf16_f32 v62, v56, v57
	v_fma_f32 v56, -v66, v67, 1.0
	v_fmac_f32_e32 v67, v56, v67
	v_div_scale_f32 v56, vcc, 2.0, v65, 2.0
	v_mul_f32_e32 v57, v56, v67
	v_fma_f32 v63, -v66, v57, v56
	v_fmac_f32_e32 v57, v63, v67
	v_div_scale_f32 v63, s[0:1], v64, v64, 2.0
	v_fma_f32 v56, -v66, v57, v56
	v_rcp_f32_e32 v66, v63
	v_div_fmas_f32 v56, v56, v67, v57
	v_div_fixup_f32 v57, v56, v65, 2.0
	v_permlane16_swap_b32_e32 v60, v62
	v_fma_f32 v56, -v63, v66, 1.0
	v_fmac_f32_e32 v66, v56, v66
	v_div_scale_f32 v56, vcc, 2.0, v64, 2.0
	v_mul_f32_e32 v65, v56, v66
	v_fma_f32 v67, -v63, v65, v56
	v_fmac_f32_e32 v65, v67, v66
	v_fma_f32 v56, -v63, v65, v56
	v_div_fmas_f32 v56, v56, v66, v65
	v_div_fixup_f32 v56, v56, v64, 2.0
	v_pk_add_f32 v[56:57], v[56:57], 1.0 op_sel_hi:[1,0] neg_lo:[1,0] neg_hi:[1,0]
	s_nop 0
	v_pk_add_f32 v[56:57], v[56:57], 1.0 op_sel_hi:[1,0]
	s_nop 0
	v_pk_mul_f32 v[56:57], v[58:59], v[56:57]
	s_nop 0
	v_cvt_pk_bf16_f32 v63, v56, v57
	v_or_b32_e32 v56, 32, v164
	v_ashrrev_i32_e32 v57, 31, v56
	v_lshlrev_b64 v[56:57], 9, v[56:57]
	v_lshl_add_u64 v[56:57], v[214:215], 0, v[56:57]
	v_lshl_add_u64 v[58:59], v[56:57], 0, v[166:167]
	v_permlane16_swap_b32_e32 v61, v63
	v_lshl_add_u64 v[56:57], v[56:57], 0, v[168:169]
	global_store_dwordx4 v[58:59], v[68:71], off
	global_store_dwordx4 v[56:57], v[60:63], off
	global_load_dwordx4 v[68:71], v212, s[16:17]
	s_nop 0
	global_load_dwordx4 v[72:75], v212, s[16:17] offset:1024
	global_load_dwordx4 v[76:79], v212, s[16:17] offset:2048
	global_load_dwordx4 v[80:83], v212, s[16:17] offset:3072
	global_load_dwordx4 v[86:89], v[216:217], off offset:-4096
	global_load_dwordx4 v[60:63], v[220:221], off offset:1024
	global_load_dwordx4 v[52:55], v[220:221], off offset:2048
	global_load_dwordx4 v[48:51], v[220:221], off offset:3072
	global_load_dwordx4 v[44:47], v[218:219], off offset:-4096
	global_load_dwordx4 v[56:59], v[216:217], off offset:1024
	global_load_dwordx4 v[64:67], v[216:217], off offset:2048
	global_load_dwordx4 v[32:35], v[216:217], off offset:3072
	global_load_dwordx4 v[36:39], v[218:219], off
	global_load_dwordx4 v[28:31], v[218:219], off offset:1024
	global_load_dwordx4 v[40:43], v[218:219], off offset:2048
	global_load_dwordx4 v[24:27], v[218:219], off offset:3072
	global_load_dwordx4 v[92:95], v[218:219], off offset:2112
	global_load_dwordx4 v[16:19], v212, s[16:17] offset:64
	global_load_dwordx4 v[20:23], v212, s[16:17] offset:1088
	global_load_dwordx4 v[96:99], v[218:219], off offset:3136
	s_waitcnt vmcnt(19)
; DI unsigned pack2(float a, float b) { v2f f = {a, b}; return __builtin_bit_cast(unsigned, __builtin_convertvector(f, v2bf)); }
;   DI u32x2 pack(int, int, float a, float b, float c, float d, float&) const { u32x2 v; v.x = pack2(a, b); v.y = pack2(c, d); return v; }
; template <class ARow, class Epi>
; DI void gemm_tile(const ARow& arow, long a_kstride, const u16* __restrict__ Bt, long ldb, int K, int m0, int n0,
;                   const Epi& epi, char* smem) {
;     ...
;     for (int mi = 0; mi < 4; ++mi) {
;       const int m = m0 + wm * 64 + mi * 16 + fr;
;       float ss = 0.f;
;       u32x2 pk[4];
; #pragma unroll
;       for (int ni = 0; ni < 4; ++ni) pk[ni] = epi.pack(m, nh + ni * 16 + fq * 4, acc[ni][mi][0], acc[ni][mi][1], acc[ni][mi][2], acc[ni][mi][3], ss);
;       epi.finish16(m, nh, ss);
;       u16* rp = epi.rowp(m) + nh;
; #pragma unroll
;       for (int pp = 0; pp < 2; ++pp) {
;         u32x2 a = pk[2 * pp], b = pk[2 * pp + 1];
;         const u32x2 rx = __builtin_amdgcn_permlane16_swap(a.x, b.x, false, false);
;         const u32x2 ry = __builtin_amdgcn_permlane16_swap(a.y, b.y, false, false);
;         const int nst = (fq & 1) ? ((2 * pp + 1) * 16 + (fq - 1) * 4) : ((2 * pp) * 16 + fq * 4);
;         *(u32x4*)(rp + nst) = (u32x4){rx[0], ry[0], rx[1], ry[1]};
;       }
;   DI u32x2 pack(int m, int n, float a, float b, float c, float d, float& ss) const {
;     f32x4 bs = {0.f, 0.f, 0.f, 0.f};
; #pragma unroll
;     for (int kc = 0; kc < 16; ++kc) bs += *(const f32x4*)(bias_part + kc * 256 + n);
;     u32x2 v; v.x = pack2(gelu_tanh(a + bs[0]), gelu_tanh(b + bs[1])); v.y = pack2(gelu_tanh(c + bs[2]), gelu_tanh(d + bs[3]));
;     return v;
;   }
	v_pk_add_f32 v[70:71], v[70:71], 0 op_sel_hi:[1,0]
	v_pk_add_f32 v[68:69], v[68:69], 0 op_sel_hi:[1,0]
	s_waitcnt vmcnt(18)
	v_pk_add_f32 v[74:75], v[70:71], v[74:75]
	v_pk_add_f32 v[72:73], v[68:69], v[72:73]
	s_waitcnt vmcnt(17)
	v_pk_add_f32 v[78:79], v[74:75], v[78:79]
	v_pk_add_f32 v[76:77], v[72:73], v[76:77]
	s_waitcnt vmcnt(16)
	v_pk_add_f32 v[82:83], v[78:79], v[82:83]
	v_pk_add_f32 v[80:81], v[76:77], v[80:81]
	s_waitcnt vmcnt(15)
	v_pk_add_f32 v[84:85], v[82:83], v[88:89]
	v_pk_add_f32 v[86:87], v[80:81], v[86:87]
	s_waitcnt vmcnt(14)
	v_pk_add_f32 v[84:85], v[84:85], v[62:63]
	v_pk_add_f32 v[86:87], v[86:87], v[60:61]
	s_waitcnt vmcnt(13)
	v_pk_add_f32 v[84:85], v[84:85], v[54:55]
	v_pk_add_f32 v[86:87], v[86:87], v[52:53]
	s_waitcnt vmcnt(12)
	v_pk_add_f32 v[84:85], v[84:85], v[50:51]
	v_pk_add_f32 v[86:87], v[86:87], v[48:49]
	s_waitcnt vmcnt(11)
	v_pk_add_f32 v[84:85], v[84:85], v[46:47]
	v_pk_add_f32 v[86:87], v[86:87], v[44:45]
	s_waitcnt vmcnt(10)
	v_pk_add_f32 v[84:85], v[84:85], v[58:59]
	v_pk_add_f32 v[86:87], v[86:87], v[56:57]
	s_waitcnt vmcnt(9)
	v_pk_add_f32 v[100:101], v[84:85], v[66:67]
	v_pk_add_f32 v[84:85], v[86:87], v[64:65]
	global_load_dwordx4 v[68:71], v212, s[16:17] offset:2112
	global_load_dwordx4 v[72:75], v212, s[16:17] offset:3136
	s_waitcnt vmcnt(10)
	v_pk_add_f32 v[32:33], v[84:85], v[32:33]
	global_load_dwordx4 v[60:63], v[220:221], off offset:1216
	s_waitcnt vmcnt(10)
	v_pk_add_f32 v[32:33], v[32:33], v[36:37]
	global_load_dwordx4 v[76:79], v[216:217], off offset:64
	global_load_dwordx4 v[44:47], v[216:217], off offset:1088
	s_waitcnt vmcnt(11)
	v_pk_add_f32 v[28:29], v[32:33], v[28:29]
	global_load_dwordx4 v[56:59], v[216:217], off offset:2112
	global_load_dwordx4 v[64:67], v[216:217], off offset:3136
	s_waitcnt vmcnt(12)
	v_pk_add_f32 v[28:29], v[28:29], v[40:41]
	global_load_dwordx4 v[84:87], v[218:219], off offset:64
	global_load_dwordx4 v[88:91], v[218:219], off offset:1088
	s_waitcnt vmcnt(13)
	v_pk_add_f32 v[24:25], v[28:29], v[24:25]
	v_pk_add_f32 v[28:29], v[100:101], v[34:35]
	v_pk_add_f32 v[12:13], v[12:13], v[24:25]
	v_pk_add_f32 v[28:29], v[28:29], v[38:39]
	v_mul_f32_e32 v24, 0x3d372713, v12
	v_mul_f32_e32 v25, 0x3d372713, v13
	v_mul_f32_e32 v24, v12, v24
	v_mul_f32_e32 v25, v13, v25
	v_fma_f32 v24, v12, v24, v12
	v_fma_f32 v25, v13, v25, v13
	v_mul_f32_e32 v24, 0x3f4c422a, v24
	v_mul_f32_e32 v25, 0x3f4c422a, v25
	v_add_f32_e32 v24, v24, v24
	v_add_f32_e32 v25, v25, v25
	v_mul_f32_e32 v24, 0x3fb8aa3b, v24
	v_mul_f32_e32 v25, 0x3fb8aa3b, v25
	v_exp_f32_e32 v24, v24
	v_exp_f32_e32 v25, v25
	v_pk_add_f32 v[28:29], v[28:29], v[30:31]
	v_pk_mul_f32 v[12:13], v[12:13], 0.5 op_sel_hi:[1,0]
	s_waitcnt vmcnt(11)
	v_pk_add_f32 v[16:17], v[16:17], 0 op_sel_hi:[1,0]
	v_pk_add_f32 v[40:41], v[24:25], 1.0 op_sel_hi:[1,0]
	v_pk_add_f32 v[24:25], v[28:29], v[42:43]
	v_div_scale_f32 v30, s[0:1], v41, v41, 2.0
	v_rcp_f32_e32 v31, v30
	v_pk_add_f32 v[24:25], v[24:25], v[26:27]
	v_div_scale_f32 v42, s[0:1], v40, v40, 2.0
	v_pk_add_f32 v[14:15], v[14:15], v[24:25]
	v_fma_f32 v24, -v30, v31, 1.0
	v_fmac_f32_e32 v31, v24, v31
	v_div_scale_f32 v24, vcc, 2.0, v41, 2.0
	v_mul_f32_e32 v28, v24, v31
	v_fma_f32 v25, -v30, v28, v24
	v_rcp_f32_e32 v43, v42
	v_fmac_f32_e32 v28, v25, v31
	v_fma_f32 v29, -v30, v28, v24
	global_load_dwordx4 v[24:27], v[220:221], off offset:64
	v_div_fmas_f32 v32, v29, v31, v28
	global_load_dwordx4 v[28:31], v[220:221], off offset:1088
	v_div_fixup_f32 v41, v32, v41, 2.0
	v_fma_f32 v36, -v42, v43, 1.0
	global_load_dwordx4 v[32:35], v[220:221], off offset:2112
	v_fmac_f32_e32 v43, v36, v43
	global_load_dwordx4 v[36:39], v[220:221], off offset:3136
	v_div_scale_f32 v100, vcc, 2.0, v40, 2.0
	v_mul_f32_e32 v101, v100, v43
	v_fma_f32 v102, -v42, v101, v100
	v_fmac_f32_e32 v101, v102, v43
	v_fma_f32 v42, -v42, v101, v100
	v_div_fmas_f32 v100, v42, v43, v101
	v_mul_f32_e32 v42, 0x3d372713, v14
	v_mul_f32_e32 v43, 0x3d372713, v15
	v_mul_f32_e32 v42, v14, v42
	v_mul_f32_e32 v43, v15, v43
	v_fma_f32 v42, v14, v42, v14
	v_fma_f32 v43, v15, v43, v15
	v_mul_f32_e32 v42, 0x3f4c422a, v42
	v_mul_f32_e32 v43, 0x3f4c422a, v43
	v_add_f32_e32 v42, v42, v42
	v_add_f32_e32 v43, v43, v43
	v_mul_f32_e32 v42, 0x3fb8aa3b, v42
	v_mul_f32_e32 v43, 0x3fb8aa3b, v43
	v_exp_f32_e32 v42, v42
	v_exp_f32_e32 v43, v43
	v_div_fixup_f32 v40, v100, v40, 2.0
	v_pk_add_f32 v[40:41], v[40:41], 1.0 op_sel_hi:[1,0] neg_lo:[1,0] neg_hi:[1,0]
	v_pk_mul_f32 v[14:15], v[14:15], 0.5 op_sel_hi:[1,0]
	v_pk_add_f32 v[42:43], v[42:43], 1.0 op_sel_hi:[1,0]
	v_pk_add_f32 v[40:41], v[40:41], 1.0 op_sel_hi:[1,0]
	v_div_scale_f32 v100, s[0:1], v43, v43, 2.0
	v_rcp_f32_e32 v101, v100
	v_pk_mul_f32 v[12:13], v[12:13], v[40:41]
	s_waitcnt vmcnt(14)
	v_pk_add_f32 v[16:17], v[16:17], v[20:21]
	v_cvt_pk_bf16_f32 v12, v12, v13
	v_fma_f32 v13, -v100, v101, 1.0
	v_fmac_f32_e32 v101, v13, v101
	v_div_scale_f32 v13, vcc, 2.0, v43, 2.0
	v_mul_f32_e32 v40, v13, v101
	v_fma_f32 v41, -v100, v40, v13
	v_fmac_f32_e32 v40, v41, v101
	v_fma_f32 v13, -v100, v40, v13
	v_div_scale_f32 v100, s[0:1], v42, v42, 2.0
	v_rcp_f32_e32 v102, v100
	v_div_fmas_f32 v13, v13, v101, v40
	v_div_fixup_f32 v41, v13, v43, 2.0
	s_waitcnt vmcnt(12)
	v_pk_add_f32 v[16:17], v[16:17], v[68:69]
	v_fma_f32 v13, -v100, v102, 1.0
	v_fmac_f32_e32 v102, v13, v102
	v_div_scale_f32 v13, vcc, 2.0, v42, 2.0
	v_mul_f32_e32 v40, v13, v102
	v_fma_f32 v43, -v100, v40, v13
	v_fmac_f32_e32 v40, v43, v102
	v_fma_f32 v13, -v100, v40, v13
	v_div_fmas_f32 v13, v13, v102, v40
	v_div_fixup_f32 v40, v13, v42, 2.0
	v_pk_add_f32 v[40:41], v[40:41], 1.0 op_sel_hi:[1,0] neg_lo:[1,0] neg_hi:[1,0]
	s_waitcnt vmcnt(11)
; DI unsigned pack2(float a, float b) { v2f f = {a, b}; return __builtin_bit_cast(unsigned, __builtin_convertvector(f, v2bf)); }
;   DI u32x2 pack(int, int, float a, float b, float c, float d, float&) const { u32x2 v; v.x = pack2(a, b); v.y = pack2(c, d); return v; }
; template <class ARow, class Epi>
; DI void gemm_tile(const ARow& arow, long a_kstride, const u16* __restrict__ Bt, long ldb, int K, int m0, int n0,
;                   const Epi& epi, char* smem) {
;     ...
;     for (int mi = 0; mi < 4; ++mi) {
;       const int m = m0 + wm * 64 + mi * 16 + fr;
;       float ss = 0.f;
;       u32x2 pk[4];
; #pragma unroll
;       for (int ni = 0; ni < 4; ++ni) pk[ni] = epi.pack(m, nh + ni * 16 + fq * 4, acc[ni][mi][0], acc[ni][mi][1], acc[ni][mi][2], acc[ni][mi][3], ss);
;       epi.finish16(m, nh, ss);
;       u16* rp = epi.rowp(m) + nh;
; #pragma unroll
;       for (int pp = 0; pp < 2; ++pp) {
;         u32x2 a = pk[2 * pp], b = pk[2 * pp + 1];
;         const u32x2 rx = __builtin_amdgcn_permlane16_swap(a.x, b.x, false, false);
;         const u32x2 ry = __builtin_amdgcn_permlane16_swap(a.y, b.y, false, false);
;         const int nst = (fq & 1) ? ((2 * pp + 1) * 16 + (fq - 1) * 4) : ((2 * pp) * 16 + fq * 4);
;         *(u32x4*)(rp + nst) = (u32x4){rx[0], ry[0], rx[1], ry[1]};
;       }
;   DI u32x2 pack(int m, int n, float a, float b, float c, float d, float& ss) const {
;     f32x4 bs = {0.f, 0.f, 0.f, 0.f};
; #pragma unroll
;     for (int kc = 0; kc < 16; ++kc) bs += *(const f32x4*)(bias_part + kc * 256 + n);
;     u32x2 v; v.x = pack2(gelu_tanh(a + bs[0]), gelu_tanh(b + bs[1])); v.y = pack2(gelu_tanh(c + bs[2]), gelu_tanh(d + bs[3]));
;     return v;
;   }
	v_pk_add_f32 v[20:21], v[16:17], v[72:73]
	v_pk_add_f32 v[40:41], v[40:41], 1.0 op_sel_hi:[1,0]
	global_load_dwordx4 v[80:83], v[220:221], off offset:192
	v_pk_mul_f32 v[14:15], v[14:15], v[40:41]
	global_load_dwordx4 v[40:43], v212, s[16:17] offset:3200
	v_cvt_pk_bf16_f32 v13, v14, v15
	v_pk_add_f32 v[14:15], v[18:19], 0 op_sel_hi:[1,0]
	global_load_dwordx4 v[16:19], v[220:221], off offset:128
	v_pk_add_f32 v[14:15], v[14:15], v[22:23]
	global_load_dwordx4 v[52:55], v[220:221], off offset:2240
	v_pk_add_f32 v[14:15], v[14:15], v[70:71]
	global_load_dwordx4 v[48:51], v[220:221], off offset:3264
	v_pk_add_f32 v[14:15], v[14:15], v[74:75]
	s_waitcnt vmcnt(8)
	v_pk_add_f32 v[24:25], v[20:21], v[24:25]
	global_load_dwordx4 v[20:23], v[220:221], off offset:1152
	s_waitcnt vmcnt(8)
	v_pk_add_f32 v[28:29], v[24:25], v[28:29]
	v_pk_add_f32 v[14:15], v[14:15], v[26:27]
	global_load_dwordx4 v[24:27], v[220:221], off offset:2176
	s_waitcnt vmcnt(8)
	v_pk_add_f32 v[32:33], v[28:29], v[32:33]
	v_pk_add_f32 v[14:15], v[14:15], v[30:31]
	global_load_dwordx4 v[28:31], v[220:221], off offset:3200
	s_waitcnt vmcnt(8)
	v_pk_add_f32 v[32:33], v[32:33], v[36:37]
	v_pk_add_f32 v[14:15], v[14:15], v[34:35]
	v_pk_add_f32 v[32:33], v[32:33], v[76:77]
	v_pk_add_f32 v[14:15], v[14:15], v[38:39]
	v_pk_add_f32 v[32:33], v[32:33], v[44:45]
	v_pk_add_f32 v[14:15], v[14:15], v[78:79]
	v_pk_add_f32 v[32:33], v[32:33], v[56:57]
	v_pk_add_f32 v[14:15], v[14:15], v[46:47]
	v_pk_add_f32 v[32:33], v[32:33], v[64:65]
	v_pk_add_f32 v[14:15], v[14:15], v[58:59]
	v_pk_add_f32 v[32:33], v[32:33], v[84:85]
	v_pk_add_f32 v[14:15], v[14:15], v[66:67]
	v_pk_add_f32 v[32:33], v[32:33], v[88:89]
	v_pk_add_f32 v[14:15], v[14:15], v[86:87]
	v_pk_add_f32 v[32:33], v[32:33], v[92:93]
	v_pk_add_f32 v[14:15], v[14:15], v[90:91]
	v_pk_add_f32 v[32:33], v[32:33], v[96:97]
	global_load_dwordx4 v[36:39], v212, s[16:17] offset:2176
	v_pk_add_f32 v[92:93], v[8:9], v[32:33]
	s_nop 0
	v_mul_f32_e32 v8, 0x3d372713, v92
	v_mul_f32_e32 v9, 0x3d372713, v93
	v_mul_f32_e32 v8, v92, v8
	v_mul_f32_e32 v9, v93, v9
	v_fma_f32 v8, v92, v8, v92
	v_fma_f32 v9, v93, v9, v93
	v_mul_f32_e32 v8, 0x3f4c422a, v8
	v_mul_f32_e32 v9, 0x3f4c422a, v9
	v_add_f32_e32 v8, v8, v8
	v_add_f32_e32 v9, v9, v9
	v_mul_f32_e32 v8, 0x3fb8aa3b, v8
	v_mul_f32_e32 v9, 0x3fb8aa3b, v9
	v_exp_f32_e32 v8, v8
	v_exp_f32_e32 v9, v9
	v_pk_mul_f32 v[92:93], v[92:93], 0.5 op_sel_hi:[1,0]
	v_pk_add_f32 v[96:97], v[8:9], 1.0 op_sel_hi:[1,0]
	s_nop 0
	v_div_scale_f32 v32, s[0:1], v97, v97, 2.0
	v_rcp_f32_e32 v33, v32
	v_pk_add_f32 v[8:9], v[14:15], v[94:95]
	v_div_scale_f32 v44, s[0:1], v96, v96, 2.0
	v_pk_add_f32 v[8:9], v[8:9], v[98:99]
	v_rcp_f32_e32 v45, v44
	v_pk_add_f32 v[94:95], v[10:11], v[8:9]
	v_fma_f32 v8, -v32, v33, 1.0
	v_fmac_f32_e32 v33, v8, v33
	v_div_scale_f32 v8, vcc, 2.0, v97, 2.0
	v_mul_f32_e32 v14, v8, v33
	v_fma_f32 v9, -v32, v14, v8
	v_fmac_f32_e32 v14, v9, v33
	v_fma_f32 v15, -v32, v14, v8
	v_div_fmas_f32 v14, v15, v33, v14
	v_div_fixup_f32 v15, v14, v97, 2.0
	v_fma_f32 v14, -v44, v45, 1.0
	global_load_dwordx4 v[8:11], v212, s[16:17] offset:128
	v_fmac_f32_e32 v45, v14, v45
	v_div_scale_f32 v14, vcc, 2.0, v96, 2.0
	global_load_dwordx4 v[32:35], v212, s[16:17] offset:1152
	v_mul_f32_e32 v46, v14, v45
	v_fma_f32 v47, -v44, v46, v14
	v_fmac_f32_e32 v46, v47, v45
	v_fma_f32 v14, -v44, v46, v14
	v_mul_f32_e32 v44, 0x3d372713, v94
	v_mul_f32_e32 v44, v94, v44
	v_fma_f32 v56, v94, v44, v94
	v_mul_f32_e32 v56, 0x3f4c422a, v56
	v_div_fmas_f32 v14, v14, v45, v46
	global_load_dwordx4 v[44:47], v[216:217], off offset:128
	v_add_f32_e32 v64, v56, v56
	global_load_dwordx4 v[56:59], v[216:217], off offset:1152
	v_mul_f32_e32 v64, 0x3fb8aa3b, v64
	v_exp_f32_e32 v98, v64
	global_load_dwordx4 v[64:67], v[216:217], off offset:2176
	v_mul_f32_e32 v68, 0x3d372713, v95
	v_mul_f32_e32 v72, v95, v68
	global_load_dwordx4 v[68:71], v[216:217], off offset:3200
	v_fma_f32 v76, v95, v72, v95
	global_load_dwordx4 v[72:75], v[218:219], off offset:128
	v_mul_f32_e32 v84, 0x3f4c422a, v76
	global_load_dwordx4 v[76:79], v[218:219], off offset:1152
	v_add_f32_e32 v88, v84, v84
	global_load_dwordx4 v[84:87], v[218:219], off offset:2176
	v_mul_f32_e32 v97, 0x3fb8aa3b, v88
	global_load_dwordx4 v[88:91], v[218:219], off offset:3200
	v_exp_f32_e32 v99, v97
	v_div_fixup_f32 v14, v14, v96, 2.0
	v_pk_add_f32 v[14:15], v[14:15], 1.0 op_sel_hi:[1,0] neg_lo:[1,0] neg_hi:[1,0]
	v_pk_mul_f32 v[94:95], v[94:95], 0.5 op_sel_hi:[1,0]
	v_pk_add_f32 v[96:97], v[98:99], 1.0 op_sel_hi:[1,0]
	v_pk_add_f32 v[14:15], v[14:15], 1.0 op_sel_hi:[1,0]
	v_div_scale_f32 v98, s[0:1], v97, v97, 2.0
	v_rcp_f32_e32 v99, v98
	v_pk_mul_f32 v[14:15], v[92:93], v[14:15]
	s_nop 0
	v_cvt_pk_bf16_f32 v14, v14, v15
	v_fma_f32 v15, -v98, v99, 1.0
	v_fmac_f32_e32 v99, v15, v99
	v_div_scale_f32 v15, vcc, 2.0, v97, 2.0
	v_mul_f32_e32 v92, v15, v99
	v_fma_f32 v93, -v98, v92, v15
	v_fmac_f32_e32 v92, v93, v99
	v_fma_f32 v15, -v98, v92, v15
	v_div_scale_f32 v98, s[0:1], v96, v96, 2.0
	v_rcp_f32_e32 v100, v98
	v_div_fmas_f32 v15, v15, v99, v92
	v_div_fixup_f32 v93, v15, v97, 2.0
	v_permlane16_swap_b32_e32 v12, v14
	v_fma_f32 v15, -v98, v100, 1.0
	v_fmac_f32_e32 v100, v15, v100
	v_div_scale_f32 v15, vcc, 2.0, v96, 2.0
	v_mul_f32_e32 v92, v15, v100
	v_fma_f32 v97, -v98, v92, v15
	v_fmac_f32_e32 v92, v97, v100
	v_fma_f32 v15, -v98, v92, v15
	v_div_fmas_f32 v15, v15, v100, v92
	v_div_fixup_f32 v92, v15, v96, 2.0
	v_pk_add_f32 v[92:93], v[92:93], 1.0 op_sel_hi:[1,0] neg_lo:[1,0] neg_hi:[1,0]
	s_nop 0
	v_pk_add_f32 v[92:93], v[92:93], 1.0 op_sel_hi:[1,0]
	s_nop 0
	v_pk_mul_f32 v[92:93], v[94:95], v[92:93]
	s_nop 0
	v_cvt_pk_bf16_f32 v15, v92, v93
	global_load_dwordx4 v[92:95], v212, s[16:17] offset:192
	s_nop 0
	v_permlane16_swap_b32_e32 v13, v15
	s_waitcnt vmcnt(10)
; DI unsigned pack2(float a, float b) { v2f f = {a, b}; return __builtin_bit_cast(unsigned, __builtin_convertvector(f, v2bf)); }
;   DI u32x2 pack(int, int, float a, float b, float c, float d, float&) const { u32x2 v; v.x = pack2(a, b); v.y = pack2(c, d); return v; }
; template <class ARow, class Epi>
; DI void gemm_tile(const ARow& arow, long a_kstride, const u16* __restrict__ Bt, long ldb, int K, int m0, int n0,
;                   const Epi& epi, char* smem) {
;     ...
;     for (int mi = 0; mi < 4; ++mi) {
;       const int m = m0 + wm * 64 + mi * 16 + fr;
;       float ss = 0.f;
;       u32x2 pk[4];
; #pragma unroll
;       for (int ni = 0; ni < 4; ++ni) pk[ni] = epi.pack(m, nh + ni * 16 + fq * 4, acc[ni][mi][0], acc[ni][mi][1], acc[ni][mi][2], acc[ni][mi][3], ss);
;       epi.finish16(m, nh, ss);
;       u16* rp = epi.rowp(m) + nh;
; #pragma unroll
;       for (int pp = 0; pp < 2; ++pp) {
;         u32x2 a = pk[2 * pp], b = pk[2 * pp + 1];
;         const u32x2 rx = __builtin_amdgcn_permlane16_swap(a.x, b.x, false, false);
;         const u32x2 ry = __builtin_amdgcn_permlane16_swap(a.y, b.y, false, false);
;         const int nst = (fq & 1) ? ((2 * pp + 1) * 16 + (fq - 1) * 4) : ((2 * pp) * 16 + fq * 4);
;         *(u32x4*)(rp + nst) = (u32x4){rx[0], ry[0], rx[1], ry[1]};
;       }
;   DI u32x2 pack(int m, int n, float a, float b, float c, float d, float& ss) const {
;     f32x4 bs = {0.f, 0.f, 0.f, 0.f};
; #pragma unroll
;     for (int kc = 0; kc < 16; ++kc) bs += *(const f32x4*)(bias_part + kc * 256 + n);
;     u32x2 v; v.x = pack2(gelu_tanh(a + bs[0]), gelu_tanh(b + bs[1])); v.y = pack2(gelu_tanh(c + bs[2]), gelu_tanh(d + bs[3]));
;     return v;
;   }
	v_pk_add_f32 v[98:99], v[8:9], 0 op_sel_hi:[1,0]
	v_pk_add_f32 v[96:97], v[10:11], 0 op_sel_hi:[1,0]
	global_load_dwordx4 v[8:11], v212, s[16:17] offset:1216
	s_waitcnt vmcnt(10)
	v_pk_add_f32 v[98:99], v[98:99], v[32:33]
	v_pk_add_f32 v[96:97], v[96:97], v[34:35]
	global_load_dwordx4 v[32:35], v212, s[16:17] offset:2240
	v_pk_add_f32 v[98:99], v[98:99], v[36:37]
	v_pk_add_f32 v[96:97], v[96:97], v[38:39]
	global_load_dwordx4 v[36:39], v212, s[16:17] offset:3264
	v_pk_add_f32 v[40:41], v[98:99], v[40:41]
	v_pk_add_f32 v[42:43], v[96:97], v[42:43]
	v_pk_add_f32 v[16:17], v[40:41], v[16:17]
	v_pk_add_f32 v[18:19], v[42:43], v[18:19]
	v_pk_add_f32 v[16:17], v[16:17], v[20:21]
	v_pk_add_f32 v[18:19], v[18:19], v[22:23]
	v_pk_add_f32 v[16:17], v[16:17], v[24:25]
	v_pk_add_f32 v[18:19], v[18:19], v[26:27]
	v_pk_add_f32 v[22:23], v[16:17], v[28:29]
	v_pk_add_f32 v[20:21], v[18:19], v[30:31]
	global_load_dwordx4 v[16:19], v[216:217], off offset:192
	s_waitcnt vmcnt(12)
	v_pk_add_f32 v[26:27], v[22:23], v[44:45]
	v_pk_add_f32 v[24:25], v[20:21], v[46:47]
	global_load_dwordx4 v[20:23], v[216:217], off offset:1216
	s_waitcnt vmcnt(12)
	v_pk_add_f32 v[30:31], v[26:27], v[56:57]
	v_pk_add_f32 v[28:29], v[24:25], v[58:59]
	global_load_dwordx4 v[24:27], v[216:217], off offset:2240
	s_waitcnt vmcnt(12)
	v_pk_add_f32 v[40:41], v[30:31], v[64:65]
	v_pk_add_f32 v[96:97], v[28:29], v[66:67]
	global_load_dwordx4 v[28:31], v[216:217], off offset:3264
	s_waitcnt vmcnt(12)
	v_pk_add_f32 v[44:45], v[40:41], v[68:69]
	global_load_dwordx4 v[40:43], v[218:219], off offset:192
	s_waitcnt vmcnt(12)
	v_pk_add_f32 v[56:57], v[44:45], v[72:73]
	global_load_dwordx4 v[44:47], v[218:219], off offset:1216
	s_waitcnt vmcnt(12)
	v_pk_add_f32 v[64:65], v[56:57], v[76:77]
	global_load_dwordx4 v[56:59], v[218:219], off offset:2240
	s_waitcnt vmcnt(12)
	v_pk_add_f32 v[68:69], v[64:65], v[84:85]
	global_load_dwordx4 v[64:67], v[218:219], off offset:3264
	s_waitcnt vmcnt(12)
	v_pk_add_f32 v[68:69], v[68:69], v[88:89]
	v_pk_add_f32 v[70:71], v[96:97], v[70:71]
	v_pk_add_f32 v[4:5], v[4:5], v[68:69]
	v_pk_add_f32 v[70:71], v[70:71], v[74:75]
	v_mul_f32_e32 v68, 0x3d372713, v4
	v_mul_f32_e32 v69, 0x3d372713, v5
	v_mul_f32_e32 v68, v4, v68
	v_mul_f32_e32 v69, v5, v69
	v_fma_f32 v68, v4, v68, v4
	v_fma_f32 v69, v5, v69, v5
	v_mul_f32_e32 v68, 0x3f4c422a, v68
	v_mul_f32_e32 v69, 0x3f4c422a, v69
	v_add_f32_e32 v68, v68, v68
	v_add_f32_e32 v69, v69, v69
	v_mul_f32_e32 v68, 0x3fb8aa3b, v68
	v_mul_f32_e32 v69, 0x3fb8aa3b, v69
	v_exp_f32_e32 v68, v68
	v_exp_f32_e32 v69, v69
	v_pk_add_f32 v[70:71], v[70:71], v[78:79]
	v_pk_mul_f32 v[4:5], v[4:5], 0.5 op_sel_hi:[1,0]
	v_pk_add_f32 v[70:71], v[70:71], v[86:87]
	v_pk_add_f32 v[68:69], v[68:69], 1.0 op_sel_hi:[1,0]
	v_pk_add_f32 v[70:71], v[70:71], v[90:91]
	v_div_scale_f32 v72, s[0:1], v69, v69, 2.0
	v_rcp_f32_e32 v73, v72
	v_pk_add_f32 v[6:7], v[6:7], v[70:71]
	v_fma_f32 v70, -v72, v73, 1.0
	v_fmac_f32_e32 v73, v70, v73
	v_div_scale_f32 v70, vcc, 2.0, v69, 2.0
	v_mul_f32_e32 v71, v70, v73
	v_fma_f32 v74, -v72, v71, v70
	v_fmac_f32_e32 v71, v74, v73
	v_fma_f32 v70, -v72, v71, v70
	v_div_scale_f32 v72, s[0:1], v68, v68, 2.0
	v_rcp_f32_e32 v74, v72
	v_div_fmas_f32 v70, v70, v73, v71
	v_div_fixup_f32 v69, v70, v69, 2.0
	v_fma_f32 v70, -v72, v74, 1.0
	v_fmac_f32_e32 v74, v70, v74
	v_div_scale_f32 v70, vcc, 2.0, v68, 2.0
	v_mul_f32_e32 v71, v70, v74
	v_fma_f32 v73, -v72, v71, v70
	v_fmac_f32_e32 v71, v73, v74
	v_fma_f32 v70, -v72, v71, v70
	v_div_fmas_f32 v72, v70, v74, v71
	v_mul_f32_e32 v70, 0x3d372713, v6
	v_mul_f32_e32 v71, 0x3d372713, v7
	v_mul_f32_e32 v70, v6, v70
	v_mul_f32_e32 v71, v7, v71
	v_fma_f32 v70, v6, v70, v6
	v_fma_f32 v71, v7, v71, v7
	v_mul_f32_e32 v70, 0x3f4c422a, v70
	v_mul_f32_e32 v71, 0x3f4c422a, v71
	v_add_f32_e32 v70, v70, v70
	v_add_f32_e32 v71, v71, v71
	v_mul_f32_e32 v70, 0x3fb8aa3b, v70
	v_mul_f32_e32 v71, 0x3fb8aa3b, v71
	v_exp_f32_e32 v70, v70
	v_exp_f32_e32 v71, v71
	v_div_fixup_f32 v68, v72, v68, 2.0
	v_pk_add_f32 v[68:69], v[68:69], 1.0 op_sel_hi:[1,0] neg_lo:[1,0] neg_hi:[1,0]
	v_pk_mul_f32 v[6:7], v[6:7], 0.5 op_sel_hi:[1,0]
	v_pk_add_f32 v[70:71], v[70:71], 1.0 op_sel_hi:[1,0]
	v_pk_add_f32 v[68:69], v[68:69], 1.0 op_sel_hi:[1,0]
	v_div_scale_f32 v72, s[0:1], v71, v71, 2.0
	v_rcp_f32_e32 v73, v72
	v_pk_mul_f32 v[4:5], v[4:5], v[68:69]
	s_nop 0
	v_cvt_pk_bf16_f32 v4, v4, v5
	v_fma_f32 v5, -v72, v73, 1.0
	v_fmac_f32_e32 v73, v5, v73
	v_div_scale_f32 v5, vcc, 2.0, v71, 2.0
	v_mul_f32_e32 v68, v5, v73
	v_fma_f32 v69, -v72, v68, v5
	v_fmac_f32_e32 v68, v69, v73
	v_fma_f32 v5, -v72, v68, v5
	v_div_scale_f32 v72, s[0:1], v70, v70, 2.0
	v_rcp_f32_e32 v74, v72
	v_div_fmas_f32 v5, v5, v73, v68
	v_div_fixup_f32 v69, v5, v71, 2.0
	v_fma_f32 v5, -v72, v74, 1.0
	v_fmac_f32_e32 v74, v5, v74
	v_div_scale_f32 v5, vcc, 2.0, v70, 2.0
	v_mul_f32_e32 v68, v5, v74
	v_fma_f32 v71, -v72, v68, v5
	v_fmac_f32_e32 v68, v71, v74
	v_fma_f32 v5, -v72, v68, v5
	v_div_fmas_f32 v5, v5, v74, v68
	v_div_fixup_f32 v68, v5, v70, 2.0
	v_pk_add_f32 v[68:69], v[68:69], 1.0 op_sel_hi:[1,0] neg_lo:[1,0] neg_hi:[1,0]
	s_nop 0
	v_pk_add_f32 v[68:69], v[68:69], 1.0 op_sel_hi:[1,0]
	s_nop 0
	v_pk_mul_f32 v[6:7], v[6:7], v[68:69]
	s_waitcnt vmcnt(11)
; DI unsigned pack2(float a, float b) { v2f f = {a, b}; return __builtin_bit_cast(unsigned, __builtin_convertvector(f, v2bf)); }
;   DI u32x2 pack(int, int, float a, float b, float c, float d, float&) const { u32x2 v; v.x = pack2(a, b); v.y = pack2(c, d); return v; }
; template <class ARow, class Epi>
; DI void gemm_tile(const ARow& arow, long a_kstride, const u16* __restrict__ Bt, long ldb, int K, int m0, int n0,
;                   const Epi& epi, char* smem) {
;     ...
;     for (int mi = 0; mi < 4; ++mi) {
;       const int m = m0 + wm * 64 + mi * 16 + fr;
;       float ss = 0.f;
;       u32x2 pk[4];
; #pragma unroll
;       for (int ni = 0; ni < 4; ++ni) pk[ni] = epi.pack(m, nh + ni * 16 + fq * 4, acc[ni][mi][0], acc[ni][mi][1], acc[ni][mi][2], acc[ni][mi][3], ss);
;       epi.finish16(m, nh, ss);
;       u16* rp = epi.rowp(m) + nh;
; #pragma unroll
;       for (int pp = 0; pp < 2; ++pp) {
;         u32x2 a = pk[2 * pp], b = pk[2 * pp + 1];
;         const u32x2 rx = __builtin_amdgcn_permlane16_swap(a.x, b.x, false, false);
;         const u32x2 ry = __builtin_amdgcn_permlane16_swap(a.y, b.y, false, false);
;         const int nst = (fq & 1) ? ((2 * pp + 1) * 16 + (fq - 1) * 4) : ((2 * pp) * 16 + fq * 4);
;         *(u32x4*)(rp + nst) = (u32x4){rx[0], ry[0], rx[1], ry[1]};
;       }
;   DI u32x2 pack(int m, int n, float a, float b, float c, float d, float& ss) const {
;     f32x4 bs = {0.f, 0.f, 0.f, 0.f};
; #pragma unroll
;     for (int kc = 0; kc < 16; ++kc) bs += *(const f32x4*)(bias_part + kc * 256 + n);
;     u32x2 v; v.x = pack2(gelu_tanh(a + bs[0]), gelu_tanh(b + bs[1])); v.y = pack2(gelu_tanh(c + bs[2]), gelu_tanh(d + bs[3]));
;     return v;
;   }
	v_pk_add_f32 v[68:69], v[92:93], 0 op_sel_hi:[1,0]
	v_cvt_pk_bf16_f32 v5, v6, v7
	s_waitcnt vmcnt(10)
	v_pk_add_f32 v[8:9], v[68:69], v[8:9]
	v_pk_add_f32 v[6:7], v[94:95], 0 op_sel_hi:[1,0]
	s_waitcnt vmcnt(9)
	v_pk_add_f32 v[8:9], v[8:9], v[32:33]
	v_pk_add_f32 v[6:7], v[6:7], v[10:11]
	s_waitcnt vmcnt(8)
	v_pk_add_f32 v[8:9], v[8:9], v[36:37]
	v_pk_add_f32 v[6:7], v[6:7], v[34:35]
	v_pk_add_f32 v[8:9], v[8:9], v[80:81]
	v_pk_add_f32 v[6:7], v[6:7], v[38:39]
	v_pk_add_f32 v[8:9], v[8:9], v[60:61]
	v_pk_add_f32 v[6:7], v[6:7], v[82:83]
	v_pk_add_f32 v[8:9], v[8:9], v[52:53]
	v_pk_add_f32 v[6:7], v[6:7], v[62:63]
	v_pk_add_f32 v[8:9], v[8:9], v[48:49]
	v_pk_add_f32 v[6:7], v[6:7], v[54:55]
	s_waitcnt vmcnt(7)
	v_pk_add_f32 v[8:9], v[8:9], v[16:17]
	v_pk_add_f32 v[6:7], v[6:7], v[50:51]
	s_waitcnt vmcnt(6)
	v_pk_add_f32 v[8:9], v[8:9], v[20:21]
	v_pk_add_f32 v[6:7], v[6:7], v[18:19]
	s_waitcnt vmcnt(5)
	v_pk_add_f32 v[8:9], v[8:9], v[24:25]
	v_pk_add_f32 v[6:7], v[6:7], v[22:23]
	s_waitcnt vmcnt(4)
	v_pk_add_f32 v[8:9], v[8:9], v[28:29]
	v_pk_add_f32 v[6:7], v[6:7], v[26:27]
	s_waitcnt vmcnt(3)
	v_pk_add_f32 v[8:9], v[8:9], v[40:41]
	v_pk_add_f32 v[6:7], v[6:7], v[30:31]
	s_waitcnt vmcnt(2)
	v_pk_add_f32 v[8:9], v[8:9], v[44:45]
	v_pk_add_f32 v[6:7], v[6:7], v[42:43]
	s_waitcnt vmcnt(1)
	v_pk_add_f32 v[8:9], v[8:9], v[56:57]
	v_pk_add_f32 v[6:7], v[6:7], v[46:47]
	s_waitcnt vmcnt(0)
	v_pk_add_f32 v[8:9], v[8:9], v[64:65]
	v_pk_add_f32 v[6:7], v[6:7], v[58:59]
	v_pk_add_f32 v[0:1], v[0:1], v[8:9]
	v_pk_add_f32 v[6:7], v[6:7], v[66:67]
	v_mul_f32_e32 v8, 0x3d372713, v0
	v_mul_f32_e32 v9, 0x3d372713, v1
	v_mul_f32_e32 v8, v0, v8
	v_mul_f32_e32 v9, v1, v9
	v_fma_f32 v8, v0, v8, v0
	v_fma_f32 v9, v1, v9, v1
	v_mul_f32_e32 v8, 0x3f4c422a, v8
	v_mul_f32_e32 v9, 0x3f4c422a, v9
	v_add_f32_e32 v8, v8, v8
	v_add_f32_e32 v9, v9, v9
	v_mul_f32_e32 v8, 0x3fb8aa3b, v8
	v_mul_f32_e32 v9, 0x3fb8aa3b, v9
	v_exp_f32_e32 v8, v8
	v_exp_f32_e32 v9, v9
	v_pk_add_f32 v[2:3], v[2:3], v[6:7]
	v_pk_mul_f32 v[0:1], v[0:1], 0.5 op_sel_hi:[1,0]
	v_pk_add_f32 v[8:9], v[8:9], 1.0 op_sel_hi:[1,0]
	s_nop 0
	v_div_scale_f32 v10, s[0:1], v9, v9, 2.0
	v_rcp_f32_e32 v11, v10
	s_nop 0
	v_fma_f32 v6, -v10, v11, 1.0
	v_fmac_f32_e32 v11, v6, v11
	v_div_scale_f32 v6, vcc, 2.0, v9, 2.0
	v_mul_f32_e32 v7, v6, v11
	v_fma_f32 v16, -v10, v7, v6
	v_fmac_f32_e32 v7, v16, v11
	v_fma_f32 v6, -v10, v7, v6
	v_div_scale_f32 v10, s[0:1], v8, v8, 2.0
	v_rcp_f32_e32 v16, v10
	v_div_fmas_f32 v6, v6, v11, v7
	v_div_fixup_f32 v7, v6, v9, 2.0
	v_fma_f32 v6, -v10, v16, 1.0
	v_fmac_f32_e32 v16, v6, v16
	v_div_scale_f32 v6, vcc, 2.0, v8, 2.0
	v_mul_f32_e32 v9, v6, v16
	v_fma_f32 v11, -v10, v9, v6
	v_fmac_f32_e32 v9, v11, v16
	v_fma_f32 v6, -v10, v9, v6
	v_div_fmas_f32 v6, v6, v16, v9
	v_mul_f32_e32 v9, 0x3d372713, v2
	v_mul_f32_e32 v9, v2, v9
	v_fma_f32 v9, v2, v9, v2
	v_mul_f32_e32 v9, 0x3f4c422a, v9
	v_add_f32_e32 v9, v9, v9
	v_mul_f32_e32 v9, 0x3fb8aa3b, v9
	v_exp_f32_e32 v10, v9
	v_mul_f32_e32 v9, 0x3d372713, v3
	v_mul_f32_e32 v9, v3, v9
	v_fma_f32 v9, v3, v9, v3
	v_mul_f32_e32 v9, 0x3f4c422a, v9
	v_add_f32_e32 v9, v9, v9
	v_mul_f32_e32 v9, 0x3fb8aa3b, v9
	v_exp_f32_e32 v11, v9
	v_div_fixup_f32 v6, v6, v8, 2.0
	v_pk_add_f32 v[6:7], v[6:7], 1.0 op_sel_hi:[1,0] neg_lo:[1,0] neg_hi:[1,0]
	v_pk_mul_f32 v[2:3], v[2:3], 0.5 op_sel_hi:[1,0]
	v_pk_add_f32 v[8:9], v[10:11], 1.0 op_sel_hi:[1,0]
	v_pk_add_f32 v[6:7], v[6:7], 1.0 op_sel_hi:[1,0]
	v_div_scale_f32 v10, s[0:1], v9, v9, 2.0
	v_rcp_f32_e32 v11, v10
	v_pk_mul_f32 v[0:1], v[0:1], v[6:7]
	s_nop 0
	v_cvt_pk_bf16_f32 v6, v0, v1
	v_fma_f32 v0, -v10, v11, 1.0
	v_fmac_f32_e32 v11, v0, v11
	v_div_scale_f32 v0, vcc, 2.0, v9, 2.0
	v_mul_f32_e32 v1, v0, v11
	v_fma_f32 v7, -v10, v1, v0
	v_fmac_f32_e32 v1, v7, v11
	v_div_scale_f32 v7, s[0:1], v8, v8, 2.0
	v_fma_f32 v0, -v10, v1, v0
	v_rcp_f32_e32 v10, v7
	v_div_fmas_f32 v0, v0, v11, v1
	v_div_fixup_f32 v1, v0, v9, 2.0
	v_permlane16_swap_b32_e32 v4, v6
	v_fma_f32 v0, -v7, v10, 1.0
	v_fmac_f32_e32 v10, v0, v10
	v_div_scale_f32 v0, vcc, 2.0, v8, 2.0
	v_mul_f32_e32 v9, v0, v10
	v_fma_f32 v11, -v7, v9, v0
	v_fmac_f32_e32 v9, v11, v10
	v_fma_f32 v0, -v7, v9, v0
	v_div_fmas_f32 v0, v0, v10, v9
	v_div_fixup_f32 v0, v0, v8, 2.0
	v_pk_add_f32 v[0:1], v[0:1], 1.0 op_sel_hi:[1,0] neg_lo:[1,0] neg_hi:[1,0]
	s_nop 0
	v_pk_add_f32 v[0:1], v[0:1], 1.0 op_sel_hi:[1,0]
	s_nop 0
	v_pk_mul_f32 v[0:1], v[2:3], v[0:1]
	s_nop 0
	v_cvt_pk_bf16_f32 v7, v0, v1
	v_or_b32_e32 v0, 48, v164
	v_ashrrev_i32_e32 v1, 31, v0
	v_lshlrev_b64 v[0:1], 9, v[0:1]
	v_lshl_add_u64 v[0:1], v[214:215], 0, v[0:1]
	v_lshl_add_u64 v[2:3], v[0:1], 0, v[166:167]
	v_permlane16_swap_b32_e32 v5, v7
	v_lshl_add_u64 v[0:1], v[0:1], 0, v[168:169]
	global_store_dwordx4 v[2:3], v[12:15], off
	global_store_dwordx4 v[0:1], v[4:7], off
	s_cbranch_scc1 .LBB0_677

; template <class ARow, class Epi>
; DI void gemm_tile(const ARow& arow, long a_kstride, const u16* __restrict__ Bt, long ldb, int K, int m0, int n0,
;                   const Epi& epi, char* smem) {
;     ...
;   const int KT = K >> 6;
;   GEMM_STAGE(0, 0);
;   asm volatile("s_waitcnt vmcnt(0)" ::: "memory");
;   __syncthreads();
;   for (int kt = 0; kt < KT; ++kt) {
;     const int cur = kt & 1;
;     if (kt + 1 < KT) GEMM_STAGE(cur ^ 1, kt + 1);
;     const char* sa = smem + cur * 32768 + wm * 64 * 128;
;     const char* sb = smem + cur * 32768 + 16384 + wn * 64 * 128;
; #pragma unroll
;     for (int ks = 0; ks < 2; ++ks) {
;       bf16x8 wf[4], af[4];
; #pragma unroll
;       for (int j = 0; j < 4; ++j) {
;         wf[j] = *(const bf16x8*)(sb + j * 2048 + foff[ks]);
;         af[j] = *(const bf16x8*)(sa + j * 2048 + foff[ks]);
;       }
; #pragma unroll
;       for (int ni = 0; ni < 4; ++ni)
; #pragma unroll
;         for (int mi = 0; mi < 4; ++mi) acc[ni][mi] = __builtin_amdgcn_mfma_f32_16x16x32_bf16(wf[ni], af[mi], acc[ni][mi], 0, 0, 0);
;     }
;     asm volatile("s_waitcnt vmcnt(0)" ::: "memory");
;     __syncthreads();
;   }
.LBB0_1045:
	s_and_b32 s20, s19, 0x8000
	s_xor_b32 s21, s20, 0x8000
	v_add_u32_e32 v108, s21, v88
	v_add_u32_e32 v91, s20, v89
	v_or_b32_e32 v116, s20, v90
	v_readfirstlane_b32 s20, v108
	v_add_u32_e32 v109, 0x4000, v108
	v_lshl_add_u64 v[92:93], v[66:67], 0, s[16:17]
	v_add_u32_e32 v110, 0x400, v108
	v_readfirstlane_b32 s21, v109
	s_mov_b32 m0, s20
	v_lshl_add_u64 v[94:95], v[68:69], 0, s[16:17]
	v_add_u32_e32 v111, 0x4400, v108
	v_readfirstlane_b32 s22, v110
	global_load_lds_dwordx4 v[92:93], off
	s_mov_b32 m0, s21
	v_lshl_add_u64 v[96:97], v[70:71], 0, s[16:17]
	v_add_u32_e32 v113, 0x800, v108
	v_readfirstlane_b32 s23, v111
	global_load_lds_dwordx4 v[94:95], off
	s_mov_b32 m0, s22
	v_lshl_add_u64 v[98:99], v[72:73], 0, s[16:17]
	v_add_u32_e32 v114, 0x4800, v108
	v_readfirstlane_b32 s24, v113
	global_load_lds_dwordx4 v[96:97], off
	s_mov_b32 m0, s23
	v_lshl_add_u64 v[100:101], v[74:75], 0, s[16:17]
	v_add_u32_e32 v115, 0xc00, v108
	v_readfirstlane_b32 s25, v114
	global_load_lds_dwordx4 v[98:99], off
	s_mov_b32 m0, s24
	v_lshl_add_u64 v[102:103], v[76:77], 0, s[16:17]
	v_add_u32_e32 v108, 0x4c00, v108
	v_readfirstlane_b32 s26, v115
	global_load_lds_dwordx4 v[100:101], off
	s_mov_b32 m0, s25
	v_lshl_add_u64 v[104:105], v[78:79], 0, s[16:17]
	v_readfirstlane_b32 s27, v108
	global_load_lds_dwordx4 v[102:103], off
	s_mov_b32 m0, s26
	v_lshl_add_u64 v[106:107], v[80:81], 0, s[16:17]
	global_load_lds_dwordx4 v[104:105], off
	s_mov_b32 m0, s27
	v_add_u32_e32 v117, v116, v87
	global_load_lds_dwordx4 v[106:107], off
	v_add_u32_e32 v112, v91, v87
	ds_read_b128 v[92:95], v117 offset:16384
	ds_read_b128 v[96:99], v112
	ds_read_b128 v[100:103], v117 offset:18432
	ds_read_b128 v[104:107], v112 offset:2048
	ds_read_b128 v[108:111], v112 offset:4096
	ds_read_b128 v[112:115], v112 offset:6144
	s_waitcnt lgkmcnt(0)
	v_mfma_f32_16x16x32_bf16 v[60:63], v[92:95], v[96:99], v[60:63]
	v_add_u32_e32 v116, v116, v86
	v_add_u32_e32 v91, v91, v86
	s_add_i32 s19, s19, 0x8000
	v_mfma_f32_16x16x32_bf16 v[56:59], v[92:95], v[104:107], v[56:59]
	s_add_u32 s16, s16, 0x80
	s_addc_u32 s17, s17, 0
	s_cmpk_lg_i32 s16, 0x780
	v_mfma_f32_16x16x32_bf16 v[52:55], v[92:95], v[108:111], v[52:55]
	v_mfma_f32_16x16x32_bf16 v[48:51], v[92:95], v[112:115], v[48:51]
	v_mfma_f32_16x16x32_bf16 v[44:47], v[100:103], v[96:99], v[44:47]
	v_mfma_f32_16x16x32_bf16 v[40:43], v[100:103], v[104:107], v[40:43]
	v_mfma_f32_16x16x32_bf16 v[36:39], v[100:103], v[108:111], v[36:39]
	v_mfma_f32_16x16x32_bf16 v[16:19], v[100:103], v[112:115], v[16:19]
	ds_read_b128 v[92:95], v117 offset:20480
	ds_read_b128 v[100:103], v117 offset:22528
	s_waitcnt lgkmcnt(1)
	v_mfma_f32_16x16x32_bf16 v[32:35], v[92:95], v[96:99], v[32:35]
	v_mfma_f32_16x16x32_bf16 v[12:15], v[92:95], v[104:107], v[12:15]
	v_mfma_f32_16x16x32_bf16 v[8:11], v[92:95], v[108:111], v[8:11]
	v_mfma_f32_16x16x32_bf16 v[4:7], v[92:95], v[112:115], v[4:7]
	ds_read_b128 v[92:95], v116 offset:16384
	s_waitcnt lgkmcnt(1)
	v_mfma_f32_16x16x32_bf16 v[24:27], v[100:103], v[96:99], v[24:27]
	v_mfma_f32_16x16x32_bf16 v[0:3], v[100:103], v[104:107], v[0:3]
	v_mfma_f32_16x16x32_bf16 v[28:31], v[100:103], v[108:111], v[28:31]
	v_mfma_f32_16x16x32_bf16 v[20:23], v[100:103], v[112:115], v[20:23]
	ds_read_b128 v[96:99], v91
	ds_read_b128 v[100:103], v116 offset:18432
	ds_read_b128 v[104:107], v91 offset:2048
	ds_read_b128 v[108:111], v91 offset:4096
	ds_read_b128 v[112:115], v91 offset:6144
	s_waitcnt lgkmcnt(4)
	v_mfma_f32_16x16x32_bf16 v[60:63], v[92:95], v[96:99], v[60:63]
	s_waitcnt lgkmcnt(2)
	v_mfma_f32_16x16x32_bf16 v[56:59], v[92:95], v[104:107], v[56:59]
	s_waitcnt lgkmcnt(1)
	v_mfma_f32_16x16x32_bf16 v[52:55], v[92:95], v[108:111], v[52:55]
	s_waitcnt lgkmcnt(0)
	v_mfma_f32_16x16x32_bf16 v[48:51], v[92:95], v[112:115], v[48:51]
	v_mfma_f32_16x16x32_bf16 v[44:47], v[100:103], v[96:99], v[44:47]
	v_mfma_f32_16x16x32_bf16 v[40:43], v[100:103], v[104:107], v[40:43]
	v_mfma_f32_16x16x32_bf16 v[36:39], v[100:103], v[108:111], v[36:39]
	v_mfma_f32_16x16x32_bf16 v[16:19], v[100:103], v[112:115], v[16:19]
	ds_read_b128 v[92:95], v116 offset:20480
	ds_read_b128 v[100:103], v116 offset:22528
	s_waitcnt lgkmcnt(0)
	s_waitcnt vmcnt(0)
	s_waitcnt vmcnt(0) lgkmcnt(0)
	v_mfma_f32_16x16x32_bf16 v[32:35], v[92:95], v[96:99], v[32:35]
	s_barrier
	v_mfma_f32_16x16x32_bf16 v[12:15], v[92:95], v[104:107], v[12:15]
	v_mfma_f32_16x16x32_bf16 v[8:11], v[92:95], v[108:111], v[8:11]
	v_mfma_f32_16x16x32_bf16 v[4:7], v[92:95], v[112:115], v[4:7]
	v_mfma_f32_16x16x32_bf16 v[24:27], v[100:103], v[96:99], v[24:27]
	v_mfma_f32_16x16x32_bf16 v[0:3], v[100:103], v[104:107], v[0:3]
	v_mfma_f32_16x16x32_bf16 v[28:31], v[100:103], v[108:111], v[28:31]
	v_mfma_f32_16x16x32_bf16 v[20:23], v[100:103], v[112:115], v[20:23]
	s_cbranch_scc1 .LBB0_1045
	v_add_u32_e32 v91, v90, v87
	ds_read_b128 v[66:69], v91 offset:49152
	v_add_u32_e32 v87, v89, v87
	ds_read_b128 v[70:73], v87 offset:32768
	ds_read_b128 v[74:77], v87 offset:34816
	ds_read_b128 v[78:81], v87 offset:36864
	ds_read_b128 v[92:95], v87 offset:38912
	v_add_u32_e32 v120, v89, v86
	v_add_u32_e32 v90, v90, v86
	v_or_b32_e32 v64, s1, v64
	s_waitcnt lgkmcnt(3)
	v_mfma_f32_16x16x32_bf16 v[60:63], v[66:69], v[70:73], v[60:63]
	s_waitcnt lgkmcnt(2)
	v_mfma_f32_16x16x32_bf16 v[56:59], v[66:69], v[74:77], v[56:59]
	s_waitcnt lgkmcnt(1)
	v_mfma_f32_16x16x32_bf16 v[52:55], v[66:69], v[78:81], v[52:55]
	s_waitcnt lgkmcnt(0)
	v_mfma_f32_16x16x32_bf16 v[48:51], v[66:69], v[92:95], v[48:51]
	ds_read_b128 v[66:69], v91 offset:51200
	ds_read_b128 v[86:89], v120 offset:38912
	ds_read_b128 v[96:99], v120 offset:36864
	ds_read_b128 v[100:103], v91 offset:55296
	ds_read_b128 v[104:107], v91 offset:53248
	ds_read_b128 v[108:111], v90 offset:55296
	ds_read_b128 v[112:115], v90 offset:53248
	ds_read_b128 v[116:119], v120 offset:34816
	ds_read_b128 v[120:123], v120 offset:32768
	ds_read_b128 v[124:127], v90 offset:51200
	ds_read_b128 v[128:131], v90 offset:49152
	s_waitcnt lgkmcnt(6)
	v_mfma_f32_16x16x32_bf16 v[32:35], v[104:107], v[70:73], v[32:35]
	s_waitcnt lgkmcnt(0)
	s_waitcnt vmcnt(0)
	s_waitcnt lgkmcnt(0)
	s_barrier
; DI int lbid() { int x = blockIdx.x; asm volatile("" : "+s"(x)); return x; }
;   DI u32x2 pack(int, int, float a, float b, float c, float d, float&) const { u32x2 v; v.x = pack2(a, b); v.y = pack2(c, d); return v; }
; template <class ARow, class Epi>
; DI void gemm_tile(const ARow& arow, long a_kstride, const u16* __restrict__ Bt, long ldb, int K, int m0, int n0,
;                   const Epi& epi, char* smem) {
;     ...
;         for (int mi = 0; mi < 4; ++mi) acc[ni][mi] = __builtin_amdgcn_mfma_f32_16x16x32_bf16(wf[ni], af[mi], acc[ni][mi], 0, 0, 0);
;     }
;     asm volatile("s_waitcnt vmcnt(0)" ::: "memory");
;     __syncthreads();
;   }
;     ...
;   const int nh = n0 + wn * 64;
;   if (epi.packed(nh)) {
; #pragma unroll
;     for (int mi = 0; mi < 4; ++mi) {
;       const int m = m0 + wm * 64 + mi * 16 + fr;
;       float ss = 0.f;
;       u32x2 pk[4];
; #pragma unroll
;       for (int ni = 0; ni < 4; ++ni) pk[ni] = epi.pack(m, nh + ni * 16 + fq * 4, acc[ni][mi][0], acc[ni][mi][1], acc[ni][mi][2], acc[ni][mi][3], ss);
;       epi.finish16(m, nh, ss);
;       u16* rp = epi.rowp(m) + nh;
; #pragma unroll
;       for (int pp = 0; pp < 2; ++pp) {
;         u32x2 a = pk[2 * pp], b = pk[2 * pp + 1];
;         const u32x2 rx = __builtin_amdgcn_permlane16_swap(a.x, b.x, false, false);
;         const u32x2 ry = __builtin_amdgcn_permlane16_swap(a.y, b.y, false, false);
;         const int nst = (fq & 1) ? ((2 * pp + 1) * 16 + (fq - 1) * 4) : ((2 * pp) * 16 + fq * 4);
;         *(u32x4*)(rp + nst) = (u32x4){rx[0], ry[0], rx[1], ry[1]};
;       }
; template <class Epi>
; DI void gemm_phase_plain(const u16* A, long lda, const u16* Bt, long ldb, int M, int N, int K, const Epi& epi, char* smem) {
;     ...
;   for (int t = lbid(); t < nwg; t += gridDim.x) {
;     const int xcd = t & 7, off = t >> 3;
;     const int wg = (xcd < rr ? xcd * (q + 1) : rr * (q + 1) + (xcd - rr) * q) + off;
;     const int nig = 8 * MT, gid = wg / nig, fm = gid * 8, gsz = (NT - fm) < 8 ? (NT - fm) : 8;
;     const int nt = fm + (wg % nig) % gsz, mt = (wg % nig) / gsz;
;     gemm_tile(ar, 64, Bt, ldb, K, mt * 128, nt * 128, epi, smem);
	v_mfma_f32_16x16x32_bf16 v[24:27], v[100:103], v[70:73], v[24:27]
	v_mfma_f32_16x16x32_bf16 v[44:47], v[66:69], v[70:73], v[44:47]
	v_lshl_add_u32 v72, v85, 6, v64
	v_lshl_or_b32 v70, v84, 6, s18
	v_ashrrev_i32_e32 v73, 31, v72
	v_mfma_f32_16x16x32_bf16 v[32:35], v[112:115], v[120:123], v[32:35]
	v_ashrrev_i32_e32 v71, 31, v70
	v_and_b32_e32 v64, 16, v82
	v_lshlrev_b32_e32 v82, 2, v83
	v_mfma_f32_16x16x32_bf16 v[24:27], v[108:111], v[120:123], v[24:27]
	v_cmp_eq_u32_e32 vcc, 0, v64
	s_nop 2
	v_cvt_pk_bf16_f32 v32, v32, v33
	v_cvt_pk_bf16_f32 v33, v34, v35
	v_mfma_f32_16x16x32_bf16 v[60:63], v[128:131], v[120:123], v[60:63]
	v_mfma_f32_16x16x32_bf16 v[44:47], v[124:127], v[120:123], v[44:47]
	v_cvt_pk_bf16_f32 v34, v24, v25
	v_lshlrev_b64 v[24:25], 11, v[72:73]
	s_nop 4
	v_cvt_pk_bf16_f32 v60, v60, v61
	v_cvt_pk_bf16_f32 v61, v62, v63
	v_lshl_add_u64 v[24:25], s[6:7], 0, v[24:25]
	v_cvt_pk_bf16_f32 v62, v44, v45
	v_lshlrev_b64 v[44:45], 1, v[70:71]
	v_cvt_pk_bf16_f32 v63, v46, v47
	v_lshl_add_u64 v[46:47], v[24:25], 0, v[44:45]
	v_add_u32_e32 v24, 12, v82
	v_cndmask_b32_e32 v24, v24, v82, vcc
	v_lshlrev_b32_e32 v64, 1, v24
	v_permlane16_swap_b32_e32 v60, v62
	v_permlane16_swap_b32_e32 v61, v63
	v_lshl_add_u64 v[24:25], v[46:47], 0, v[64:65]
	v_mfma_f32_16x16x32_bf16 v[40:43], v[66:69], v[74:77], v[40:43]
	v_cvt_pk_bf16_f32 v35, v26, v27
	global_store_dwordx4 v[24:25], v[60:63], off
	v_permlane16_swap_b32_e32 v32, v34
	v_mfma_f32_16x16x32_bf16 v[24:27], v[100:103], v[78:81], v[28:31]
	v_mov_b32_e32 v61, v65
	v_permlane16_swap_b32_e32 v33, v35
	s_nop 0
	v_add_u32_e32 v28, 44, v82
	v_or_b32_e32 v29, 32, v82
	v_cndmask_b32_e32 v28, v28, v29, vcc
	v_lshlrev_b32_e32 v60, 1, v28
	v_lshl_add_u64 v[46:47], v[46:47], 0, v[60:61]
	v_mfma_f32_16x16x32_bf16 v[28:31], v[128:131], v[116:119], v[56:59]
	global_store_dwordx4 v[46:47], v[32:35], off
	s_nop 1
	v_mfma_f32_16x16x32_bf16 v[32:35], v[124:127], v[116:119], v[40:43]
	v_mfma_f32_16x16x32_bf16 v[12:15], v[104:107], v[74:77], v[12:15]
	s_nop 2
	v_cvt_pk_bf16_f32 v28, v28, v29
	v_cvt_pk_bf16_f32 v29, v30, v31
	s_nop 1
	v_cvt_pk_bf16_f32 v30, v32, v33
	v_mfma_f32_16x16x32_bf16 v[0:3], v[100:103], v[74:77], v[0:3]
	v_or_b32_e32 v32, 16, v72
	v_ashrrev_i32_e32 v33, 31, v32
	v_lshlrev_b64 v[32:33], 11, v[32:33]
	v_mfma_f32_16x16x32_bf16 v[12:15], v[112:115], v[116:119], v[12:15]
	v_lshl_add_u64 v[40:41], s[6:7], 0, v[32:33]
	v_cvt_pk_bf16_f32 v31, v34, v35
	v_lshl_add_u64 v[40:41], v[40:41], 0, v[44:45]
	v_mfma_f32_16x16x32_bf16 v[0:3], v[108:111], v[116:119], v[0:3]
	v_permlane16_swap_b32_e32 v28, v30
	s_nop 2
	v_cvt_pk_bf16_f32 v12, v12, v13
	v_mfma_f32_16x16x32_bf16 v[8:11], v[104:107], v[78:81], v[8:11]
	v_cvt_pk_bf16_f32 v13, v14, v15
	s_nop 0
	v_cvt_pk_bf16_f32 v14, v0, v1
	v_cvt_pk_bf16_f32 v15, v2, v3
	v_permlane16_swap_b32_e32 v29, v31
	v_lshl_add_u64 v[42:43], v[40:41], 0, v[64:65]
	global_store_dwordx4 v[42:43], v[28:31], off
	v_permlane16_swap_b32_e32 v12, v14
	v_permlane16_swap_b32_e32 v13, v15
	v_lshl_add_u64 v[28:29], v[40:41], 0, v[60:61]
	v_mfma_f32_16x16x32_bf16 v[36:39], v[66:69], v[78:81], v[36:39]
	global_store_dwordx4 v[28:29], v[12:15], off
	v_mfma_f32_16x16x32_bf16 v[8:11], v[112:115], v[96:99], v[8:11]
	s_nop 0
	v_mfma_f32_16x16x32_bf16 v[12:15], v[108:111], v[96:99], v[24:27]
	v_mfma_f32_16x16x32_bf16 v[0:3], v[128:131], v[96:99], v[52:55]
	s_nop 4
	v_cvt_pk_bf16_f32 v8, v8, v9
	v_cvt_pk_bf16_f32 v9, v10, v11
	v_cvt_pk_bf16_f32 v10, v12, v13
	v_mfma_f32_16x16x32_bf16 v[36:39], v[124:127], v[96:99], v[36:39]
	v_or_b32_e32 v12, 32, v72
	v_ashrrev_i32_e32 v13, 31, v12
	v_lshlrev_b64 v[12:13], 11, v[12:13]
	v_mfma_f32_16x16x32_bf16 v[16:19], v[66:69], v[92:95], v[16:19]
	v_lshl_add_u64 v[12:13], s[6:7], 0, v[12:13]
	v_cvt_pk_bf16_f32 v0, v0, v1
	v_cvt_pk_bf16_f32 v1, v2, v3
	v_mfma_f32_16x16x32_bf16 v[4:7], v[104:107], v[92:95], v[4:7]
	v_cvt_pk_bf16_f32 v2, v36, v37
	v_cvt_pk_bf16_f32 v3, v38, v39
	v_lshl_add_u64 v[12:13], v[12:13], 0, v[44:45]
	v_mfma_f32_16x16x32_bf16 v[20:23], v[100:103], v[92:95], v[20:23]
	v_cvt_pk_bf16_f32 v11, v14, v15
	v_permlane16_swap_b32_e32 v0, v2
	v_permlane16_swap_b32_e32 v1, v3
	v_lshl_add_u64 v[14:15], v[12:13], 0, v[64:65]
	global_store_dwordx4 v[14:15], v[0:3], off
	v_permlane16_swap_b32_e32 v8, v10
	v_permlane16_swap_b32_e32 v9, v11
	v_lshl_add_u64 v[0:1], v[12:13], 0, v[60:61]
	v_mfma_f32_16x16x32_bf16 v[32:35], v[128:131], v[86:89], v[48:51]
	global_store_dwordx4 v[0:1], v[8:11], off
	v_mfma_f32_16x16x32_bf16 v[16:19], v[124:127], v[86:89], v[16:19]
	s_nop 0
	v_or_b32_e32 v8, 48, v72
	v_ashrrev_i32_e32 v9, 31, v8
	v_lshlrev_b64 v[8:9], 11, v[8:9]
	v_mfma_f32_16x16x32_bf16 v[4:7], v[112:115], v[86:89], v[4:7]
	v_lshl_add_u64 v[8:9], s[6:7], 0, v[8:9]
	v_cvt_pk_bf16_f32 v0, v32, v33
	v_cvt_pk_bf16_f32 v1, v34, v35
	v_mfma_f32_16x16x32_bf16 v[20:23], v[108:111], v[86:89], v[20:23]
	v_cvt_pk_bf16_f32 v2, v16, v17
	v_cvt_pk_bf16_f32 v3, v18, v19
	v_lshl_add_u64 v[8:9], v[8:9], 0, v[44:45]
	s_nop 0
	v_cvt_pk_bf16_f32 v4, v4, v5
	v_cvt_pk_bf16_f32 v5, v6, v7
	s_nop 1
	v_cvt_pk_bf16_f32 v6, v20, v21
	v_cvt_pk_bf16_f32 v7, v22, v23
	v_permlane16_swap_b32_e32 v0, v2
	v_permlane16_swap_b32_e32 v1, v3
	v_lshl_add_u64 v[10:11], v[8:9], 0, v[64:65]
	global_store_dwordx4 v[10:11], v[0:3], off
	v_permlane16_swap_b32_e32 v4, v6
	v_permlane16_swap_b32_e32 v5, v7
	v_lshl_add_u64 v[0:1], v[8:9], 0, v[60:61]
	global_store_dwordx4 v[0:1], v[4:7], off
	s_load_dword s1, s[10:11], 0x0
	s_waitcnt lgkmcnt(0)
	s_add_i32 s0, s1, s0
	s_cmpk_lt_i32 s0, 0x400
	s_cbranch_scc1 .LBB0_1044

; template <class ARow, class Epi>
; DI void gemm_tile(const ARow& arow, long a_kstride, const u16* __restrict__ Bt, long ldb, int K, int m0, int n0,
;                   const Epi& epi, char* smem) {
;     ...
;   const int KT = K >> 6;
;   GEMM_STAGE(0, 0);
;   asm volatile("s_waitcnt vmcnt(0)" ::: "memory");
;   __syncthreads();
;   for (int kt = 0; kt < KT; ++kt) {
;     const int cur = kt & 1;
;     if (kt + 1 < KT) GEMM_STAGE(cur ^ 1, kt + 1);
;     const char* sa = smem + cur * 32768 + wm * 64 * 128;
;     const char* sb = smem + cur * 32768 + 16384 + wn * 64 * 128;
; #pragma unroll
;     for (int ks = 0; ks < 2; ++ks) {
;       bf16x8 wf[4], af[4];
; #pragma unroll
;       for (int j = 0; j < 4; ++j) {
;         wf[j] = *(const bf16x8*)(sb + j * 2048 + foff[ks]);
;         af[j] = *(const bf16x8*)(sa + j * 2048 + foff[ks]);
;       }
; #pragma unroll
;       for (int ni = 0; ni < 4; ++ni)
; #pragma unroll
;         for (int mi = 0; mi < 4; ++mi) acc[ni][mi] = __builtin_amdgcn_mfma_f32_16x16x32_bf16(wf[ni], af[mi], acc[ni][mi], 0, 0, 0);
;     }
;     asm volatile("s_waitcnt vmcnt(0)" ::: "memory");
;     __syncthreads();
;   }
.LBB0_1173:
	s_and_b32 s6, s1, 0x8000
	s_xor_b32 s7, s6, 0x8000
	v_add_u32_e32 v108, s7, v91
	v_add_u32_e32 v116, s6, v89
	v_or_b32_e32 v117, s6, v90
	v_readfirstlane_b32 s6, v108
	v_add_u32_e32 v109, 0x4000, v108
	v_lshl_add_u64 v[92:93], v[66:67], 0, s[4:5]
	v_add_u32_e32 v110, 0x400, v108
	v_readfirstlane_b32 s7, v109
	s_mov_b32 m0, s6
	v_lshl_add_u64 v[94:95], v[68:69], 0, s[4:5]
	v_add_u32_e32 v111, 0x4400, v108
	v_readfirstlane_b32 s8, v110
	global_load_lds_dwordx4 v[92:93], off
	s_mov_b32 m0, s7
	v_lshl_add_u64 v[96:97], v[70:71], 0, s[4:5]
	v_add_u32_e32 v113, 0x800, v108
	v_readfirstlane_b32 s9, v111
	global_load_lds_dwordx4 v[94:95], off
	s_mov_b32 m0, s8
	v_lshl_add_u64 v[98:99], v[72:73], 0, s[4:5]
	v_add_u32_e32 v114, 0x4800, v108
	v_readfirstlane_b32 s10, v113
	global_load_lds_dwordx4 v[96:97], off
	s_mov_b32 m0, s9
	v_lshl_add_u64 v[100:101], v[74:75], 0, s[4:5]
	v_add_u32_e32 v115, 0xc00, v108
	v_readfirstlane_b32 s11, v114
	global_load_lds_dwordx4 v[98:99], off
	s_mov_b32 m0, s10
	v_lshl_add_u64 v[102:103], v[76:77], 0, s[4:5]
	v_add_u32_e32 v108, 0x4c00, v108
	v_readfirstlane_b32 s12, v115
	global_load_lds_dwordx4 v[100:101], off
	s_mov_b32 m0, s11
	v_lshl_add_u64 v[104:105], v[78:79], 0, s[4:5]
	v_readfirstlane_b32 s13, v108
	global_load_lds_dwordx4 v[102:103], off
	s_mov_b32 m0, s12
	v_lshl_add_u64 v[106:107], v[80:81], 0, s[4:5]
	global_load_lds_dwordx4 v[104:105], off
	s_mov_b32 m0, s13
	v_add_u32_e32 v118, v117, v88
	global_load_lds_dwordx4 v[106:107], off
	v_add_u32_e32 v112, v116, v88
	ds_read_b128 v[92:95], v118 offset:16384
	ds_read_b128 v[96:99], v112
	ds_read_b128 v[100:103], v118 offset:18432
	ds_read_b128 v[104:107], v112 offset:2048
	ds_read_b128 v[108:111], v112 offset:4096
	ds_read_b128 v[112:115], v112 offset:6144
	s_waitcnt lgkmcnt(0)
	v_mfma_f32_16x16x32_bf16 v[60:63], v[92:95], v[96:99], v[60:63]
	v_add_u32_e32 v117, v117, v87
	v_add_u32_e32 v116, v116, v87
	s_add_i32 s1, s1, 0x8000
	v_mfma_f32_16x16x32_bf16 v[56:59], v[92:95], v[104:107], v[56:59]
	s_add_u32 s4, s4, 0x80
	s_addc_u32 s5, s5, 0
	s_cmpk_eq_i32 s4, 0x780
	v_mfma_f32_16x16x32_bf16 v[48:51], v[92:95], v[108:111], v[48:51]
	v_mfma_f32_16x16x32_bf16 v[40:43], v[92:95], v[112:115], v[40:43]
	v_mfma_f32_16x16x32_bf16 v[36:39], v[100:103], v[96:99], v[36:39]
	v_mfma_f32_16x16x32_bf16 v[32:35], v[100:103], v[104:107], v[32:35]
	v_mfma_f32_16x16x32_bf16 v[28:31], v[100:103], v[108:111], v[28:31]
	v_mfma_f32_16x16x32_bf16 v[24:27], v[100:103], v[112:115], v[24:27]
	ds_read_b128 v[92:95], v118 offset:20480
	ds_read_b128 v[100:103], v118 offset:22528
	s_waitcnt lgkmcnt(1)
	v_mfma_f32_16x16x32_bf16 v[20:23], v[92:95], v[96:99], v[20:23]
	v_mfma_f32_16x16x32_bf16 v[16:19], v[92:95], v[104:107], v[16:19]
	v_mfma_f32_16x16x32_bf16 v[12:15], v[92:95], v[108:111], v[12:15]
	v_mfma_f32_16x16x32_bf16 v[8:11], v[92:95], v[112:115], v[8:11]
	ds_read_b128 v[92:95], v117 offset:16384
	s_waitcnt lgkmcnt(1)
	v_mfma_f32_16x16x32_bf16 v[4:7], v[100:103], v[96:99], v[4:7]
	v_mfma_f32_16x16x32_bf16 v[0:3], v[100:103], v[104:107], v[0:3]
	v_mfma_f32_16x16x32_bf16 v[52:55], v[100:103], v[108:111], v[52:55]
	v_mfma_f32_16x16x32_bf16 v[44:47], v[100:103], v[112:115], v[44:47]
	ds_read_b128 v[96:99], v116
	ds_read_b128 v[100:103], v117 offset:18432
	ds_read_b128 v[104:107], v116 offset:2048
	ds_read_b128 v[108:111], v116 offset:4096
	ds_read_b128 v[112:115], v116 offset:6144
	s_waitcnt lgkmcnt(4)
	v_mfma_f32_16x16x32_bf16 v[60:63], v[92:95], v[96:99], v[60:63]
	s_waitcnt lgkmcnt(2)
	v_mfma_f32_16x16x32_bf16 v[56:59], v[92:95], v[104:107], v[56:59]
	s_waitcnt lgkmcnt(1)
	v_mfma_f32_16x16x32_bf16 v[48:51], v[92:95], v[108:111], v[48:51]
	s_waitcnt lgkmcnt(0)
	v_mfma_f32_16x16x32_bf16 v[40:43], v[92:95], v[112:115], v[40:43]
	v_mfma_f32_16x16x32_bf16 v[36:39], v[100:103], v[96:99], v[36:39]
	v_mfma_f32_16x16x32_bf16 v[32:35], v[100:103], v[104:107], v[32:35]
	v_mfma_f32_16x16x32_bf16 v[28:31], v[100:103], v[108:111], v[28:31]
	v_mfma_f32_16x16x32_bf16 v[24:27], v[100:103], v[112:115], v[24:27]
	ds_read_b128 v[92:95], v117 offset:20480
	ds_read_b128 v[100:103], v117 offset:22528
	s_waitcnt lgkmcnt(0)
	s_waitcnt vmcnt(0)
	s_waitcnt vmcnt(0) lgkmcnt(0)
	v_mfma_f32_16x16x32_bf16 v[20:23], v[92:95], v[96:99], v[20:23]
	s_barrier
	v_mfma_f32_16x16x32_bf16 v[16:19], v[92:95], v[104:107], v[16:19]
	v_mfma_f32_16x16x32_bf16 v[12:15], v[92:95], v[108:111], v[12:15]
	v_mfma_f32_16x16x32_bf16 v[8:11], v[92:95], v[112:115], v[8:11]
	v_mfma_f32_16x16x32_bf16 v[4:7], v[100:103], v[96:99], v[4:7]
	v_mfma_f32_16x16x32_bf16 v[0:3], v[100:103], v[104:107], v[0:3]
	v_mfma_f32_16x16x32_bf16 v[52:55], v[100:103], v[108:111], v[52:55]
	v_mfma_f32_16x16x32_bf16 v[44:47], v[100:103], v[112:115], v[44:47]
	s_cbranch_scc0 .LBB0_1173
; DI unsigned pack2(float a, float b) { v2f f = {a, b}; return __builtin_bit_cast(unsigned, __builtin_convertvector(f, v2bf)); }
; DI float silu_f(float v) { return v / (1.f + fexp(-v)); }
;   DI u32x2 pack(int, int, float a, float b, float c, float d, float&) const { u32x2 v; v.x = pack2(a, b); v.y = pack2(c, d); return v; }
; template <class ARow, class Epi>
; DI void gemm_tile(const ARow& arow, long a_kstride, const u16* __restrict__ Bt, long ldb, int K, int m0, int n0,
;                   const Epi& epi, char* smem) {
;     ...
;         for (int mi = 0; mi < 4; ++mi) acc[ni][mi] = __builtin_amdgcn_mfma_f32_16x16x32_bf16(wf[ni], af[mi], acc[ni][mi], 0, 0, 0);
;     }
;     asm volatile("s_waitcnt vmcnt(0)" ::: "memory");
;     __syncthreads();
;   }
;     ...
;   const int nh = n0 + wn * 64;
;   if (epi.packed(nh)) {
; #pragma unroll
;     for (int mi = 0; mi < 4; ++mi) {
;       const int m = m0 + wm * 64 + mi * 16 + fr;
;       float ss = 0.f;
;       u32x2 pk[4];
; #pragma unroll
;       for (int ni = 0; ni < 4; ++ni) pk[ni] = epi.pack(m, nh + ni * 16 + fq * 4, acc[ni][mi][0], acc[ni][mi][1], acc[ni][mi][2], acc[ni][mi][3], ss);
;       epi.finish16(m, nh, ss);
;       u16* rp = epi.rowp(m) + nh;
; #pragma unroll
;       for (int pp = 0; pp < 2; ++pp) {
;         u32x2 a = pk[2 * pp], b = pk[2 * pp + 1];
;         const u32x2 rx = __builtin_amdgcn_permlane16_swap(a.x, b.x, false, false);
;         const u32x2 ry = __builtin_amdgcn_permlane16_swap(a.y, b.y, false, false);
;         const int nst = (fq & 1) ? ((2 * pp + 1) * 16 + (fq - 1) * 4) : ((2 * pp) * 16 + fq * 4);
;         *(u32x4*)(rp + nst) = (u32x4){rx[0], ry[0], rx[1], ry[1]};
;       }
;   DI u32x2 pack(int m, int n, float a, float b, float c, float d, float& ss) const {
;     if (n < q_end) { a *= qscale; b *= qscale; c *= qscale; d *= qscale; }
;     else if (n >= z_start) { a = silu_f(a); b = silu_f(b); c = silu_f(c); d = silu_f(d); }
;     ss += a * a + b * b + c * c + d * d;
;     u32x2 v; v.x = pack2(a, b); v.y = pack2(c, d);
;     return v;
;   }
	v_add_u32_e32 v91, v90, v88
	ds_read_b128 v[66:69], v91 offset:49152
	v_add_u32_e32 v88, v89, v88
	ds_read_b128 v[70:73], v88 offset:32768
	ds_read_b128 v[74:77], v88 offset:34816
	ds_read_b128 v[78:81], v88 offset:36864
	ds_read_b128 v[92:95], v88 offset:38912
	v_add_u32_e32 v116, v90, v87
	s_waitcnt lgkmcnt(3)
	v_mfma_f32_16x16x32_bf16 v[60:63], v[66:69], v[70:73], v[60:63]
	s_waitcnt lgkmcnt(2)
	v_mfma_f32_16x16x32_bf16 v[56:59], v[66:69], v[74:77], v[56:59]
	s_waitcnt lgkmcnt(1)
	v_mfma_f32_16x16x32_bf16 v[48:51], v[66:69], v[78:81], v[48:51]
	s_waitcnt lgkmcnt(0)
	v_mfma_f32_16x16x32_bf16 v[40:43], v[66:69], v[92:95], v[40:43]
	ds_read_b128 v[66:69], v91 offset:51200
	s_waitcnt lgkmcnt(0)
	v_mfma_f32_16x16x32_bf16 v[36:39], v[66:69], v[70:73], v[36:39]
	v_mfma_f32_16x16x32_bf16 v[32:35], v[66:69], v[74:77], v[32:35]
	v_mfma_f32_16x16x32_bf16 v[96:99], v[66:69], v[78:81], v[28:31]
	v_mfma_f32_16x16x32_bf16 v[66:69], v[66:69], v[92:95], v[24:27]
	s_nop 2
	ds_read_b128 v[24:27], v91 offset:53248
	s_waitcnt lgkmcnt(0)
	v_mfma_f32_16x16x32_bf16 v[104:107], v[24:27], v[92:95], v[8:11]
	s_nop 2
	ds_read_b128 v[8:11], v91 offset:55296
	v_mfma_f32_16x16x32_bf16 v[20:23], v[24:27], v[70:73], v[20:23]
	s_waitcnt lgkmcnt(0)
	v_mfma_f32_16x16x32_bf16 v[70:73], v[8:11], v[70:73], v[4:7]
	s_nop 2
	ds_read_b128 v[4:7], v116 offset:49152
	v_mfma_f32_16x16x32_bf16 v[100:103], v[24:27], v[78:81], v[12:15]
	s_nop 2
	v_add_u32_e32 v12, v89, v87
	v_mfma_f32_16x16x32_bf16 v[16:19], v[24:27], v[74:77], v[16:19]
	ds_read_b128 v[88:91], v12 offset:32768
	ds_read_b128 v[108:111], v12 offset:36864
	ds_read_b128 v[112:115], v12 offset:38912
	v_mfma_f32_16x16x32_bf16 v[0:3], v[8:11], v[74:77], v[0:3]
	v_mfma_f32_16x16x32_bf16 v[74:77], v[8:11], v[78:81], v[52:55]
	v_mfma_f32_16x16x32_bf16 v[78:81], v[8:11], v[92:95], v[44:47]
	ds_read_b128 v[92:95], v12 offset:34816
	s_waitcnt lgkmcnt(3)
	v_mfma_f32_16x16x32_bf16 v[60:63], v[4:7], v[88:91], v[60:63]
	s_waitcnt lgkmcnt(0)
	v_mfma_f32_16x16x32_bf16 v[44:47], v[4:7], v[92:95], v[56:59]
	v_mfma_f32_16x16x32_bf16 v[28:31], v[4:7], v[108:111], v[48:51]
	v_mfma_f32_16x16x32_bf16 v[12:15], v[4:7], v[112:115], v[40:43]
	ds_read_b128 v[4:7], v116 offset:51200
	s_waitcnt lgkmcnt(0)
	v_mfma_f32_16x16x32_bf16 v[56:59], v[4:7], v[88:91], v[36:39]
	v_mfma_f32_16x16x32_bf16 v[40:43], v[4:7], v[92:95], v[32:35]
	v_mfma_f32_16x16x32_bf16 v[24:27], v[4:7], v[108:111], v[96:99]
	v_mfma_f32_16x16x32_bf16 v[8:11], v[4:7], v[112:115], v[66:69]
	ds_read_b128 v[4:7], v116 offset:53248
	s_nop 0
	ds_read_b128 v[96:99], v116 offset:55296
	s_waitcnt lgkmcnt(0)
	s_waitcnt vmcnt(0)
	s_waitcnt lgkmcnt(0)
	v_mfma_f32_16x16x32_bf16 v[32:35], v[96:99], v[92:95], v[0:3]
	s_nop 2
	v_or_b32_e32 v0, s0, v64
	v_lshl_add_u32 v66, v86, 6, v0
	v_lshl_or_b32 v68, v85, 6, s38
	v_mfma_f32_16x16x32_bf16 v[52:55], v[4:7], v[88:91], v[20:23]
	v_cmp_lt_i32_e32 vcc, s33, v68
	s_barrier
	v_mfma_f32_16x16x32_bf16 v[36:39], v[4:7], v[92:95], v[16:19]
	v_mfma_f32_16x16x32_bf16 v[20:23], v[4:7], v[108:111], v[100:103]
	v_mfma_f32_16x16x32_bf16 v[4:7], v[4:7], v[112:115], v[104:107]
	v_mfma_f32_16x16x32_bf16 v[48:51], v[96:99], v[88:91], v[70:73]
	v_mfma_f32_16x16x32_bf16 v[16:19], v[96:99], v[108:111], v[74:77]
	s_nop 1
	v_lshlrev_b32_e32 v72, 2, v84
	v_or_b32_e32 v64, v68, v72
	v_mfma_f32_16x16x32_bf16 v[0:3], v[96:99], v[112:115], v[78:81]
	s_nop 7
	v_readfirstlane_b32 s99, v68
	s_cmpk_ge_u32 s99, 0x800
	s_cbranch_scc0 .Lfe_B_not_plain
	s_cmpk_lt_u32 s99, 0xc00
	s_cbranch_scc0 .Lfe_B_not_plain
	s_load_dwordx2 s[100:101], s[56:57], 0x130
	v_and_b32_e32 v152, 1, v84
	v_mul_u32_u24_e32 v152, 12, v152
	v_lshl_add_u32 v152, v84, 2, v152
	v_add_u32_e32 v152, v152, v68
	v_lshl_add_u32 v152, v66, 12, v152
	v_lshlrev_b32_e32 v152, 1, v152
	v_add_u32_e32 v153, 0x20000, v152
	v_add_u32_e32 v154, 0x40000, v152
	v_add_u32_e32 v155, 0x60000, v152
	s_nop 3
	v_cvt_pk_bf16_f32 v120, v60, v61
	v_cvt_pk_bf16_f32 v121, v62, v63
	v_cvt_pk_bf16_f32 v122, v56, v57
	v_cvt_pk_bf16_f32 v123, v58, v59
	v_cvt_pk_bf16_f32 v124, v52, v53
	v_cvt_pk_bf16_f32 v125, v54, v55
	v_cvt_pk_bf16_f32 v126, v48, v49
	v_cvt_pk_bf16_f32 v127, v50, v51
	s_nop 1
	v_permlane16_swap_b32_e32 v120, v122
	v_permlane16_swap_b32_e32 v121, v123
	v_permlane16_swap_b32_e32 v124, v126
	v_permlane16_swap_b32_e32 v125, v127
	s_waitcnt lgkmcnt(0)
	global_store_dwordx4 v152, v[120:123], s[100:101]
	global_store_dwordx4 v152, v[124:127], s[100:101] offset:64
	v_cvt_pk_bf16_f32 v128, v44, v45
	v_cvt_pk_bf16_f32 v129, v46, v47
	v_cvt_pk_bf16_f32 v130, v40, v41
	v_cvt_pk_bf16_f32 v131, v42, v43
	v_cvt_pk_bf16_f32 v132, v36, v37
	v_cvt_pk_bf16_f32 v133, v38, v39
	v_cvt_pk_bf16_f32 v134, v32, v33
	v_cvt_pk_bf16_f32 v135, v34, v35
	s_nop 1
	v_permlane16_swap_b32_e32 v128, v130
	v_permlane16_swap_b32_e32 v129, v131
	v_permlane16_swap_b32_e32 v132, v134
	v_permlane16_swap_b32_e32 v133, v135
	global_store_dwordx4 v153, v[128:131], s[100:101]
	global_store_dwordx4 v153, v[132:135], s[100:101] offset:64
	v_cvt_pk_bf16_f32 v136, v28, v29
	v_cvt_pk_bf16_f32 v137, v30, v31
	v_cvt_pk_bf16_f32 v138, v24, v25
	v_cvt_pk_bf16_f32 v139, v26, v27
	v_cvt_pk_bf16_f32 v140, v20, v21
	v_cvt_pk_bf16_f32 v141, v22, v23
	v_cvt_pk_bf16_f32 v142, v16, v17
	v_cvt_pk_bf16_f32 v143, v18, v19
	s_nop 1
	v_permlane16_swap_b32_e32 v136, v138
	v_permlane16_swap_b32_e32 v137, v139
	v_permlane16_swap_b32_e32 v140, v142
	v_permlane16_swap_b32_e32 v141, v143
	global_store_dwordx4 v154, v[136:139], s[100:101]
	global_store_dwordx4 v154, v[140:143], s[100:101] offset:64
	v_cvt_pk_bf16_f32 v144, v12, v13
	v_cvt_pk_bf16_f32 v145, v14, v15
	v_cvt_pk_bf16_f32 v146, v8, v9
	v_cvt_pk_bf16_f32 v147, v10, v11
	v_cvt_pk_bf16_f32 v148, v4, v5
	v_cvt_pk_bf16_f32 v149, v6, v7
	v_cvt_pk_bf16_f32 v150, v0, v1
	v_cvt_pk_bf16_f32 v151, v2, v3
	s_nop 1
	v_permlane16_swap_b32_e32 v144, v146
	v_permlane16_swap_b32_e32 v145, v147
	v_permlane16_swap_b32_e32 v148, v150
	v_permlane16_swap_b32_e32 v149, v151
	global_store_dwordx4 v155, v[144:147], s[100:101]
	global_store_dwordx4 v155, v[148:151], s[100:101] offset:64
	s_branch .Lfe_join_B

; template <class ARow, class Epi>
; DI void gemm_tile(const ARow& arow, long a_kstride, const u16* __restrict__ Bt, long ldb, int K, int m0, int n0,
;                   const Epi& epi, char* smem) {
;     ...
;   const int KT = K >> 6;
;   GEMM_STAGE(0, 0);
;   asm volatile("s_waitcnt vmcnt(0)" ::: "memory");
;   __syncthreads();
;   for (int kt = 0; kt < KT; ++kt) {
;     const int cur = kt & 1;
;     if (kt + 1 < KT) GEMM_STAGE(cur ^ 1, kt + 1);
;     const char* sa = smem + cur * 32768 + wm * 64 * 128;
;     const char* sb = smem + cur * 32768 + 16384 + wn * 64 * 128;
; #pragma unroll
;     for (int ks = 0; ks < 2; ++ks) {
;       bf16x8 wf[4], af[4];
; #pragma unroll
;       for (int j = 0; j < 4; ++j) {
;         wf[j] = *(const bf16x8*)(sb + j * 2048 + foff[ks]);
;         af[j] = *(const bf16x8*)(sa + j * 2048 + foff[ks]);
;       }
; #pragma unroll
;       for (int ni = 0; ni < 4; ++ni)
; #pragma unroll
;         for (int mi = 0; mi < 4; ++mi) acc[ni][mi] = __builtin_amdgcn_mfma_f32_16x16x32_bf16(wf[ni], af[mi], acc[ni][mi], 0, 0, 0);
;     }
;     asm volatile("s_waitcnt vmcnt(0)" ::: "memory");
;     __syncthreads();
;   }
.LBB0_1702:
	s_and_b32 s6, s1, 0x8000
	s_xor_b32 s7, s6, 0x8000
	v_add_u32_e32 v108, s7, v90
	v_add_u32_e32 v91, s6, v88
	v_or_b32_e32 v116, s6, v89
	v_readfirstlane_b32 s6, v108
	v_add_u32_e32 v109, 0x4000, v108
	v_lshl_add_u64 v[92:93], v[66:67], 0, s[4:5]
	v_add_u32_e32 v110, 0x400, v108
	v_readfirstlane_b32 s7, v109
	s_mov_b32 m0, s6
	v_lshl_add_u64 v[94:95], v[68:69], 0, s[4:5]
	v_add_u32_e32 v111, 0x4400, v108
	v_readfirstlane_b32 s8, v110
	global_load_lds_dwordx4 v[92:93], off
	s_mov_b32 m0, s7
	v_lshl_add_u64 v[96:97], v[70:71], 0, s[4:5]
	v_add_u32_e32 v113, 0x800, v108
	v_readfirstlane_b32 s9, v111
	global_load_lds_dwordx4 v[94:95], off
	s_mov_b32 m0, s8
	v_lshl_add_u64 v[98:99], v[72:73], 0, s[4:5]
	v_add_u32_e32 v114, 0x4800, v108
	v_readfirstlane_b32 s10, v113
	global_load_lds_dwordx4 v[96:97], off
	s_mov_b32 m0, s9
	v_lshl_add_u64 v[100:101], v[74:75], 0, s[4:5]
	v_add_u32_e32 v115, 0xc00, v108
	v_readfirstlane_b32 s11, v114
	global_load_lds_dwordx4 v[98:99], off
	s_mov_b32 m0, s10
	v_lshl_add_u64 v[102:103], v[76:77], 0, s[4:5]
	v_add_u32_e32 v108, 0x4c00, v108
	v_readfirstlane_b32 s26, v115
	global_load_lds_dwordx4 v[100:101], off
	s_mov_b32 m0, s11
	v_lshl_add_u64 v[104:105], v[78:79], 0, s[4:5]
	v_readfirstlane_b32 s27, v108
	global_load_lds_dwordx4 v[102:103], off
	s_mov_b32 m0, s26
	v_lshl_add_u64 v[106:107], v[80:81], 0, s[4:5]
	global_load_lds_dwordx4 v[104:105], off
	s_mov_b32 m0, s27
	v_add_u32_e32 v117, v116, v87
	global_load_lds_dwordx4 v[106:107], off
	v_add_u32_e32 v112, v91, v87
	ds_read_b128 v[92:95], v117 offset:16384
	ds_read_b128 v[96:99], v112
	ds_read_b128 v[100:103], v117 offset:18432
	ds_read_b128 v[104:107], v112 offset:2048
	ds_read_b128 v[108:111], v112 offset:4096
	ds_read_b128 v[112:115], v112 offset:6144
	s_waitcnt lgkmcnt(0)
	v_mfma_f32_16x16x32_bf16 v[60:63], v[92:95], v[96:99], v[60:63]
	v_add_u32_e32 v116, v116, v86
	v_add_u32_e32 v91, v91, v86
	s_add_i32 s1, s1, 0x8000
	v_mfma_f32_16x16x32_bf16 v[56:59], v[92:95], v[104:107], v[56:59]
	s_add_u32 s4, s4, 0x80
	s_addc_u32 s5, s5, 0
	s_cmpk_eq_i32 s4, 0x780
	v_mfma_f32_16x16x32_bf16 v[48:51], v[92:95], v[108:111], v[48:51]
	v_mfma_f32_16x16x32_bf16 v[40:43], v[92:95], v[112:115], v[40:43]
	v_mfma_f32_16x16x32_bf16 v[36:39], v[100:103], v[96:99], v[36:39]
	v_mfma_f32_16x16x32_bf16 v[32:35], v[100:103], v[104:107], v[32:35]
	v_mfma_f32_16x16x32_bf16 v[28:31], v[100:103], v[108:111], v[28:31]
	v_mfma_f32_16x16x32_bf16 v[24:27], v[100:103], v[112:115], v[24:27]
	ds_read_b128 v[92:95], v117 offset:20480
	ds_read_b128 v[100:103], v117 offset:22528
	s_waitcnt lgkmcnt(1)
	v_mfma_f32_16x16x32_bf16 v[20:23], v[92:95], v[96:99], v[20:23]
	v_mfma_f32_16x16x32_bf16 v[16:19], v[92:95], v[104:107], v[16:19]
	v_mfma_f32_16x16x32_bf16 v[12:15], v[92:95], v[108:111], v[12:15]
	v_mfma_f32_16x16x32_bf16 v[8:11], v[92:95], v[112:115], v[8:11]
	ds_read_b128 v[92:95], v116 offset:16384
	s_waitcnt lgkmcnt(1)
	v_mfma_f32_16x16x32_bf16 v[4:7], v[100:103], v[96:99], v[4:7]
	v_mfma_f32_16x16x32_bf16 v[0:3], v[100:103], v[104:107], v[0:3]
	v_mfma_f32_16x16x32_bf16 v[52:55], v[100:103], v[108:111], v[52:55]
	v_mfma_f32_16x16x32_bf16 v[44:47], v[100:103], v[112:115], v[44:47]
	ds_read_b128 v[96:99], v91
	ds_read_b128 v[100:103], v116 offset:18432
	ds_read_b128 v[104:107], v91 offset:2048
	ds_read_b128 v[108:111], v91 offset:4096
	ds_read_b128 v[112:115], v91 offset:6144
	s_waitcnt lgkmcnt(4)
	v_mfma_f32_16x16x32_bf16 v[60:63], v[92:95], v[96:99], v[60:63]
	s_waitcnt lgkmcnt(2)
	v_mfma_f32_16x16x32_bf16 v[56:59], v[92:95], v[104:107], v[56:59]
	s_waitcnt lgkmcnt(1)
	v_mfma_f32_16x16x32_bf16 v[48:51], v[92:95], v[108:111], v[48:51]
	s_waitcnt lgkmcnt(0)
	v_mfma_f32_16x16x32_bf16 v[40:43], v[92:95], v[112:115], v[40:43]
	v_mfma_f32_16x16x32_bf16 v[36:39], v[100:103], v[96:99], v[36:39]
	v_mfma_f32_16x16x32_bf16 v[32:35], v[100:103], v[104:107], v[32:35]
	v_mfma_f32_16x16x32_bf16 v[28:31], v[100:103], v[108:111], v[28:31]
	v_mfma_f32_16x16x32_bf16 v[24:27], v[100:103], v[112:115], v[24:27]
	ds_read_b128 v[92:95], v116 offset:20480
	ds_read_b128 v[100:103], v116 offset:22528
	s_waitcnt lgkmcnt(0)
	s_waitcnt vmcnt(0)
	s_waitcnt vmcnt(0) lgkmcnt(0)
	v_mfma_f32_16x16x32_bf16 v[20:23], v[92:95], v[96:99], v[20:23]
	s_barrier
	v_mfma_f32_16x16x32_bf16 v[16:19], v[92:95], v[104:107], v[16:19]
	v_mfma_f32_16x16x32_bf16 v[12:15], v[92:95], v[108:111], v[12:15]
	v_mfma_f32_16x16x32_bf16 v[8:11], v[92:95], v[112:115], v[8:11]
	v_mfma_f32_16x16x32_bf16 v[4:7], v[100:103], v[96:99], v[4:7]
	v_mfma_f32_16x16x32_bf16 v[0:3], v[100:103], v[104:107], v[0:3]
	v_mfma_f32_16x16x32_bf16 v[52:55], v[100:103], v[108:111], v[52:55]
	v_mfma_f32_16x16x32_bf16 v[44:47], v[100:103], v[112:115], v[44:47]
	s_cbranch_scc0 .LBB0_1702
; DI unsigned pack2(float a, float b) { v2f f = {a, b}; return __builtin_bit_cast(unsigned, __builtin_convertvector(f, v2bf)); }
; DI float silu_f(float v) { return v / (1.f + fexp(-v)); }
;   DI u32x2 pack(int, int, float a, float b, float c, float d, float&) const { u32x2 v; v.x = pack2(a, b); v.y = pack2(c, d); return v; }
; template <class ARow, class Epi>
; DI void gemm_tile(const ARow& arow, long a_kstride, const u16* __restrict__ Bt, long ldb, int K, int m0, int n0,
;                   const Epi& epi, char* smem) {
;     ...
;         for (int mi = 0; mi < 4; ++mi) acc[ni][mi] = __builtin_amdgcn_mfma_f32_16x16x32_bf16(wf[ni], af[mi], acc[ni][mi], 0, 0, 0);
;     }
;     asm volatile("s_waitcnt vmcnt(0)" ::: "memory");
;     __syncthreads();
;   }
;     ...
;   const int nh = n0 + wn * 64;
;   if (epi.packed(nh)) {
; #pragma unroll
;     for (int mi = 0; mi < 4; ++mi) {
;       const int m = m0 + wm * 64 + mi * 16 + fr;
;       float ss = 0.f;
;       u32x2 pk[4];
; #pragma unroll
;       for (int ni = 0; ni < 4; ++ni) pk[ni] = epi.pack(m, nh + ni * 16 + fq * 4, acc[ni][mi][0], acc[ni][mi][1], acc[ni][mi][2], acc[ni][mi][3], ss);
;       epi.finish16(m, nh, ss);
;       u16* rp = epi.rowp(m) + nh;
; #pragma unroll
;       for (int pp = 0; pp < 2; ++pp) {
;         u32x2 a = pk[2 * pp], b = pk[2 * pp + 1];
;         const u32x2 rx = __builtin_amdgcn_permlane16_swap(a.x, b.x, false, false);
;         const u32x2 ry = __builtin_amdgcn_permlane16_swap(a.y, b.y, false, false);
;         const int nst = (fq & 1) ? ((2 * pp + 1) * 16 + (fq - 1) * 4) : ((2 * pp) * 16 + fq * 4);
;         *(u32x4*)(rp + nst) = (u32x4){rx[0], ry[0], rx[1], ry[1]};
;       }
;   DI u32x2 pack(int m, int n, float a, float b, float c, float d, float& ss) const {
;     if (n < q_end) { a *= qscale; b *= qscale; c *= qscale; d *= qscale; }
;     else if (n >= z_start) { a = silu_f(a); b = silu_f(b); c = silu_f(c); d = silu_f(d); }
;     ss += a * a + b * b + c * c + d * d;
;     u32x2 v; v.x = pack2(a, b); v.y = pack2(c, d);
;     return v;
;   }
	v_add_u32_e32 v106, v89, v87
	ds_read_b128 v[66:69], v106 offset:49152
	v_add_u32_e32 v87, v88, v87
	ds_read_b128 v[70:73], v87 offset:32768
	ds_read_b128 v[74:77], v87 offset:34816
	ds_read_b128 v[78:81], v87 offset:36864
	ds_read_b128 v[90:93], v87 offset:38912
	v_add_u32_e32 v114, v89, v86
	s_waitcnt lgkmcnt(3)
	v_mfma_f32_16x16x32_bf16 v[60:63], v[66:69], v[70:73], v[60:63]
	s_waitcnt lgkmcnt(2)
	v_mfma_f32_16x16x32_bf16 v[56:59], v[66:69], v[74:77], v[56:59]
	s_waitcnt lgkmcnt(1)
	v_mfma_f32_16x16x32_bf16 v[48:51], v[66:69], v[78:81], v[48:51]
	s_waitcnt lgkmcnt(0)
	v_mfma_f32_16x16x32_bf16 v[40:43], v[66:69], v[90:93], v[40:43]
	ds_read_b128 v[66:69], v106 offset:51200
	s_waitcnt lgkmcnt(0)
	v_mfma_f32_16x16x32_bf16 v[36:39], v[66:69], v[70:73], v[36:39]
	v_mfma_f32_16x16x32_bf16 v[32:35], v[66:69], v[74:77], v[32:35]
	v_mfma_f32_16x16x32_bf16 v[94:97], v[66:69], v[78:81], v[28:31]
	v_mfma_f32_16x16x32_bf16 v[66:69], v[66:69], v[90:93], v[24:27]
	s_nop 2
	ds_read_b128 v[24:27], v106 offset:53248
	s_waitcnt lgkmcnt(0)
	v_mfma_f32_16x16x32_bf16 v[102:105], v[24:27], v[90:93], v[8:11]
	s_nop 2
	ds_read_b128 v[8:11], v106 offset:55296
	v_mfma_f32_16x16x32_bf16 v[20:23], v[24:27], v[70:73], v[20:23]
	s_waitcnt lgkmcnt(0)
	v_mfma_f32_16x16x32_bf16 v[70:73], v[8:11], v[70:73], v[4:7]
	s_nop 2
	ds_read_b128 v[4:7], v114 offset:49152
	v_mfma_f32_16x16x32_bf16 v[98:101], v[24:27], v[78:81], v[12:15]
	s_nop 2
	v_add_u32_e32 v12, v88, v86
	v_mfma_f32_16x16x32_bf16 v[16:19], v[24:27], v[74:77], v[16:19]
	ds_read_b128 v[86:89], v12 offset:32768
	ds_read_b128 v[106:109], v12 offset:36864
	ds_read_b128 v[110:113], v12 offset:38912
	v_mfma_f32_16x16x32_bf16 v[0:3], v[8:11], v[74:77], v[0:3]
	v_mfma_f32_16x16x32_bf16 v[74:77], v[8:11], v[78:81], v[52:55]
	v_mfma_f32_16x16x32_bf16 v[78:81], v[8:11], v[90:93], v[44:47]
	ds_read_b128 v[90:93], v12 offset:34816
	s_waitcnt lgkmcnt(3)
	v_mfma_f32_16x16x32_bf16 v[60:63], v[4:7], v[86:89], v[60:63]
	s_waitcnt lgkmcnt(0)
	v_mfma_f32_16x16x32_bf16 v[44:47], v[4:7], v[90:93], v[56:59]
	v_mfma_f32_16x16x32_bf16 v[28:31], v[4:7], v[106:109], v[48:51]
	v_mfma_f32_16x16x32_bf16 v[12:15], v[4:7], v[110:113], v[40:43]
	ds_read_b128 v[4:7], v114 offset:51200
	s_waitcnt lgkmcnt(0)
	v_mfma_f32_16x16x32_bf16 v[56:59], v[4:7], v[86:89], v[36:39]
	v_mfma_f32_16x16x32_bf16 v[40:43], v[4:7], v[90:93], v[32:35]
	v_mfma_f32_16x16x32_bf16 v[24:27], v[4:7], v[106:109], v[94:97]
	v_mfma_f32_16x16x32_bf16 v[8:11], v[4:7], v[110:113], v[66:69]
	ds_read_b128 v[4:7], v114 offset:53248
	s_nop 0
	ds_read_b128 v[94:97], v114 offset:55296
	s_waitcnt lgkmcnt(0)
	s_waitcnt vmcnt(0)
	s_waitcnt lgkmcnt(0)
	v_mfma_f32_16x16x32_bf16 v[32:35], v[94:97], v[90:93], v[0:3]
	s_nop 2
	v_or_b32_e32 v0, s0, v64
	v_lshl_or_b32 v66, v84, 6, s35
	v_lshlrev_b32_e32 v68, 2, v83
	v_mfma_f32_16x16x32_bf16 v[52:55], v[4:7], v[86:89], v[20:23]
	v_cmp_lt_i32_e32 vcc, s30, v66
	v_or_b32_e32 v64, v66, v68
	v_mfma_f32_16x16x32_bf16 v[36:39], v[4:7], v[90:93], v[16:19]
	s_barrier
	v_mfma_f32_16x16x32_bf16 v[20:23], v[4:7], v[106:109], v[98:101]
	v_mfma_f32_16x16x32_bf16 v[4:7], v[4:7], v[110:113], v[102:105]
	v_mfma_f32_16x16x32_bf16 v[48:51], v[94:97], v[86:89], v[70:73]
	v_mfma_f32_16x16x32_bf16 v[16:19], v[94:97], v[106:109], v[74:77]
	s_nop 2
	v_lshl_add_u32 v74, v85, 6, v0
	v_mfma_f32_16x16x32_bf16 v[0:3], v[94:97], v[110:113], v[78:81]
	s_nop 7
	v_readfirstlane_b32 s99, v66
	s_cmpk_ge_u32 s99, 0x300
	s_cbranch_scc0 .Lfe_C_not_plain
	s_cmpk_lt_u32 s99, 0xa00
	s_cbranch_scc0 .Lfe_C_not_plain
	s_load_dwordx2 s[100:101], s[56:57], 0x130
	v_and_b32_e32 v152, 1, v83
	v_mul_u32_u24_e32 v152, 12, v152
	v_lshl_add_u32 v152, v83, 2, v152
	v_add_u32_e32 v152, v152, v66
	v_mul_u32_u24_e32 v153, 0xe00, v74
	v_add_u32_e32 v152, v152, v153
	v_lshlrev_b32_e32 v152, 1, v152
	v_add_u32_e32 v153, 0x1c000, v152
	v_add_u32_e32 v154, 0x38000, v152
	v_add_u32_e32 v155, 0x54000, v152
	s_nop 3
	v_cvt_pk_bf16_f32 v120, v60, v61
	v_cvt_pk_bf16_f32 v121, v62, v63
	v_cvt_pk_bf16_f32 v122, v56, v57
	v_cvt_pk_bf16_f32 v123, v58, v59
	v_cvt_pk_bf16_f32 v124, v52, v53
	v_cvt_pk_bf16_f32 v125, v54, v55
	v_cvt_pk_bf16_f32 v126, v48, v49
	v_cvt_pk_bf16_f32 v127, v50, v51
	s_nop 1
	v_permlane16_swap_b32_e32 v120, v122
	v_permlane16_swap_b32_e32 v121, v123
	v_permlane16_swap_b32_e32 v124, v126
	v_permlane16_swap_b32_e32 v125, v127
	s_waitcnt lgkmcnt(0)
	global_store_dwordx4 v152, v[120:123], s[100:101]
	global_store_dwordx4 v152, v[124:127], s[100:101] offset:64
	v_cvt_pk_bf16_f32 v128, v44, v45
	v_cvt_pk_bf16_f32 v129, v46, v47
	v_cvt_pk_bf16_f32 v130, v40, v41
	v_cvt_pk_bf16_f32 v131, v42, v43
	v_cvt_pk_bf16_f32 v132, v36, v37
	v_cvt_pk_bf16_f32 v133, v38, v39
	v_cvt_pk_bf16_f32 v134, v32, v33
	v_cvt_pk_bf16_f32 v135, v34, v35
	s_nop 1
	v_permlane16_swap_b32_e32 v128, v130
	v_permlane16_swap_b32_e32 v129, v131
	v_permlane16_swap_b32_e32 v132, v134
	v_permlane16_swap_b32_e32 v133, v135
	global_store_dwordx4 v153, v[128:131], s[100:101]
	global_store_dwordx4 v153, v[132:135], s[100:101] offset:64
	v_cvt_pk_bf16_f32 v136, v28, v29
	v_cvt_pk_bf16_f32 v137, v30, v31
	v_cvt_pk_bf16_f32 v138, v24, v25
	v_cvt_pk_bf16_f32 v139, v26, v27
	v_cvt_pk_bf16_f32 v140, v20, v21
	v_cvt_pk_bf16_f32 v141, v22, v23
	v_cvt_pk_bf16_f32 v142, v16, v17
	v_cvt_pk_bf16_f32 v143, v18, v19
	s_nop 1
	v_permlane16_swap_b32_e32 v136, v138
	v_permlane16_swap_b32_e32 v137, v139
	v_permlane16_swap_b32_e32 v140, v142
	v_permlane16_swap_b32_e32 v141, v143
	global_store_dwordx4 v154, v[136:139], s[100:101]
	global_store_dwordx4 v154, v[140:143], s[100:101] offset:64
	v_cvt_pk_bf16_f32 v144, v12, v13
	v_cvt_pk_bf16_f32 v145, v14, v15
	v_cvt_pk_bf16_f32 v146, v8, v9
	v_cvt_pk_bf16_f32 v147, v10, v11
	v_cvt_pk_bf16_f32 v148, v4, v5
	v_cvt_pk_bf16_f32 v149, v6, v7
	v_cvt_pk_bf16_f32 v150, v0, v1
	v_cvt_pk_bf16_f32 v151, v2, v3
	s_nop 1
	v_permlane16_swap_b32_e32 v144, v146
	v_permlane16_swap_b32_e32 v145, v147
	v_permlane16_swap_b32_e32 v148, v150
	v_permlane16_swap_b32_e32 v149, v151
	global_store_dwordx4 v155, v[144:147], s[100:101]
	global_store_dwordx4 v155, v[148:151], s[100:101] offset:64
	s_branch .Lfe_join_C

; template <class ARow, class Epi>
; DI void gemm_tile(const ARow& arow, long a_kstride, const u16* __restrict__ Bt, long ldb, int K, int m0, int n0,
;                   const Epi& epi, char* smem) {
;     ...
;   const int KT = K >> 6;
;   GEMM_STAGE(0, 0);
;   asm volatile("s_waitcnt vmcnt(0)" ::: "memory");
;   __syncthreads();
;   for (int kt = 0; kt < KT; ++kt) {
;     const int cur = kt & 1;
;     if (kt + 1 < KT) GEMM_STAGE(cur ^ 1, kt + 1);
;     const char* sa = smem + cur * 32768 + wm * 64 * 128;
;     const char* sb = smem + cur * 32768 + 16384 + wn * 64 * 128;
; #pragma unroll
;     for (int ks = 0; ks < 2; ++ks) {
;       bf16x8 wf[4], af[4];
; #pragma unroll
;       for (int j = 0; j < 4; ++j) {
;         wf[j] = *(const bf16x8*)(sb + j * 2048 + foff[ks]);
;         af[j] = *(const bf16x8*)(sa + j * 2048 + foff[ks]);
;       }
; #pragma unroll
;       for (int ni = 0; ni < 4; ++ni)
; #pragma unroll
;         for (int mi = 0; mi < 4; ++mi) acc[ni][mi] = __builtin_amdgcn_mfma_f32_16x16x32_bf16(wf[ni], af[mi], acc[ni][mi], 0, 0, 0);
;     }
;     asm volatile("s_waitcnt vmcnt(0)" ::: "memory");
;     __syncthreads();
;   }
.LBB0_2314:
	s_and_b32 s6, s1, 0x8000
	s_xor_b32 s7, s6, 0x8000
	v_add_u32_e32 v108, s7, v90
	v_add_u32_e32 v91, s6, v88
	v_or_b32_e32 v116, s6, v89
	v_readfirstlane_b32 s6, v108
	v_add_u32_e32 v109, 0x4000, v108
	v_lshl_add_u64 v[92:93], v[66:67], 0, s[4:5]
	v_add_u32_e32 v110, 0x400, v108
	v_readfirstlane_b32 s7, v109
	s_mov_b32 m0, s6
	v_lshl_add_u64 v[94:95], v[68:69], 0, s[4:5]
	v_add_u32_e32 v111, 0x4400, v108
	v_readfirstlane_b32 s8, v110
	global_load_lds_dwordx4 v[92:93], off
	s_mov_b32 m0, s7
	v_lshl_add_u64 v[96:97], v[70:71], 0, s[4:5]
	v_add_u32_e32 v113, 0x800, v108
	v_readfirstlane_b32 s9, v111
	global_load_lds_dwordx4 v[94:95], off
	s_mov_b32 m0, s8
	v_lshl_add_u64 v[98:99], v[72:73], 0, s[4:5]
	v_add_u32_e32 v114, 0x4800, v108
	v_readfirstlane_b32 s10, v113
	global_load_lds_dwordx4 v[96:97], off
	s_mov_b32 m0, s9
	v_lshl_add_u64 v[100:101], v[74:75], 0, s[4:5]
	v_add_u32_e32 v115, 0xc00, v108
	v_readfirstlane_b32 s11, v114
	global_load_lds_dwordx4 v[98:99], off
	s_mov_b32 m0, s10
	v_lshl_add_u64 v[102:103], v[76:77], 0, s[4:5]
	v_add_u32_e32 v108, 0x4c00, v108
	v_readfirstlane_b32 s26, v115
	global_load_lds_dwordx4 v[100:101], off
	s_mov_b32 m0, s11
	v_lshl_add_u64 v[104:105], v[78:79], 0, s[4:5]
	v_readfirstlane_b32 s27, v108
	global_load_lds_dwordx4 v[102:103], off
	s_mov_b32 m0, s26
	v_lshl_add_u64 v[106:107], v[80:81], 0, s[4:5]
	global_load_lds_dwordx4 v[104:105], off
	s_mov_b32 m0, s27
	v_add_u32_e32 v117, v116, v87
	global_load_lds_dwordx4 v[106:107], off
	v_add_u32_e32 v112, v91, v87
	ds_read_b128 v[92:95], v117 offset:16384
	ds_read_b128 v[96:99], v112
	ds_read_b128 v[100:103], v117 offset:18432
	ds_read_b128 v[104:107], v112 offset:2048
	ds_read_b128 v[108:111], v112 offset:4096
	ds_read_b128 v[112:115], v112 offset:6144
	s_waitcnt lgkmcnt(0)
	v_mfma_f32_16x16x32_bf16 v[60:63], v[92:95], v[96:99], v[60:63]
	v_add_u32_e32 v116, v116, v86
	v_add_u32_e32 v91, v91, v86
	s_add_i32 s1, s1, 0x8000
	v_mfma_f32_16x16x32_bf16 v[56:59], v[92:95], v[104:107], v[56:59]
	s_add_u32 s4, s4, 0x80
	s_addc_u32 s5, s5, 0
	s_cmpk_eq_i32 s4, 0x780
	v_mfma_f32_16x16x32_bf16 v[48:51], v[92:95], v[108:111], v[48:51]
	v_mfma_f32_16x16x32_bf16 v[40:43], v[92:95], v[112:115], v[40:43]
	v_mfma_f32_16x16x32_bf16 v[36:39], v[100:103], v[96:99], v[36:39]
	v_mfma_f32_16x16x32_bf16 v[32:35], v[100:103], v[104:107], v[32:35]
	v_mfma_f32_16x16x32_bf16 v[28:31], v[100:103], v[108:111], v[28:31]
	v_mfma_f32_16x16x32_bf16 v[24:27], v[100:103], v[112:115], v[24:27]
	ds_read_b128 v[92:95], v117 offset:20480
	ds_read_b128 v[100:103], v117 offset:22528
	s_waitcnt lgkmcnt(1)
	v_mfma_f32_16x16x32_bf16 v[20:23], v[92:95], v[96:99], v[20:23]
	v_mfma_f32_16x16x32_bf16 v[16:19], v[92:95], v[104:107], v[16:19]
	v_mfma_f32_16x16x32_bf16 v[12:15], v[92:95], v[108:111], v[12:15]
	v_mfma_f32_16x16x32_bf16 v[8:11], v[92:95], v[112:115], v[8:11]
	ds_read_b128 v[92:95], v116 offset:16384
	s_waitcnt lgkmcnt(1)
	v_mfma_f32_16x16x32_bf16 v[4:7], v[100:103], v[96:99], v[4:7]
	v_mfma_f32_16x16x32_bf16 v[0:3], v[100:103], v[104:107], v[0:3]
	v_mfma_f32_16x16x32_bf16 v[52:55], v[100:103], v[108:111], v[52:55]
	v_mfma_f32_16x16x32_bf16 v[44:47], v[100:103], v[112:115], v[44:47]
	ds_read_b128 v[96:99], v91
	ds_read_b128 v[100:103], v116 offset:18432
	ds_read_b128 v[104:107], v91 offset:2048
	ds_read_b128 v[108:111], v91 offset:4096
	ds_read_b128 v[112:115], v91 offset:6144
	s_waitcnt lgkmcnt(4)
	v_mfma_f32_16x16x32_bf16 v[60:63], v[92:95], v[96:99], v[60:63]
	s_waitcnt lgkmcnt(2)
	v_mfma_f32_16x16x32_bf16 v[56:59], v[92:95], v[104:107], v[56:59]
	s_waitcnt lgkmcnt(1)
	v_mfma_f32_16x16x32_bf16 v[48:51], v[92:95], v[108:111], v[48:51]
	s_waitcnt lgkmcnt(0)
	v_mfma_f32_16x16x32_bf16 v[40:43], v[92:95], v[112:115], v[40:43]
	v_mfma_f32_16x16x32_bf16 v[36:39], v[100:103], v[96:99], v[36:39]
	v_mfma_f32_16x16x32_bf16 v[32:35], v[100:103], v[104:107], v[32:35]
	v_mfma_f32_16x16x32_bf16 v[28:31], v[100:103], v[108:111], v[28:31]
	v_mfma_f32_16x16x32_bf16 v[24:27], v[100:103], v[112:115], v[24:27]
	ds_read_b128 v[92:95], v116 offset:20480
	ds_read_b128 v[100:103], v116 offset:22528
	s_waitcnt lgkmcnt(0)
	s_waitcnt vmcnt(0)
	s_waitcnt vmcnt(0) lgkmcnt(0)
	v_mfma_f32_16x16x32_bf16 v[20:23], v[92:95], v[96:99], v[20:23]
	s_barrier
	v_mfma_f32_16x16x32_bf16 v[16:19], v[92:95], v[104:107], v[16:19]
	v_mfma_f32_16x16x32_bf16 v[12:15], v[92:95], v[108:111], v[12:15]
	v_mfma_f32_16x16x32_bf16 v[8:11], v[92:95], v[112:115], v[8:11]
	v_mfma_f32_16x16x32_bf16 v[4:7], v[100:103], v[96:99], v[4:7]
	v_mfma_f32_16x16x32_bf16 v[0:3], v[100:103], v[104:107], v[0:3]
	v_mfma_f32_16x16x32_bf16 v[52:55], v[100:103], v[108:111], v[52:55]
	v_mfma_f32_16x16x32_bf16 v[44:47], v[100:103], v[112:115], v[44:47]
	s_cbranch_scc0 .LBB0_2314
; DI unsigned pack2(float a, float b) { v2f f = {a, b}; return __builtin_bit_cast(unsigned, __builtin_convertvector(f, v2bf)); }
; DI float silu_f(float v) { return v / (1.f + fexp(-v)); }
;   DI u32x2 pack(int, int, float a, float b, float c, float d, float&) const { u32x2 v; v.x = pack2(a, b); v.y = pack2(c, d); return v; }
; template <class ARow, class Epi>
; DI void gemm_tile(const ARow& arow, long a_kstride, const u16* __restrict__ Bt, long ldb, int K, int m0, int n0,
;                   const Epi& epi, char* smem) {
;     ...
;         for (int mi = 0; mi < 4; ++mi) acc[ni][mi] = __builtin_amdgcn_mfma_f32_16x16x32_bf16(wf[ni], af[mi], acc[ni][mi], 0, 0, 0);
;     }
;     asm volatile("s_waitcnt vmcnt(0)" ::: "memory");
;     __syncthreads();
;   }
;     ...
;   const int nh = n0 + wn * 64;
;   if (epi.packed(nh)) {
; #pragma unroll
;     for (int mi = 0; mi < 4; ++mi) {
;       const int m = m0 + wm * 64 + mi * 16 + fr;
;       float ss = 0.f;
;       u32x2 pk[4];
; #pragma unroll
;       for (int ni = 0; ni < 4; ++ni) pk[ni] = epi.pack(m, nh + ni * 16 + fq * 4, acc[ni][mi][0], acc[ni][mi][1], acc[ni][mi][2], acc[ni][mi][3], ss);
;       epi.finish16(m, nh, ss);
;       u16* rp = epi.rowp(m) + nh;
; #pragma unroll
;       for (int pp = 0; pp < 2; ++pp) {
;         u32x2 a = pk[2 * pp], b = pk[2 * pp + 1];
;         const u32x2 rx = __builtin_amdgcn_permlane16_swap(a.x, b.x, false, false);
;         const u32x2 ry = __builtin_amdgcn_permlane16_swap(a.y, b.y, false, false);
;         const int nst = (fq & 1) ? ((2 * pp + 1) * 16 + (fq - 1) * 4) : ((2 * pp) * 16 + fq * 4);
;         *(u32x4*)(rp + nst) = (u32x4){rx[0], ry[0], rx[1], ry[1]};
;       }
;   DI u32x2 pack(int m, int n, float a, float b, float c, float d, float& ss) const {
;     if (n < q_end) { a *= qscale; b *= qscale; c *= qscale; d *= qscale; }
;     else if (n >= z_start) { a = silu_f(a); b = silu_f(b); c = silu_f(c); d = silu_f(d); }
;     ss += a * a + b * b + c * c + d * d;
;     u32x2 v; v.x = pack2(a, b); v.y = pack2(c, d);
;     return v;
;   }
	v_add_u32_e32 v106, v89, v87
	ds_read_b128 v[66:69], v106 offset:49152
	v_add_u32_e32 v87, v88, v87
	ds_read_b128 v[70:73], v87 offset:32768
	ds_read_b128 v[74:77], v87 offset:34816
	ds_read_b128 v[78:81], v87 offset:36864
	ds_read_b128 v[90:93], v87 offset:38912
	v_add_u32_e32 v114, v89, v86
	s_waitcnt lgkmcnt(3)
	v_mfma_f32_16x16x32_bf16 v[60:63], v[66:69], v[70:73], v[60:63]
	s_waitcnt lgkmcnt(2)
	v_mfma_f32_16x16x32_bf16 v[56:59], v[66:69], v[74:77], v[56:59]
	s_waitcnt lgkmcnt(1)
	v_mfma_f32_16x16x32_bf16 v[48:51], v[66:69], v[78:81], v[48:51]
	s_waitcnt lgkmcnt(0)
	v_mfma_f32_16x16x32_bf16 v[40:43], v[66:69], v[90:93], v[40:43]
	ds_read_b128 v[66:69], v106 offset:51200
	s_waitcnt lgkmcnt(0)
	v_mfma_f32_16x16x32_bf16 v[36:39], v[66:69], v[70:73], v[36:39]
	v_mfma_f32_16x16x32_bf16 v[32:35], v[66:69], v[74:77], v[32:35]
	v_mfma_f32_16x16x32_bf16 v[94:97], v[66:69], v[78:81], v[28:31]
	v_mfma_f32_16x16x32_bf16 v[66:69], v[66:69], v[90:93], v[24:27]
	s_nop 2
	ds_read_b128 v[24:27], v106 offset:53248
	s_waitcnt lgkmcnt(0)
	v_mfma_f32_16x16x32_bf16 v[102:105], v[24:27], v[90:93], v[8:11]
	s_nop 2
	ds_read_b128 v[8:11], v106 offset:55296
	v_mfma_f32_16x16x32_bf16 v[20:23], v[24:27], v[70:73], v[20:23]
	s_waitcnt lgkmcnt(0)
	v_mfma_f32_16x16x32_bf16 v[70:73], v[8:11], v[70:73], v[4:7]
	s_nop 2
	ds_read_b128 v[4:7], v114 offset:49152
	v_mfma_f32_16x16x32_bf16 v[98:101], v[24:27], v[78:81], v[12:15]
	s_nop 2
	v_add_u32_e32 v12, v88, v86
	v_mfma_f32_16x16x32_bf16 v[16:19], v[24:27], v[74:77], v[16:19]
	ds_read_b128 v[86:89], v12 offset:32768
	ds_read_b128 v[106:109], v12 offset:36864
	ds_read_b128 v[110:113], v12 offset:38912
	v_mfma_f32_16x16x32_bf16 v[0:3], v[8:11], v[74:77], v[0:3]
	v_mfma_f32_16x16x32_bf16 v[74:77], v[8:11], v[78:81], v[52:55]
	v_mfma_f32_16x16x32_bf16 v[78:81], v[8:11], v[90:93], v[44:47]
	ds_read_b128 v[90:93], v12 offset:34816
	s_waitcnt lgkmcnt(3)
	v_mfma_f32_16x16x32_bf16 v[60:63], v[4:7], v[86:89], v[60:63]
	s_waitcnt lgkmcnt(0)
	v_mfma_f32_16x16x32_bf16 v[44:47], v[4:7], v[90:93], v[56:59]
	v_mfma_f32_16x16x32_bf16 v[28:31], v[4:7], v[106:109], v[48:51]
	v_mfma_f32_16x16x32_bf16 v[12:15], v[4:7], v[110:113], v[40:43]
	ds_read_b128 v[4:7], v114 offset:51200
	s_waitcnt lgkmcnt(0)
	v_mfma_f32_16x16x32_bf16 v[56:59], v[4:7], v[86:89], v[36:39]
	v_mfma_f32_16x16x32_bf16 v[40:43], v[4:7], v[90:93], v[32:35]
	v_mfma_f32_16x16x32_bf16 v[24:27], v[4:7], v[106:109], v[94:97]
	v_mfma_f32_16x16x32_bf16 v[8:11], v[4:7], v[110:113], v[66:69]
	ds_read_b128 v[4:7], v114 offset:53248
	s_nop 0
	ds_read_b128 v[94:97], v114 offset:55296
	s_waitcnt lgkmcnt(0)
	s_waitcnt vmcnt(0)
	s_waitcnt lgkmcnt(0)
	v_mfma_f32_16x16x32_bf16 v[32:35], v[94:97], v[90:93], v[0:3]
	s_nop 2
	v_or_b32_e32 v0, s0, v64
	v_lshl_add_u32 v66, v85, 6, v0
	v_lshl_or_b32 v68, v84, 6, s34
	v_mfma_f32_16x16x32_bf16 v[52:55], v[4:7], v[86:89], v[20:23]
	v_cmp_lt_i32_e32 vcc, s30, v68
	s_barrier
	v_mfma_f32_16x16x32_bf16 v[36:39], v[4:7], v[90:93], v[16:19]
	v_mfma_f32_16x16x32_bf16 v[20:23], v[4:7], v[106:109], v[98:101]
	v_mfma_f32_16x16x32_bf16 v[4:7], v[4:7], v[110:113], v[102:105]
	v_mfma_f32_16x16x32_bf16 v[48:51], v[94:97], v[86:89], v[70:73]
	v_mfma_f32_16x16x32_bf16 v[16:19], v[94:97], v[106:109], v[74:77]
	s_nop 1
	v_lshlrev_b32_e32 v70, 2, v83
	v_or_b32_e32 v64, v68, v70
	v_mfma_f32_16x16x32_bf16 v[0:3], v[94:97], v[110:113], v[78:81]
	s_nop 7
	v_readfirstlane_b32 s99, v68
	s_cmpk_ge_u32 s99, 0x400
	s_cbranch_scc0 .Lfe_D_not_plain
	s_cmpk_lt_u32 s99, 0xc00
	s_cbranch_scc0 .Lfe_D_not_plain
	s_load_dwordx2 s[100:101], s[56:57], 0x130
	v_and_b32_e32 v152, 1, v83
	v_mul_u32_u24_e32 v152, 12, v152
	v_lshl_add_u32 v152, v83, 2, v152
	v_add_u32_e32 v152, v152, v68
	v_lshl_add_u32 v152, v66, 12, v152
	v_lshlrev_b32_e32 v152, 1, v152
	v_add_u32_e32 v153, 0x20000, v152
	v_add_u32_e32 v154, 0x40000, v152
	v_add_u32_e32 v155, 0x60000, v152
	s_nop 3
	v_cvt_pk_bf16_f32 v120, v60, v61
	v_cvt_pk_bf16_f32 v121, v62, v63
	v_cvt_pk_bf16_f32 v122, v56, v57
	v_cvt_pk_bf16_f32 v123, v58, v59
	v_cvt_pk_bf16_f32 v124, v52, v53
	v_cvt_pk_bf16_f32 v125, v54, v55
	v_cvt_pk_bf16_f32 v126, v48, v49
	v_cvt_pk_bf16_f32 v127, v50, v51
	s_nop 1
	v_permlane16_swap_b32_e32 v120, v122
	v_permlane16_swap_b32_e32 v121, v123
	v_permlane16_swap_b32_e32 v124, v126
	v_permlane16_swap_b32_e32 v125, v127
	s_waitcnt lgkmcnt(0)
	global_store_dwordx4 v152, v[120:123], s[100:101]
	global_store_dwordx4 v152, v[124:127], s[100:101] offset:64
	v_cvt_pk_bf16_f32 v128, v44, v45
	v_cvt_pk_bf16_f32 v129, v46, v47
	v_cvt_pk_bf16_f32 v130, v40, v41
	v_cvt_pk_bf16_f32 v131, v42, v43
	v_cvt_pk_bf16_f32 v132, v36, v37
	v_cvt_pk_bf16_f32 v133, v38, v39
	v_cvt_pk_bf16_f32 v134, v32, v33
	v_cvt_pk_bf16_f32 v135, v34, v35
	s_nop 1
	v_permlane16_swap_b32_e32 v128, v130
	v_permlane16_swap_b32_e32 v129, v131
	v_permlane16_swap_b32_e32 v132, v134
	v_permlane16_swap_b32_e32 v133, v135
	global_store_dwordx4 v153, v[128:131], s[100:101]
	global_store_dwordx4 v153, v[132:135], s[100:101] offset:64
	v_cvt_pk_bf16_f32 v136, v28, v29
	v_cvt_pk_bf16_f32 v137, v30, v31
	v_cvt_pk_bf16_f32 v138, v24, v25
	v_cvt_pk_bf16_f32 v139, v26, v27
	v_cvt_pk_bf16_f32 v140, v20, v21
	v_cvt_pk_bf16_f32 v141, v22, v23
	v_cvt_pk_bf16_f32 v142, v16, v17
	v_cvt_pk_bf16_f32 v143, v18, v19
	s_nop 1
	v_permlane16_swap_b32_e32 v136, v138
	v_permlane16_swap_b32_e32 v137, v139
	v_permlane16_swap_b32_e32 v140, v142
	v_permlane16_swap_b32_e32 v141, v143
	global_store_dwordx4 v154, v[136:139], s[100:101]
	global_store_dwordx4 v154, v[140:143], s[100:101] offset:64
	v_cvt_pk_bf16_f32 v144, v12, v13
	v_cvt_pk_bf16_f32 v145, v14, v15
	v_cvt_pk_bf16_f32 v146, v8, v9
	v_cvt_pk_bf16_f32 v147, v10, v11
	v_cvt_pk_bf16_f32 v148, v4, v5
	v_cvt_pk_bf16_f32 v149, v6, v7
	v_cvt_pk_bf16_f32 v150, v0, v1
	v_cvt_pk_bf16_f32 v151, v2, v3
	s_nop 1
	v_permlane16_swap_b32_e32 v144, v146
	v_permlane16_swap_b32_e32 v145, v147
	v_permlane16_swap_b32_e32 v148, v150
	v_permlane16_swap_b32_e32 v149, v151
	global_store_dwordx4 v155, v[144:147], s[100:101]
	global_store_dwordx4 v155, v[148:151], s[100:101] offset:64
	s_branch .Lfe_join_D
